# gate GEMM (K=256) straight-line K part: same MFMA-segment head/tail trims as the K-loops
# baseline (speedup 1.0000x reference)
; #define PG8_STAGE(bufoff, gbase, voff) do { _Pragma("unroll") for (int _i = 0; _i < 2; ++_i) \
;         __builtin_amdgcn_global_load_lds((const unsigned*)((const char*)(gbase) + (voff)[_i]), (LAS unsigned*)(lds + (bufoff) + ldsw + _i * 8192), 16, 0, 0); } while (0)
; #define PG8_LDA(dst, b, h) do { _Pragma("unroll") for (int m = 0; m < 4; ++m) _Pragma("unroll") for (int k = 0; k < 2; ++k) dst[m][k] = *(const LAS bf16x8*)(lds + PG8_SA(b, h) + aoff + m * 2048 + k * 1024); } while (0)
; #define PG8_LDB(dst, b, h) do { _Pragma("unroll") for (int n = 0; n < 2; ++n) _Pragma("unroll") for (int k = 0; k < 2; ++k) dst[n][k] = *(const LAS bf16x8*)(lds + PG8_SB(b, h) + boff + n * 2048 + k * 1024); } while (0)
; #define PG8_WAIT_V(n) asm volatile("s_waitcnt vmcnt(" #n ")" ::: "memory")
; #define PG8_WAIT_L(n) asm volatile("s_waitcnt lgkmcnt(" #n ")" ::: "memory")
; #define PG8_BAR __builtin_amdgcn_s_barrier()
; #define PG8_SCHED __builtin_amdgcn_sched_barrier(0)
; template <class Epi>
; __device__ __forceinline__ void gemm_phase(LAS unsigned char* lds, const bf16_t* A, int lda, const bf16_t* Bt, int ldb, int M, int N, int K, int asel, const Epi& E, const int fixed_round = -1) {
;     ...
;         const bool has_next = (fixed_round < 0) && S.next(ui + 1, nxt);
;         const char* nA = has_next ? PG8_ABASE(nxt) : cA; const char* nB = has_next ? (const char*)Bt + (size_t)nxt.pn * tstepB : cB;
;         for (int t = 0; t < nt; t += 2) {
;             const bool last = (t == nt - 2);
;             const char* a1 = cA + (size_t)(t + 1) * kstep;
;             const char* a2 = last ? nA : cA + (size_t)(t + 2) * kstep; const char* b2 = last ? nB : cB + (size_t)(t + 2) * kstep;
;             const char* a3 = a2 + kstep; const char* b3 = b2 + kstep;
;             PG8_LDB(B0, 0, 0); PG8_SCHED; PG8_LDA(At, 0, 0); PG8_STAGE(PG8_SA(1, 1), a1 + hstepA, voffA);
;             PG8_WAIT_L(8); PG8_BAR; PG8_WAIT_L(0); PG8_MMA(0, 0, At, B0); PG8_BAR; PG8_SCHED;
;             PG8_LDB(B1, 0, 1); PG8_STAGE(PG8_SB(0, 0), b2, voffB);
;             PG8_BAR; PG8_WAIT_L(0); PG8_MMA(0, 1, At, B1); PG8_BAR;
;             PG8_LDA(At, 0, 1); PG8_STAGE(PG8_SA(0, 0), a2, voffA);
;             PG8_BAR; PG8_WAIT_L(0); PG8_MMA(1, 0, At, B0); PG8_BAR; PG8_SCHED;
;             PG8_STAGE(PG8_SB(0, 1), b2 + hstepB, voffB);
;             PG8_WAIT_V(6); PG8_BAR; PG8_MMA(1, 1, At, B1); PG8_BAR;
.LBB0_938:
	s_ashr_i32 s57, s56, 31
	s_lshl_b64 s[2:3], s[56:57], 20
	s_add_u32 s28, s6, s2
	s_addc_u32 s29, s7, s3
	s_ashr_i32 s2, s54, 1
	s_ashr_i32 s3, s2, 31
	s_lshl_b64 s[2:3], s[2:3], 9
	s_add_u32 s58, s28, s2
	s_addc_u32 s59, s29, s3
	ds_read_b128 v[0:3], v215
	ds_read_b128 v[4:7], v215 offset:1024
	ds_read_b128 v[8:11], v215 offset:2048
	ds_read_b128 v[12:15], v215 offset:3072
	s_and_b64 s[2:3], exec, s[0:1]
	s_cselect_b32 s3, s59, s65
	s_cselect_b32 s2, s58, s64
	s_ashr_i32 s55, s54, 31
	s_lshl_b64 s[28:29], s[54:55], 17
	s_add_u32 s60, s68, s28
	s_addc_u32 s61, s69, s29
	s_and_b64 s[0:1], exec, s[0:1]
	s_cselect_b32 s1, s61, s67
	s_cselect_b32 s0, s60, s66
	s_add_u32 s28, s64, 0x80080
	s_addc_u32 s29, s65, 0
	s_add_i32 vcc_hi, s63, 0xc000
	v_lshl_add_u64 v[48:49], s[28:29], 0, v[140:141]
	s_mov_b32 m0, vcc_hi
	s_add_i32 s55, s63, 0xe000
	ds_read_b128 v[16:19], v216
	ds_read_b128 v[20:23], v216 offset:1024
	ds_read_b128 v[24:27], v216 offset:2048
	ds_read_b128 v[28:31], v216 offset:3072
	ds_read_b128 v[32:35], v216 offset:4096
	ds_read_b128 v[36:39], v216 offset:5120
	ds_read_b128 v[40:43], v216 offset:6144
	ds_read_b128 v[44:47], v216 offset:7168
	global_load_lds_dwordx4 v[48:49], off
	v_lshl_add_u64 v[48:49], s[28:29], 0, v[144:145]
	s_mov_b32 m0, s55
	s_nop 0
	global_load_lds_dwordx4 v[48:49], off
	s_waitcnt lgkmcnt(8)
	s_setprio 1
	s_barrier
	s_waitcnt lgkmcnt(0)
	v_mfma_f32_16x16x32_bf16 v[48:51], v[0:3], v[16:19], 0
	v_mfma_f32_16x16x32_bf16 v[52:55], v[8:11], v[16:19], 0
	v_mfma_f32_16x16x32_bf16 v[56:59], v[0:3], v[24:27], 0
	v_mfma_f32_16x16x32_bf16 v[60:63], v[8:11], v[24:27], 0
	v_mfma_f32_16x16x32_bf16 v[64:67], v[0:3], v[32:35], 0
	v_mfma_f32_16x16x32_bf16 v[68:71], v[8:11], v[32:35], 0
	v_mfma_f32_16x16x32_bf16 v[72:75], v[0:3], v[40:43], 0
	v_mfma_f32_16x16x32_bf16 v[76:79], v[8:11], v[40:43], 0
	v_mfma_f32_16x16x32_bf16 v[48:51], v[4:7], v[20:23], v[48:51]
	v_mfma_f32_16x16x32_bf16 v[52:55], v[12:15], v[20:23], v[52:55]
	v_mfma_f32_16x16x32_bf16 v[56:59], v[4:7], v[28:31], v[56:59]
	v_mfma_f32_16x16x32_bf16 v[60:63], v[12:15], v[28:31], v[60:63]
	v_mfma_f32_16x16x32_bf16 v[64:67], v[4:7], v[36:39], v[64:67]
	v_mfma_f32_16x16x32_bf16 v[68:71], v[12:15], v[36:39], v[68:71]
	v_mfma_f32_16x16x32_bf16 v[72:75], v[4:7], v[44:47], v[72:75]
	v_mfma_f32_16x16x32_bf16 v[76:79], v[12:15], v[44:47], v[76:79]
	s_barrier
	s_setprio 0
	v_lshl_add_u64 v[198:199], s[66:67], 0, v[142:143]
	s_add_i32 s96, s81, s70
	v_lshl_add_u64 v[96:97], v[198:199], 0, s[46:47]
	s_mov_b32 m0, s96
	v_lshl_add_u64 v[210:211], s[66:67], 0, v[146:147]
	s_add_i32 s57, s96, 0x2000
	ds_read_b128 v[80:83], v217
	ds_read_b128 v[84:87], v217 offset:1024
	ds_read_b128 v[88:91], v217 offset:2048
	ds_read_b128 v[92:95], v217 offset:3072
	global_load_lds_dwordx4 v[96:97], off
	v_lshl_add_u64 v[96:97], v[210:211], 0, s[46:47]
	s_mov_b32 m0, s57
	s_nop 0
	global_load_lds_dwordx4 v[96:97], off
	s_setprio 1
	s_barrier
	s_waitcnt lgkmcnt(0)
	v_mfma_f32_16x16x32_bf16 v[96:99], v[80:83], v[16:19], 0
	v_mfma_f32_16x16x32_bf16 v[16:19], v[88:91], v[16:19], 0
	v_mfma_f32_16x16x32_bf16 v[96:99], v[84:87], v[20:23], v[96:99]
	v_mfma_f32_16x16x32_bf16 v[16:19], v[92:95], v[20:23], v[16:19]
	v_mfma_f32_16x16x32_bf16 v[20:23], v[80:83], v[24:27], 0
	v_mfma_f32_16x16x32_bf16 v[24:27], v[88:91], v[24:27], 0
	v_mfma_f32_16x16x32_bf16 v[20:23], v[84:87], v[28:31], v[20:23]
	v_mfma_f32_16x16x32_bf16 v[24:27], v[92:95], v[28:31], v[24:27]
	v_mfma_f32_16x16x32_bf16 v[28:31], v[80:83], v[32:35], 0
	v_mfma_f32_16x16x32_bf16 v[32:35], v[88:91], v[32:35], 0
	v_mfma_f32_16x16x32_bf16 v[28:31], v[84:87], v[36:39], v[28:31]
	v_mfma_f32_16x16x32_bf16 v[32:35], v[92:95], v[36:39], v[32:35]
	v_mfma_f32_16x16x32_bf16 v[36:39], v[80:83], v[40:43], 0
	v_mfma_f32_16x16x32_bf16 v[40:43], v[88:91], v[40:43], 0
	v_mfma_f32_16x16x32_bf16 v[36:39], v[84:87], v[44:47], v[36:39]
	v_mfma_f32_16x16x32_bf16 v[40:43], v[92:95], v[44:47], v[40:43]
	s_setprio 0
	v_lshl_add_u64 v[224:225], s[64:65], 0, v[140:141]
	s_mov_b32 m0, s63
	v_lshl_add_u64 v[128:129], v[224:225], 0, s[46:47]
	v_lshl_add_u64 v[226:227], s[64:65], 0, v[144:145]
	s_barrier
	ds_read_b128 v[44:47], v216 offset:16384
	ds_read_b128 v[100:103], v216 offset:17408
	ds_read_b128 v[104:107], v216 offset:18432
	ds_read_b128 v[108:111], v216 offset:19456
	ds_read_b128 v[112:115], v216 offset:20480
	ds_read_b128 v[116:119], v216 offset:21504
	ds_read_b128 v[120:123], v216 offset:22528
	ds_read_b128 v[124:127], v216 offset:23552
	global_load_lds_dwordx4 v[128:129], off
	v_lshl_add_u64 v[128:129], v[226:227], 0, s[46:47]
	s_mov_b32 m0, s71
	s_nop 0
	global_load_lds_dwordx4 v[128:129], off
	s_setprio 1
	s_barrier
	s_waitcnt lgkmcnt(0)
	v_mfma_f32_16x16x32_bf16 v[128:131], v[0:3], v[44:47], 0
	v_mfma_f32_16x16x32_bf16 v[136:139], v[0:3], v[104:107], 0
	v_mfma_f32_16x16x32_bf16 v[158:161], v[0:3], v[112:115], 0
	v_mfma_f32_16x16x32_bf16 v[0:3], v[0:3], v[120:123], 0
	v_mfma_f32_16x16x32_bf16 v[128:131], v[4:7], v[100:103], v[128:131]
	v_mfma_f32_16x16x32_bf16 v[132:135], v[8:11], v[44:47], 0
	v_mfma_f32_16x16x32_bf16 v[136:139], v[4:7], v[108:111], v[136:139]
	v_mfma_f32_16x16x32_bf16 v[154:157], v[8:11], v[104:107], 0
	v_mfma_f32_16x16x32_bf16 v[158:161], v[4:7], v[116:119], v[158:161]
	v_mfma_f32_16x16x32_bf16 v[162:165], v[8:11], v[112:115], 0
	v_mfma_f32_16x16x32_bf16 v[0:3], v[4:7], v[124:127], v[0:3]
	v_mfma_f32_16x16x32_bf16 v[4:7], v[8:11], v[120:123], 0
	v_mfma_f32_16x16x32_bf16 v[132:135], v[12:15], v[100:103], v[132:135]
	v_mfma_f32_16x16x32_bf16 v[154:157], v[12:15], v[108:111], v[154:157]
	v_mfma_f32_16x16x32_bf16 v[162:165], v[12:15], v[116:119], v[162:165]
	v_mfma_f32_16x16x32_bf16 v[4:7], v[12:15], v[124:127], v[4:7]
	s_barrier
; #define PG8_STAGE(bufoff, gbase, voff) do { _Pragma("unroll") for (int _i = 0; _i < 2; ++_i) \
;         __builtin_amdgcn_global_load_lds((const unsigned*)((const char*)(gbase) + (voff)[_i]), (LAS unsigned*)(lds + (bufoff) + ldsw + _i * 8192), 16, 0, 0); } while (0)
; #define PG8_LDA(dst, b, h) do { _Pragma("unroll") for (int m = 0; m < 4; ++m) _Pragma("unroll") for (int k = 0; k < 2; ++k) dst[m][k] = *(const LAS bf16x8*)(lds + PG8_SA(b, h) + aoff + m * 2048 + k * 1024); } while (0)
; #define PG8_LDB(dst, b, h) do { _Pragma("unroll") for (int n = 0; n < 2; ++n) _Pragma("unroll") for (int k = 0; k < 2; ++k) dst[n][k] = *(const LAS bf16x8*)(lds + PG8_SB(b, h) + boff + n * 2048 + k * 1024); } while (0)
; #define PG8_WAIT_V(n) asm volatile("s_waitcnt vmcnt(" #n ")" ::: "memory")
; #define PG8_WAIT_L(n) asm volatile("s_waitcnt lgkmcnt(" #n ")" ::: "memory")
; #define PG8_BAR __builtin_amdgcn_s_barrier()
; #define PG8_SCHED __builtin_amdgcn_sched_barrier(0)
; template <class Epi>
; __device__ __forceinline__ void gemm_phase(LAS unsigned char* lds, const bf16_t* A, int lda, const bf16_t* Bt, int ldb, int M, int N, int K, int asel, const Epi& E, const int fixed_round = -1) {
;     ...
;             PG8_WAIT_V(6); PG8_BAR; PG8_MMA(1, 1, At, B1); PG8_BAR;
;             PG8_LDB(B0, 1, 0); PG8_SCHED; PG8_LDA(At, 1, 0); PG8_STAGE(PG8_SA(0, 1), a2 + hstepA, voffA);
;             PG8_WAIT_L(8); PG8_BAR; PG8_WAIT_L(0); PG8_MMA(0, 0, At, B0); PG8_BAR; PG8_SCHED;
;             PG8_LDB(B1, 1, 1); PG8_STAGE(PG8_SB(1, 0), b3, voffB);
;             PG8_BAR; PG8_WAIT_L(0); PG8_MMA(0, 1, At, B1); PG8_BAR;
;             PG8_LDA(At, 1, 1); PG8_STAGE(PG8_SA(1, 0), a3, voffA);
;             PG8_BAR; PG8_WAIT_L(0); PG8_MMA(1, 0, At, B0); PG8_BAR; PG8_SCHED;
	s_setprio 0
	s_add_u32 s28, s66, 0x10100
	s_addc_u32 s29, s67, 0
	s_add_i32 vcc_lo, s82, s70
	v_lshl_add_u64 v[8:9], s[28:29], 0, v[142:143]
	s_mov_b32 m0, vcc_lo
	s_add_i32 s95, vcc_lo, 0x2000
	global_load_lds_dwordx4 v[8:9], off
	v_lshl_add_u64 v[8:9], s[28:29], 0, v[146:147]
	s_mov_b32 m0, s95
	s_nop 0
	global_load_lds_dwordx4 v[8:9], off
	s_waitcnt vmcnt(6)
	s_setprio 1
	s_barrier
	v_mfma_f32_16x16x32_bf16 v[8:11], v[80:83], v[44:47], 0
	v_mfma_f32_16x16x32_bf16 v[12:15], v[88:91], v[44:47], 0
	v_mfma_f32_16x16x32_bf16 v[8:11], v[84:87], v[100:103], v[8:11]
	v_mfma_f32_16x16x32_bf16 v[12:15], v[92:95], v[100:103], v[12:15]
	v_mfma_f32_16x16x32_bf16 v[44:47], v[80:83], v[104:107], 0
	v_mfma_f32_16x16x32_bf16 v[100:103], v[88:91], v[104:107], 0
	v_mfma_f32_16x16x32_bf16 v[104:107], v[80:83], v[112:115], 0
	v_mfma_f32_16x16x32_bf16 v[80:83], v[80:83], v[120:123], 0
	v_mfma_f32_16x16x32_bf16 v[44:47], v[84:87], v[108:111], v[44:47]
	v_mfma_f32_16x16x32_bf16 v[100:103], v[92:95], v[108:111], v[100:103]
	v_mfma_f32_16x16x32_bf16 v[104:107], v[84:87], v[116:119], v[104:107]
	v_mfma_f32_16x16x32_bf16 v[108:111], v[88:91], v[112:115], 0
	v_mfma_f32_16x16x32_bf16 v[80:83], v[84:87], v[124:127], v[80:83]
	v_mfma_f32_16x16x32_bf16 v[84:87], v[88:91], v[120:123], 0
	v_mfma_f32_16x16x32_bf16 v[108:111], v[92:95], v[116:119], v[108:111]
	v_mfma_f32_16x16x32_bf16 v[84:87], v[92:95], v[124:127], v[84:87]
	s_barrier
	s_setprio 0
	v_add_u32_e32 v153, s83, v213
	ds_read_b128 v[88:91], v153
	ds_read_b128 v[92:95], v153 offset:1024
	ds_read_b128 v[112:115], v153 offset:2048
	ds_read_b128 v[116:119], v153 offset:3072
	s_add_u32 s28, s64, 0x80100
	s_addc_u32 s29, s65, 0
	s_mov_b32 m0, s72
	v_lshl_add_u64 v[190:191], s[28:29], 0, v[140:141]
	ds_read_b128 v[120:123], v216 offset:32768
	ds_read_b128 v[124:127], v216 offset:33792
	ds_read_b128 v[166:169], v216 offset:34816
	ds_read_b128 v[170:173], v216 offset:35840
	ds_read_b128 v[174:177], v216 offset:36864
	ds_read_b128 v[178:181], v216 offset:37888
	ds_read_b128 v[182:185], v216 offset:38912
	ds_read_b128 v[186:189], v216 offset:39936
	global_load_lds_dwordx4 v[190:191], off
	v_lshl_add_u64 v[190:191], s[28:29], 0, v[144:145]
	s_mov_b32 m0, s73
	s_nop 0
	global_load_lds_dwordx4 v[190:191], off
	s_waitcnt lgkmcnt(8)
	s_setprio 1
	s_barrier
	s_waitcnt lgkmcnt(0)
	v_mfma_f32_16x16x32_bf16 v[48:51], v[88:91], v[120:123], v[48:51]
	v_mfma_f32_16x16x32_bf16 v[52:55], v[112:115], v[120:123], v[52:55]
	v_mfma_f32_16x16x32_bf16 v[56:59], v[88:91], v[166:169], v[56:59]
	v_mfma_f32_16x16x32_bf16 v[60:63], v[112:115], v[166:169], v[60:63]
	v_mfma_f32_16x16x32_bf16 v[64:67], v[88:91], v[174:177], v[64:67]
	v_mfma_f32_16x16x32_bf16 v[68:71], v[112:115], v[174:177], v[68:71]
	v_mfma_f32_16x16x32_bf16 v[72:75], v[88:91], v[182:185], v[72:75]
	v_mfma_f32_16x16x32_bf16 v[76:79], v[112:115], v[182:185], v[76:79]
	v_mfma_f32_16x16x32_bf16 v[48:51], v[92:95], v[124:127], v[48:51]
	v_mfma_f32_16x16x32_bf16 v[52:55], v[116:119], v[124:127], v[52:55]
	v_mfma_f32_16x16x32_bf16 v[56:59], v[92:95], v[170:173], v[56:59]
	v_mfma_f32_16x16x32_bf16 v[60:63], v[116:119], v[170:173], v[60:63]
	v_mfma_f32_16x16x32_bf16 v[64:67], v[92:95], v[178:181], v[64:67]
	v_mfma_f32_16x16x32_bf16 v[68:71], v[116:119], v[178:181], v[68:71]
	v_mfma_f32_16x16x32_bf16 v[72:75], v[92:95], v[186:189], v[72:75]
	v_mfma_f32_16x16x32_bf16 v[76:79], v[116:119], v[186:189], v[76:79]
	s_barrier
	s_setprio 0
	s_add_i32 s97, s83, s70
	v_add_u32_e32 v223, s84, v213
	v_lshl_add_u64 v[198:199], v[198:199], 0, s[48:49]
	s_mov_b32 m0, s97
	s_add_i32 s28, s97, 0x2000
	ds_read_b128 v[190:193], v223
	ds_read_b128 v[194:197], v223 offset:1024
	ds_read_b128 v[202:205], v223 offset:2048
	ds_read_b128 v[206:209], v223 offset:3072
	global_load_lds_dwordx4 v[198:199], off
	v_lshl_add_u64 v[198:199], v[210:211], 0, s[48:49]
	s_mov_b32 m0, s28
	s_nop 0
	global_load_lds_dwordx4 v[198:199], off
	s_setprio 1
	s_barrier
	s_waitcnt lgkmcnt(0)
	v_mfma_f32_16x16x32_bf16 v[96:99], v[190:193], v[120:123], v[96:99]
	v_mfma_f32_16x16x32_bf16 v[16:19], v[202:205], v[120:123], v[16:19]
	v_mfma_f32_16x16x32_bf16 v[20:23], v[190:193], v[166:169], v[20:23]
	v_mfma_f32_16x16x32_bf16 v[24:27], v[202:205], v[166:169], v[24:27]
	v_mfma_f32_16x16x32_bf16 v[28:31], v[190:193], v[174:177], v[28:31]
	v_mfma_f32_16x16x32_bf16 v[32:35], v[202:205], v[174:177], v[32:35]
	v_mfma_f32_16x16x32_bf16 v[36:39], v[190:193], v[182:185], v[36:39]
	v_mfma_f32_16x16x32_bf16 v[40:43], v[202:205], v[182:185], v[40:43]
	v_mfma_f32_16x16x32_bf16 v[96:99], v[194:197], v[124:127], v[96:99]
	v_mfma_f32_16x16x32_bf16 v[16:19], v[206:209], v[124:127], v[16:19]
	v_mfma_f32_16x16x32_bf16 v[20:23], v[194:197], v[170:173], v[20:23]
	v_mfma_f32_16x16x32_bf16 v[24:27], v[206:209], v[170:173], v[24:27]
	v_mfma_f32_16x16x32_bf16 v[28:31], v[194:197], v[178:181], v[28:31]
	v_mfma_f32_16x16x32_bf16 v[32:35], v[206:209], v[178:181], v[32:35]
	v_mfma_f32_16x16x32_bf16 v[36:39], v[194:197], v[186:189], v[36:39]
	v_mfma_f32_16x16x32_bf16 v[40:43], v[206:209], v[186:189], v[40:43]
	s_setprio 0
	s_mov_b32 m0, s74
	v_lshl_add_u64 v[198:199], v[224:225], 0, s[48:49]
	s_barrier
	ds_read_b128 v[120:123], v216 offset:49152
	ds_read_b128 v[124:127], v216 offset:50176
	ds_read_b128 v[166:169], v216 offset:51200
	ds_read_b128 v[170:173], v216 offset:52224
	ds_read_b128 v[174:177], v216 offset:53248
	ds_read_b128 v[178:181], v216 offset:54272
	ds_read_b128 v[182:185], v216 offset:55296
	ds_read_b128 v[186:189], v216 offset:56320
	global_load_lds_dwordx4 v[198:199], off
	v_lshl_add_u64 v[198:199], v[226:227], 0, s[48:49]
	s_mov_b32 m0, s75
	s_nop 0
	global_load_lds_dwordx4 v[198:199], off
	s_setprio 1
	s_barrier
; #define PG8_STAGE(bufoff, gbase, voff) do { _Pragma("unroll") for (int _i = 0; _i < 2; ++_i) \
;         __builtin_amdgcn_global_load_lds((const unsigned*)((const char*)(gbase) + (voff)[_i]), (LAS unsigned*)(lds + (bufoff) + ldsw + _i * 8192), 16, 0, 0); } while (0)
; #define PG8_LDA(dst, b, h) do { _Pragma("unroll") for (int m = 0; m < 4; ++m) _Pragma("unroll") for (int k = 0; k < 2; ++k) dst[m][k] = *(const LAS bf16x8*)(lds + PG8_SA(b, h) + aoff + m * 2048 + k * 1024); } while (0)
; #define PG8_LDB(dst, b, h) do { _Pragma("unroll") for (int n = 0; n < 2; ++n) _Pragma("unroll") for (int k = 0; k < 2; ++k) dst[n][k] = *(const LAS bf16x8*)(lds + PG8_SB(b, h) + boff + n * 2048 + k * 1024); } while (0)
; #define PG8_WAIT_V(n) asm volatile("s_waitcnt vmcnt(" #n ")" ::: "memory")
; #define PG8_WAIT_L(n) asm volatile("s_waitcnt lgkmcnt(" #n ")" ::: "memory")
; #define PG8_BAR __builtin_amdgcn_s_barrier()
; #define PG8_SCHED __builtin_amdgcn_sched_barrier(0)
; template <class Epi>
; __device__ __forceinline__ void gemm_phase(LAS unsigned char* lds, const bf16_t* A, int lda, const bf16_t* Bt, int ldb, int M, int N, int K, int asel, const Epi& E, const int fixed_round = -1) {
;     ...
;             PG8_LDB(B0, 0, 0); PG8_SCHED; PG8_LDA(At, 0, 0); PG8_STAGE(PG8_SA(1, 1), a1 + hstepA, voffA);
;             PG8_WAIT_L(8); PG8_BAR; PG8_WAIT_L(0); PG8_MMA(0, 0, At, B0); PG8_BAR; PG8_SCHED;
;             PG8_LDB(B1, 0, 1); PG8_STAGE(PG8_SB(0, 0), b2, voffB);
;     ...
;             PG8_BAR; PG8_WAIT_L(0); PG8_MMA(1, 0, At, B0); PG8_BAR; PG8_SCHED;
;             PG8_STAGE(PG8_SB(1, 1), b3 + hstepB, voffB);
;             PG8_WAIT_V(6); PG8_BAR; PG8_MMA(1, 1, At, B1); PG8_BAR;
	s_waitcnt lgkmcnt(0)
	v_mfma_f32_16x16x32_bf16 v[128:131], v[88:91], v[120:123], v[128:131]
	v_mfma_f32_16x16x32_bf16 v[132:135], v[112:115], v[120:123], v[132:135]
	v_mfma_f32_16x16x32_bf16 v[136:139], v[88:91], v[166:169], v[136:139]
	v_mfma_f32_16x16x32_bf16 v[154:157], v[112:115], v[166:169], v[154:157]
	v_mfma_f32_16x16x32_bf16 v[158:161], v[88:91], v[174:177], v[158:161]
	v_mfma_f32_16x16x32_bf16 v[162:165], v[112:115], v[174:177], v[162:165]
	v_mfma_f32_16x16x32_bf16 v[0:3], v[88:91], v[182:185], v[0:3]
	v_mfma_f32_16x16x32_bf16 v[4:7], v[112:115], v[182:185], v[4:7]
	v_mfma_f32_16x16x32_bf16 v[128:131], v[92:95], v[124:127], v[128:131]
	v_mfma_f32_16x16x32_bf16 v[132:135], v[116:119], v[124:127], v[132:135]
	v_mfma_f32_16x16x32_bf16 v[136:139], v[92:95], v[170:173], v[136:139]
	v_mfma_f32_16x16x32_bf16 v[154:157], v[116:119], v[170:173], v[154:157]
	v_mfma_f32_16x16x32_bf16 v[158:161], v[92:95], v[178:181], v[158:161]
	v_mfma_f32_16x16x32_bf16 v[162:165], v[116:119], v[178:181], v[162:165]
	v_mfma_f32_16x16x32_bf16 v[0:3], v[92:95], v[186:189], v[0:3]
	v_mfma_f32_16x16x32_bf16 v[4:7], v[116:119], v[186:189], v[4:7]
	s_barrier
	s_setprio 0
	s_add_u32 s66, s66, 0x10180
	s_addc_u32 s67, s67, 0
	s_add_i32 s29, s84, s70
	v_lshl_add_u64 v[88:89], s[66:67], 0, v[142:143]
	s_mov_b32 m0, s29
	s_nop 0
	global_load_lds_dwordx4 v[88:89], off
	v_lshl_add_u64 v[88:89], s[66:67], 0, v[146:147]
	s_add_i32 s66, s29, 0x2000
	s_mov_b32 m0, s66
	s_nop 0
	global_load_lds_dwordx4 v[88:89], off
	s_waitcnt vmcnt(6)
	s_setprio 1
	s_barrier
	v_mfma_f32_16x16x32_bf16 v[8:11], v[190:193], v[120:123], v[8:11]
	v_mfma_f32_16x16x32_bf16 v[12:15], v[202:205], v[120:123], v[12:15]
	v_mfma_f32_16x16x32_bf16 v[44:47], v[190:193], v[166:169], v[44:47]
	v_mfma_f32_16x16x32_bf16 v[88:91], v[202:205], v[166:169], v[100:103]
	v_mfma_f32_16x16x32_bf16 v[92:95], v[190:193], v[174:177], v[104:107]
	v_mfma_f32_16x16x32_bf16 v[100:103], v[202:205], v[174:177], v[108:111]
	v_mfma_f32_16x16x32_bf16 v[80:83], v[190:193], v[182:185], v[80:83]
	v_mfma_f32_16x16x32_bf16 v[84:87], v[202:205], v[182:185], v[84:87]
	v_mfma_f32_16x16x32_bf16 v[8:11], v[194:197], v[124:127], v[8:11]
	v_mfma_f32_16x16x32_bf16 v[12:15], v[206:209], v[124:127], v[12:15]
	v_mfma_f32_16x16x32_bf16 v[44:47], v[194:197], v[170:173], v[44:47]
	v_mfma_f32_16x16x32_bf16 v[88:91], v[206:209], v[170:173], v[88:91]
	v_mfma_f32_16x16x32_bf16 v[92:95], v[194:197], v[178:181], v[92:95]
	v_mfma_f32_16x16x32_bf16 v[100:103], v[206:209], v[178:181], v[100:103]
	v_mfma_f32_16x16x32_bf16 v[80:83], v[194:197], v[186:189], v[80:83]
	v_mfma_f32_16x16x32_bf16 v[84:87], v[206:209], v[186:189], v[84:87]
	s_barrier
	s_setprio 0
	ds_read_b128 v[104:107], v215
	ds_read_b128 v[108:111], v215 offset:1024
	ds_read_b128 v[112:115], v215 offset:2048
	ds_read_b128 v[116:119], v215 offset:3072
	s_add_u32 s64, s64, 0x80180
	s_addc_u32 s65, s65, 0
	s_mov_b32 m0, vcc_hi
	v_lshl_add_u64 v[190:191], s[64:65], 0, v[140:141]
	ds_read_b128 v[120:123], v216
	ds_read_b128 v[124:127], v216 offset:1024
	ds_read_b128 v[166:169], v216 offset:2048
	ds_read_b128 v[170:173], v216 offset:3072
	ds_read_b128 v[174:177], v216 offset:4096
	ds_read_b128 v[178:181], v216 offset:5120
	ds_read_b128 v[182:185], v216 offset:6144
	ds_read_b128 v[186:189], v216 offset:7168
	global_load_lds_dwordx4 v[190:191], off
	v_lshl_add_u64 v[190:191], s[64:65], 0, v[144:145]
	s_mov_b32 m0, s55
	s_nop 0
	global_load_lds_dwordx4 v[190:191], off
	s_waitcnt lgkmcnt(8)
	s_setprio 1
	s_barrier
	s_waitcnt lgkmcnt(0)
	v_mfma_f32_16x16x32_bf16 v[56:59], v[104:107], v[166:169], v[56:59]
	v_mfma_f32_16x16x32_bf16 v[190:193], v[108:111], v[170:173], v[56:59]
	v_mfma_f32_16x16x32_bf16 v[56:59], v[112:115], v[166:169], v[60:63]
	v_mfma_f32_16x16x32_bf16 v[60:63], v[116:119], v[170:173], v[56:59]
	v_mfma_f32_16x16x32_bf16 v[56:59], v[104:107], v[174:177], v[64:67]
	v_mfma_f32_16x16x32_bf16 v[64:67], v[108:111], v[178:181], v[56:59]
	v_mfma_f32_16x16x32_bf16 v[56:59], v[112:115], v[174:177], v[68:71]
	v_mfma_f32_16x16x32_bf16 v[68:71], v[116:119], v[178:181], v[56:59]
	v_mfma_f32_16x16x32_bf16 v[56:59], v[104:107], v[182:185], v[72:75]
	v_mfma_f32_16x16x32_bf16 v[48:51], v[104:107], v[120:123], v[48:51]
	v_mfma_f32_16x16x32_bf16 v[52:55], v[112:115], v[120:123], v[52:55]
	v_mfma_f32_16x16x32_bf16 v[72:75], v[108:111], v[186:189], v[56:59]
	v_mfma_f32_16x16x32_bf16 v[56:59], v[112:115], v[182:185], v[76:79]
	v_mfma_f32_16x16x32_bf16 v[48:51], v[108:111], v[124:127], v[48:51]
	v_mfma_f32_16x16x32_bf16 v[52:55], v[116:119], v[124:127], v[52:55]
	v_mfma_f32_16x16x32_bf16 v[76:79], v[116:119], v[186:189], v[56:59]
	s_barrier
	s_setprio 0
	s_mov_b32 m0, s96
	v_lshl_add_u64 v[198:199], s[0:1], 0, v[142:143]
	s_nop 0
	ds_read_b128 v[56:59], v217
	ds_read_b128 v[194:197], v217 offset:1024
	ds_read_b128 v[202:205], v217 offset:2048
	ds_read_b128 v[206:209], v217 offset:3072
	global_load_lds_dwordx4 v[198:199], off
	v_lshl_add_u64 v[210:211], s[0:1], 0, v[146:147]
	s_mov_b32 m0, s57
	s_nop 0
	global_load_lds_dwordx4 v[210:211], off
	s_setprio 1
	s_barrier
; #define PG8_STAGE(bufoff, gbase, voff) do { _Pragma("unroll") for (int _i = 0; _i < 2; ++_i) \
;         __builtin_amdgcn_global_load_lds((const unsigned*)((const char*)(gbase) + (voff)[_i]), (LAS unsigned*)(lds + (bufoff) + ldsw + _i * 8192), 16, 0, 0); } while (0)
; #define PG8_LDA(dst, b, h) do { _Pragma("unroll") for (int m = 0; m < 4; ++m) _Pragma("unroll") for (int k = 0; k < 2; ++k) dst[m][k] = *(const LAS bf16x8*)(lds + PG8_SA(b, h) + aoff + m * 2048 + k * 1024); } while (0)
; #define PG8_LDB(dst, b, h) do { _Pragma("unroll") for (int n = 0; n < 2; ++n) _Pragma("unroll") for (int k = 0; k < 2; ++k) dst[n][k] = *(const LAS bf16x8*)(lds + PG8_SB(b, h) + boff + n * 2048 + k * 1024); } while (0)
; #define PG8_WAIT_V(n) asm volatile("s_waitcnt vmcnt(" #n ")" ::: "memory")
; #define PG8_WAIT_L(n) asm volatile("s_waitcnt lgkmcnt(" #n ")" ::: "memory")
; #define PG8_BAR __builtin_amdgcn_s_barrier()
; #define PG8_SCHED __builtin_amdgcn_sched_barrier(0)
; template <class Epi>
; __device__ __forceinline__ void gemm_phase(LAS unsigned char* lds, const bf16_t* A, int lda, const bf16_t* Bt, int ldb, int M, int N, int K, int asel, const Epi& E, const int fixed_round = -1) {
;     ...
;             PG8_LDB(B1, 0, 1); PG8_STAGE(PG8_SB(0, 0), b2, voffB);
;             PG8_BAR; PG8_WAIT_L(0); PG8_MMA(0, 1, At, B1); PG8_BAR;
;             PG8_LDA(At, 0, 1); PG8_STAGE(PG8_SA(0, 0), a2, voffA);
;             PG8_BAR; PG8_WAIT_L(0); PG8_MMA(1, 0, At, B0); PG8_BAR; PG8_SCHED;
;             PG8_STAGE(PG8_SB(0, 1), b2 + hstepB, voffB);
;             PG8_WAIT_V(6); PG8_BAR; PG8_MMA(1, 1, At, B1); PG8_BAR;
;             PG8_LDB(B0, 1, 0); PG8_SCHED; PG8_LDA(At, 1, 0); PG8_STAGE(PG8_SA(0, 1), a2 + hstepA, voffA);
;             PG8_WAIT_L(8); PG8_BAR; PG8_WAIT_L(0); PG8_MMA(0, 0, At, B0); PG8_BAR; PG8_SCHED;
	s_waitcnt lgkmcnt(0)
	v_mfma_f32_16x16x32_bf16 v[32:35], v[202:205], v[174:177], v[32:35]
	v_mfma_f32_16x16x32_bf16 v[20:23], v[56:59], v[166:169], v[20:23]
	v_mfma_f32_16x16x32_bf16 v[24:27], v[202:205], v[166:169], v[24:27]
	v_mfma_f32_16x16x32_bf16 v[166:169], v[206:209], v[178:181], v[32:35]
	v_mfma_f32_16x16x32_bf16 v[32:35], v[56:59], v[182:185], v[36:39]
	v_mfma_f32_16x16x32_bf16 v[96:99], v[56:59], v[120:123], v[96:99]
	v_mfma_f32_16x16x32_bf16 v[16:19], v[202:205], v[120:123], v[16:19]
	v_mfma_f32_16x16x32_bf16 v[28:31], v[56:59], v[174:177], v[28:31]
	v_mfma_f32_16x16x32_bf16 v[36:39], v[194:197], v[186:189], v[32:35]
	v_mfma_f32_16x16x32_bf16 v[32:35], v[202:205], v[182:185], v[40:43]
	v_mfma_f32_16x16x32_bf16 v[96:99], v[194:197], v[124:127], v[96:99]
	v_mfma_f32_16x16x32_bf16 v[16:19], v[206:209], v[124:127], v[16:19]
	v_mfma_f32_16x16x32_bf16 v[20:23], v[194:197], v[170:173], v[20:23]
	v_mfma_f32_16x16x32_bf16 v[24:27], v[206:209], v[170:173], v[24:27]
	v_mfma_f32_16x16x32_bf16 v[28:31], v[194:197], v[178:181], v[28:31]
	v_mfma_f32_16x16x32_bf16 v[170:173], v[206:209], v[186:189], v[32:35]
	s_setprio 0
	s_mov_b32 m0, s63
	v_lshl_add_u64 v[252:253], s[2:3], 0, v[140:141]
	s_barrier
	ds_read_b128 v[32:35], v216 offset:16384
	ds_read_b128 v[40:43], v216 offset:17408
	ds_read_b128 v[120:123], v216 offset:18432
	ds_read_b128 v[124:127], v216 offset:19456
	ds_read_b128 v[174:177], v216 offset:20480
	ds_read_b128 v[178:181], v216 offset:21504
	ds_read_b128 v[182:185], v216 offset:22528
	ds_read_b128 v[186:189], v216 offset:23552
	global_load_lds_dwordx4 v[252:253], off
	v_lshl_add_u64 v[148:149], s[2:3], 0, v[144:145]
	s_mov_b32 m0, s71
	s_nop 0
	global_load_lds_dwordx4 v[148:149], off
	s_setprio 1
	s_barrier
	s_waitcnt lgkmcnt(0)
	v_mfma_f32_16x16x32_bf16 v[128:131], v[104:107], v[32:35], v[128:131]
	v_mfma_f32_16x16x32_bf16 v[224:227], v[108:111], v[40:43], v[128:131]
	v_mfma_f32_16x16x32_bf16 v[128:131], v[112:115], v[32:35], v[132:135]
	v_mfma_f32_16x16x32_bf16 v[228:231], v[116:119], v[40:43], v[128:131]
	v_mfma_f32_16x16x32_bf16 v[128:131], v[104:107], v[120:123], v[136:139]
	v_mfma_f32_16x16x32_bf16 v[136:139], v[108:111], v[124:127], v[128:131]
	v_mfma_f32_16x16x32_bf16 v[128:131], v[112:115], v[120:123], v[154:157]
	v_mfma_f32_16x16x32_bf16 v[154:157], v[116:119], v[124:127], v[128:131]
	v_mfma_f32_16x16x32_bf16 v[128:131], v[104:107], v[174:177], v[158:161]
	v_mfma_f32_16x16x32_bf16 v[158:161], v[108:111], v[178:181], v[128:131]
	v_mfma_f32_16x16x32_bf16 v[128:131], v[112:115], v[174:177], v[162:165]
	v_mfma_f32_16x16x32_bf16 v[0:3], v[104:107], v[182:185], v[0:3]
	v_mfma_f32_16x16x32_bf16 v[4:7], v[112:115], v[182:185], v[4:7]
	v_mfma_f32_16x16x32_bf16 v[162:165], v[116:119], v[178:181], v[128:131]
	v_mfma_f32_16x16x32_bf16 v[0:3], v[108:111], v[186:189], v[0:3]
	v_mfma_f32_16x16x32_bf16 v[4:7], v[116:119], v[186:189], v[4:7]
	s_barrier
	s_setprio 0
	s_add_u32 s64, s0, 0x10000
	s_addc_u32 s65, s1, 0
	s_mov_b32 m0, vcc_lo
	v_lshl_add_u64 v[104:105], s[64:65], 0, v[142:143]
	global_load_lds_dwordx4 v[104:105], off
	v_lshl_add_u64 v[104:105], s[64:65], 0, v[146:147]
	s_mov_b32 m0, s95
	s_nop 0
	global_load_lds_dwordx4 v[104:105], off
	s_waitcnt vmcnt(6)
	s_setprio 1
	s_barrier
	v_mfma_f32_16x16x32_bf16 v[8:11], v[56:59], v[32:35], v[8:11]
	v_mfma_f32_16x16x32_bf16 v[232:235], v[194:197], v[40:43], v[8:11]
	v_mfma_f32_16x16x32_bf16 v[8:11], v[202:205], v[32:35], v[12:15]
	v_mfma_f32_16x16x32_bf16 v[12:15], v[206:209], v[40:43], v[8:11]
	v_mfma_f32_16x16x32_bf16 v[8:11], v[56:59], v[120:123], v[44:47]
	v_mfma_f32_16x16x32_bf16 v[236:239], v[194:197], v[124:127], v[8:11]
	v_mfma_f32_16x16x32_bf16 v[8:11], v[202:205], v[120:123], v[88:91]
	v_mfma_f32_16x16x32_bf16 v[240:243], v[206:209], v[124:127], v[8:11]
	v_mfma_f32_16x16x32_bf16 v[8:11], v[56:59], v[174:177], v[92:95]
	v_mfma_f32_16x16x32_bf16 v[244:247], v[194:197], v[178:181], v[8:11]
	v_mfma_f32_16x16x32_bf16 v[8:11], v[202:205], v[174:177], v[100:103]
	v_mfma_f32_16x16x32_bf16 v[174:177], v[206:209], v[178:181], v[8:11]
	v_mfma_f32_16x16x32_bf16 v[8:11], v[56:59], v[182:185], v[80:83]
	v_mfma_f32_16x16x32_bf16 v[178:181], v[194:197], v[186:189], v[8:11]
	v_mfma_f32_16x16x32_bf16 v[8:11], v[202:205], v[182:185], v[84:87]
	v_mfma_f32_16x16x32_bf16 v[182:185], v[206:209], v[186:189], v[8:11]
	s_barrier
	s_setprio 0
	ds_read_b128 v[84:87], v153
	ds_read_b128 v[92:95], v153 offset:1024
	ds_read_b128 v[100:103], v153 offset:2048
	ds_read_b128 v[186:189], v153 offset:3072
	s_add_u32 s2, s2, 0x80000
	s_addc_u32 s3, s3, 0
	s_mov_b32 m0, s72
	v_lshl_add_u64 v[32:33], s[2:3], 0, v[140:141]
	ds_read_b128 v[8:11], v216 offset:32768
	ds_read_b128 v[44:47], v216 offset:33792
	ds_read_b128 v[80:83], v216 offset:34816
	ds_read_b128 v[88:91], v216 offset:35840
	ds_read_b128 v[108:111], v216 offset:36864
	ds_read_b128 v[194:197], v216 offset:37888
	ds_read_b128 v[202:205], v216 offset:38912
	ds_read_b128 v[206:209], v216 offset:39936
	global_load_lds_dwordx4 v[32:33], off
	v_lshl_add_u64 v[32:33], s[2:3], 0, v[144:145]
	s_mov_b32 m0, s73
	s_nop 0
	global_load_lds_dwordx4 v[32:33], off
	s_waitcnt lgkmcnt(8)
	s_setprio 1
	s_barrier
; #define PG8_STAGE(bufoff, gbase, voff) do { _Pragma("unroll") for (int _i = 0; _i < 2; ++_i) \
;         __builtin_amdgcn_global_load_lds((const unsigned*)((const char*)(gbase) + (voff)[_i]), (LAS unsigned*)(lds + (bufoff) + ldsw + _i * 8192), 16, 0, 0); } while (0)
; #define PG8_LDA(dst, b, h) do { _Pragma("unroll") for (int m = 0; m < 4; ++m) _Pragma("unroll") for (int k = 0; k < 2; ++k) dst[m][k] = *(const LAS bf16x8*)(lds + PG8_SA(b, h) + aoff + m * 2048 + k * 1024); } while (0)
; #define PG8_LDB(dst, b, h) do { _Pragma("unroll") for (int n = 0; n < 2; ++n) _Pragma("unroll") for (int k = 0; k < 2; ++k) dst[n][k] = *(const LAS bf16x8*)(lds + PG8_SB(b, h) + boff + n * 2048 + k * 1024); } while (0)
; #define PG8_WAIT_V(n) asm volatile("s_waitcnt vmcnt(" #n ")" ::: "memory")
; #define PG8_WAIT_L(n) asm volatile("s_waitcnt lgkmcnt(" #n ")" ::: "memory")
; #define PG8_BAR __builtin_amdgcn_s_barrier()
; #define PG8_SCHED __builtin_amdgcn_sched_barrier(0)
; template <class Epi>
; __device__ __forceinline__ void gemm_phase(LAS unsigned char* lds, const bf16_t* A, int lda, const bf16_t* Bt, int ldb, int M, int N, int K, int asel, const Epi& E, const int fixed_round = -1) {
;     ...
;             PG8_WAIT_L(8); PG8_BAR; PG8_WAIT_L(0); PG8_MMA(0, 0, At, B0); PG8_BAR; PG8_SCHED;
;             PG8_LDB(B1, 1, 1); PG8_STAGE(PG8_SB(1, 0), b3, voffB);
;             PG8_BAR; PG8_WAIT_L(0); PG8_MMA(0, 1, At, B1); PG8_BAR;
;             PG8_LDA(At, 1, 1); PG8_STAGE(PG8_SA(1, 0), a3, voffA);
;             PG8_BAR; PG8_WAIT_L(0); PG8_MMA(1, 0, At, B0); PG8_BAR; PG8_SCHED;
;             PG8_STAGE(PG8_SB(1, 1), b3 + hstepB, voffB);
;             PG8_WAIT_V(6); PG8_BAR; PG8_MMA(1, 1, At, B1); PG8_BAR;
	s_waitcnt lgkmcnt(0)
	v_mfma_f32_16x16x32_bf16 v[32:35], v[84:87], v[8:11], v[48:51]
	v_mfma_f32_16x16x32_bf16 v[128:131], v[92:95], v[44:47], v[32:35]
	v_mfma_f32_16x16x32_bf16 v[32:35], v[100:103], v[8:11], v[52:55]
	v_mfma_f32_16x16x32_bf16 v[56:59], v[186:189], v[44:47], v[32:35]
	v_mfma_f32_16x16x32_bf16 v[32:35], v[84:87], v[80:83], v[190:193]
	v_mfma_f32_16x16x32_bf16 v[120:123], v[92:95], v[88:91], v[32:35]
	v_mfma_f32_16x16x32_bf16 v[32:35], v[100:103], v[80:83], v[60:63]
	v_mfma_f32_16x16x32_bf16 v[48:51], v[186:189], v[88:91], v[32:35]
	v_mfma_f32_16x16x32_bf16 v[32:35], v[84:87], v[108:111], v[64:67]
	v_mfma_f32_16x16x32_bf16 v[112:115], v[92:95], v[194:197], v[32:35]
	v_mfma_f32_16x16x32_bf16 v[32:35], v[100:103], v[108:111], v[68:71]
	v_mfma_f32_16x16x32_bf16 v[40:43], v[186:189], v[194:197], v[32:35]
	v_mfma_f32_16x16x32_bf16 v[32:35], v[84:87], v[202:205], v[72:75]
	v_mfma_f32_16x16x32_bf16 v[104:107], v[92:95], v[206:209], v[32:35]
	v_mfma_f32_16x16x32_bf16 v[32:35], v[100:103], v[202:205], v[76:79]
	v_mfma_f32_16x16x32_bf16 v[32:35], v[186:189], v[206:209], v[32:35]
	s_barrier
	s_setprio 0
	s_mov_b32 m0, s97
	v_lshl_add_u64 v[52:53], v[198:199], 0, s[44:45]
	ds_read_b128 v[68:71], v223
	ds_read_b128 v[72:75], v223 offset:1024
	ds_read_b128 v[76:79], v223 offset:2048
	ds_read_b128 v[190:193], v223 offset:3072
	global_load_lds_dwordx4 v[52:53], off
	v_lshl_add_u64 v[52:53], v[210:211], 0, s[44:45]
	s_mov_b32 m0, s28
	s_nop 0
	global_load_lds_dwordx4 v[52:53], off
	s_setprio 1
	s_barrier
	s_waitcnt lgkmcnt(0)
	v_mfma_f32_16x16x32_bf16 v[52:55], v[68:71], v[8:11], v[96:99]
	v_mfma_f32_16x16x32_bf16 v[8:11], v[76:79], v[8:11], v[16:19]
	v_mfma_f32_16x16x32_bf16 v[60:63], v[190:193], v[44:47], v[8:11]
	v_mfma_f32_16x16x32_bf16 v[8:11], v[68:71], v[80:83], v[20:23]
	v_mfma_f32_16x16x32_bf16 v[124:127], v[72:75], v[88:91], v[8:11]
	v_mfma_f32_16x16x32_bf16 v[8:11], v[76:79], v[80:83], v[24:27]
	v_mfma_f32_16x16x32_bf16 v[132:135], v[72:75], v[44:47], v[52:55]
	v_mfma_f32_16x16x32_bf16 v[52:55], v[190:193], v[88:91], v[8:11]
	v_mfma_f32_16x16x32_bf16 v[8:11], v[68:71], v[108:111], v[28:31]
	v_mfma_f32_16x16x32_bf16 v[116:119], v[72:75], v[194:197], v[8:11]
	v_mfma_f32_16x16x32_bf16 v[8:11], v[76:79], v[108:111], v[166:169]
	v_mfma_f32_16x16x32_bf16 v[44:47], v[190:193], v[194:197], v[8:11]
	v_mfma_f32_16x16x32_bf16 v[8:11], v[68:71], v[202:205], v[36:39]
	v_mfma_f32_16x16x32_bf16 v[108:111], v[72:75], v[206:209], v[8:11]
	v_mfma_f32_16x16x32_bf16 v[8:11], v[76:79], v[202:205], v[170:173]
	v_mfma_f32_16x16x32_bf16 v[36:39], v[190:193], v[206:209], v[8:11]
	s_setprio 0
	s_mov_b32 m0, s74
	s_nop 4
	v_lshl_add_u64 v[8:9], v[252:253], 0, s[44:45]
	s_barrier
	ds_read_b128 v[20:23], v216 offset:49152
	ds_read_b128 v[28:31], v216 offset:50176
	ds_read_b128 v[166:169], v216 offset:51200
	ds_read_b128 v[170:173], v216 offset:52224
	ds_read_b128 v[194:197], v216 offset:53248
	ds_read_b128 v[202:205], v216 offset:54272
	ds_read_b128 v[206:209], v216 offset:55296
	ds_read_b128 v[248:251], v216 offset:56320
	global_load_lds_dwordx4 v[8:9], off
	v_lshl_add_u64 v[8:9], v[148:149], 0, s[44:45]
	s_mov_b32 m0, s75
	s_nop 0
	global_load_lds_dwordx4 v[8:9], off
	s_setprio 1
	s_barrier
	s_waitcnt lgkmcnt(0)
	v_mfma_f32_16x16x32_bf16 v[8:11], v[84:87], v[20:23], v[224:227]
	v_mfma_f32_16x16x32_bf16 v[96:99], v[92:95], v[28:31], v[8:11]
	v_mfma_f32_16x16x32_bf16 v[8:11], v[100:103], v[20:23], v[228:231]
	v_mfma_f32_16x16x32_bf16 v[24:27], v[186:189], v[28:31], v[8:11]
	v_mfma_f32_16x16x32_bf16 v[8:11], v[84:87], v[166:169], v[136:139]
	v_mfma_f32_16x16x32_bf16 v[88:91], v[92:95], v[170:173], v[8:11]
	v_mfma_f32_16x16x32_bf16 v[8:11], v[100:103], v[166:169], v[154:157]
	v_mfma_f32_16x16x32_bf16 v[16:19], v[186:189], v[170:173], v[8:11]
	v_mfma_f32_16x16x32_bf16 v[8:11], v[84:87], v[194:197], v[158:161]
	v_mfma_f32_16x16x32_bf16 v[0:3], v[84:87], v[206:209], v[0:3]
	v_mfma_f32_16x16x32_bf16 v[80:83], v[92:95], v[202:205], v[8:11]
	v_mfma_f32_16x16x32_bf16 v[8:11], v[100:103], v[194:197], v[162:165]
	v_mfma_f32_16x16x32_bf16 v[64:67], v[92:95], v[248:251], v[0:3]
	v_mfma_f32_16x16x32_bf16 v[0:3], v[100:103], v[206:209], v[4:7]
	v_mfma_f32_16x16x32_bf16 v[8:11], v[186:189], v[202:205], v[8:11]
	v_mfma_f32_16x16x32_bf16 v[0:3], v[186:189], v[248:251], v[0:3]
	s_barrier
	s_setprio 0
	s_add_u32 s0, s0, 0x10080
	s_addc_u32 s1, s1, 0
	s_mov_b32 m0, s29
	v_lshl_add_u64 v[4:5], s[0:1], 0, v[142:143]
	global_load_lds_dwordx4 v[4:5], off
	v_lshl_add_u64 v[4:5], s[0:1], 0, v[146:147]
	s_mov_b32 m0, s66
	s_nop 0
	global_load_lds_dwordx4 v[4:5], off
	s_waitcnt vmcnt(6)
	s_setprio 1
	s_barrier
; #define PG8_WAIT_V(n) asm volatile("s_waitcnt vmcnt(" #n ")" ::: "memory")
; #define PG8_BAR __builtin_amdgcn_s_barrier()
; template <class Epi>
; __device__ __forceinline__ void gemm_phase(LAS unsigned char* lds, const bf16_t* A, int lda, const bf16_t* Bt, int ldb, int M, int N, int K, int asel, const Epi& E, const int fixed_round = -1) {
;     ...
;             PG8_WAIT_V(6); PG8_BAR; PG8_MMA(1, 1, At, B1); PG8_BAR;
;     __device__ __forceinline__ void operator()(const AccT& acc, const Unit& u, int wr, int wc, int fr, int fq) const {
;         const int row0 = u.pm * BM + wr * 64 + fr, ch0 = u.pn * HALF + wc * 32 + 4 * fq;
; #pragma unroll
;         for (int n = 0; n < 2; ++n) {
;             u32x2 xw[2][4];
; #pragma unroll
;             for (int ai = 0; ai < 2; ++ai)
; #pragma unroll
;                 for (int m = 0; m < 4; ++m) xw[ai][m] = *(const u32x2*)(XC + (size_t)(row0 + ai * HALF + m * 16) * DM + ch0 + 16 * n);
;             const f32x4 bra = *(const f32x4*)(b_ra + ch0 + 16 * n), bri = *(const f32x4*)(b_ri + ch0 + 16 * n), l = *(const f32x4*)(lam + ch0 + 16 * n);
;             f32x4 sp;
; #pragma unroll
;             for (int j = 0; j < 4; ++j) sp[j] = -8.0f * log1pf(__expf(-l[j]));
	v_mfma_f32_16x16x32_bf16 v[4:7], v[68:71], v[20:23], v[232:235]
	v_mfma_f32_16x16x32_bf16 v[100:103], v[72:75], v[28:31], v[4:7]
	v_mfma_f32_16x16x32_bf16 v[4:7], v[76:79], v[20:23], v[12:15]
	v_mfma_f32_16x16x32_bf16 v[28:31], v[190:193], v[28:31], v[4:7]
	v_mfma_f32_16x16x32_bf16 v[4:7], v[68:71], v[166:169], v[236:239]
	v_mfma_f32_16x16x32_bf16 v[92:95], v[72:75], v[170:173], v[4:7]
	v_mfma_f32_16x16x32_bf16 v[4:7], v[76:79], v[166:169], v[240:243]
	v_mfma_f32_16x16x32_bf16 v[20:23], v[190:193], v[170:173], v[4:7]
	v_mfma_f32_16x16x32_bf16 v[4:7], v[68:71], v[194:197], v[244:247]
	v_mfma_f32_16x16x32_bf16 v[84:87], v[72:75], v[202:205], v[4:7]
	v_mfma_f32_16x16x32_bf16 v[4:7], v[76:79], v[194:197], v[174:177]
	v_mfma_f32_16x16x32_bf16 v[12:15], v[190:193], v[202:205], v[4:7]
	v_mfma_f32_16x16x32_bf16 v[4:7], v[68:71], v[206:209], v[178:181]
	v_mfma_f32_16x16x32_bf16 v[68:71], v[72:75], v[248:251], v[4:7]
	v_mfma_f32_16x16x32_bf16 v[4:7], v[76:79], v[206:209], v[182:185]
	v_mfma_f32_16x16x32_bf16 v[4:7], v[190:193], v[248:251], v[4:7]
	s_setprio 0
	v_readlane_b32 s8, v254, 8
	v_lshl_or_b32 v72, s94, 7, v214
	v_readlane_b32 s12, v254, 12
	v_readlane_b32 s13, v254, 13
	v_readlane_b32 s14, v254, 14
	v_readlane_b32 s15, v254, 15
	v_readlane_b32 s20, v254, 20
	v_readlane_b32 s21, v254, 21
	v_ashrrev_i32_e32 v73, 31, v72
	v_readlane_b32 s22, v254, 22
	v_readlane_b32 s23, v254, 23
	s_mov_b64 s[12:13], s[20:21]
	v_lshlrev_b64 v[174:175], 2, v[72:73]
	s_mov_b64 s[14:15], s[22:23]
	v_lshl_add_u64 v[172:173], s[14:15], 0, v[174:175]
	global_load_dwordx4 v[136:139], v[172:173], off
	v_lshl_add_u32 v206, s62, 8, v212
	v_ashrrev_i32_e32 v207, 31, v206
	v_or_b32_e32 v202, 16, v206
	v_lshl_add_u64 v[74:75], v[72:73], 1, s[6:7]
	v_lshlrev_b64 v[76:77], 12, v[206:207]
	v_ashrrev_i32_e32 v203, 31, v202
	v_or_b32_e32 v196, 32, v206
	v_lshl_add_u64 v[154:155], v[74:75], 0, v[76:77]
	v_lshlrev_b64 v[76:77], 12, v[202:203]
	v_ashrrev_i32_e32 v197, 31, v196
	v_or_b32_e32 v192, 48, v206
	v_lshl_add_u64 v[156:157], v[74:75], 0, v[76:77]
	v_lshlrev_b64 v[76:77], 12, v[196:197]
	v_ashrrev_i32_e32 v193, 31, v192
	v_add_u32_e32 v188, 0x80, v206
	v_lshl_add_u64 v[158:159], v[74:75], 0, v[76:77]
	v_lshlrev_b64 v[76:77], 12, v[192:193]
	v_ashrrev_i32_e32 v189, 31, v188
	v_add_u32_e32 v184, 0x90, v206
	v_lshl_add_u64 v[160:161], v[74:75], 0, v[76:77]
	v_lshlrev_b64 v[76:77], 12, v[188:189]
	v_ashrrev_i32_e32 v185, 31, v184
	v_add_u32_e32 v180, 0xa0, v206
	v_lshl_add_u64 v[162:163], v[74:75], 0, v[76:77]
	v_lshlrev_b64 v[76:77], 12, v[184:185]
	v_ashrrev_i32_e32 v181, 31, v180
	v_add_u32_e32 v170, 0xb0, v206
	v_readlane_b32 s9, v254, 9
	v_readlane_b32 s16, v254, 16
	v_readlane_b32 s17, v254, 17
	v_lshl_add_u64 v[164:165], v[74:75], 0, v[76:77]
	v_lshlrev_b64 v[76:77], 12, v[180:181]
	v_ashrrev_i32_e32 v171, 31, v170
	s_mov_b64 s[8:9], s[16:17]
	v_lshl_add_u64 v[166:167], v[74:75], 0, v[76:77]
	v_lshlrev_b64 v[76:77], 12, v[170:171]
	v_lshl_add_u64 v[176:177], s[8:9], 0, v[174:175]
	v_lshl_add_u64 v[168:169], v[74:75], 0, v[76:77]
	global_load_dwordx4 v[76:79], v[176:177], off
	v_lshl_add_u64 v[178:179], s[12:13], 0, v[174:175]
	global_load_dwordx4 v[72:75], v[178:179], off
	global_load_dwordx2 v[210:211], v[154:155], off
	global_load_dwordx2 v[208:209], v[156:157], off
	global_load_dwordx2 v[204:205], v[158:159], off
	global_load_dwordx2 v[198:199], v[160:161], off
	global_load_dwordx2 v[194:195], v[162:163], off
	global_load_dwordx2 v[190:191], v[164:165], off
	global_load_dwordx2 v[186:187], v[166:167], off
	global_load_dwordx2 v[182:183], v[168:169], off
	v_readlane_b32 s96, v254, 58
	s_mov_b64 s[2:3], s[52:53]
	s_mov_b32 s94, s54
	s_mov_b32 s62, s56
	s_mov_b64 s[66:67], s[60:61]
	s_mov_b64 s[64:65], s[58:59]
	v_readlane_b32 s97, v254, 59
	v_readlane_b32 s10, v254, 10
	v_readlane_b32 s11, v254, 11
	v_readlane_b32 s18, v254, 18
	v_readlane_b32 s19, v254, 19
	s_barrier
	s_waitcnt vmcnt(0)
	v_mul_f32_e32 v136, 0xbfb8aa3b, v136
	v_exp_f32_e32 v136, v136
	v_mul_f32_e32 v137, 0xbfb8aa3b, v137
	v_exp_f32_e32 v137, v137
	v_mul_f32_e32 v138, 0xbfb8aa3b, v138
	v_add_f32_e32 v153, 1.0, v136
	v_add_f32_e32 v148, -1.0, v153
	v_sub_f32_e32 v149, v148, v153
	v_add_f32_e32 v149, 1.0, v149
	v_sub_f32_e32 v148, v136, v148
	v_add_f32_e32 v223, v148, v149
	v_frexp_mant_f32_e32 v148, v153
	v_cmp_gt_f32_e32 vcc, s76, v148
	v_cvt_f64_f32_e32 v[148:149], v153
	v_frexp_exp_i32_f64_e32 v148, v[148:149]
	v_subbrev_co_u32_e32 v230, vcc, 0, v148, vcc
	v_sub_u32_e32 v148, 0, v230
	v_ldexp_f32 v149, v153, v148
	v_add_f32_e32 v153, -1.0, v149
	v_add_f32_e32 v224, 1.0, v149
	v_ldexp_f32 v148, v223, v148
	v_add_f32_e32 v223, 1.0, v153
	v_add_f32_e32 v225, -1.0, v224
	v_sub_f32_e32 v223, v149, v223
	v_sub_f32_e32 v149, v149, v225
	v_add_f32_e32 v223, v148, v223
	v_add_f32_e32 v148, v148, v149
	v_add_f32_e32 v231, v224, v148
	v_rcp_f32_e32 v233, v231
	v_sub_f32_e32 v149, v231, v224
	v_sub_f32_e32 v232, v148, v149
	v_add_f32_e32 v149, v153, v223
	v_sub_f32_e32 v148, v149, v153
	v_sub_f32_e32 v153, v223, v148
	v_mul_f32_e32 v223, v149, v233
	v_mul_f32_e32 v224, v231, v223
	v_fma_f32 v226, v223, v231, -v224
	v_fmac_f32_e32 v226, v223, v232
	v_add_f32_e32 v148, v224, v226
	v_sub_f32_e32 v225, v149, v148
	v_pk_add_f32 v[228:229], v[148:149], v[224:225] neg_lo:[0,1] neg_hi:[0,1]
	v_mov_b32_e32 v227, v148
	v_pk_add_f32 v[148:149], v[228:229], v[226:227] neg_lo:[0,1] neg_hi:[0,1]
	v_cmp_neq_f32_e32 vcc, s78, v136
	v_add_f32_e32 v149, v153, v149
	v_add_f32_e32 v148, v148, v149
	v_add_f32_e32 v149, v225, v148
	v_mul_f32_e32 v153, v233, v149
	v_mul_f32_e32 v224, v231, v153
	v_fma_f32 v226, v153, v231, -v224
; __device__ __forceinline__ unsigned cvt_pk_bf16(float lo, float hi) { const bf16x2_t r = __builtin_convertvector((f32x2){lo, hi}, bf16x2_t); return __builtin_bit_cast(unsigned, r); }
; __device__ __forceinline__ float bf_lo(unsigned w) { return __uint_as_float(w << 16); }
; __device__ __forceinline__ float bf_hi(unsigned w) { return __uint_as_float(w & 0xffff0000u); }
;     __device__ __forceinline__ void operator()(const AccT& acc, const Unit& u, int wr, int wc, int fr, int fq) const {
;     ...
;             for (int j = 0; j < 4; ++j) sp[j] = -8.0f * log1pf(__expf(-l[j]));
; #pragma unroll
;             for (int ai = 0; ai < 2; ++ai)
; #pragma unroll
;                 for (int m = 0; m < 4; ++m) { const size_t off = (size_t)(row0 + ai * HALF + m * 16) * DM + ch0 + 16 * n;
;                     const f32x4 rp = acc[ai][0][m][n] + bra, ip = acc[ai][1][m][n] + bri;
;                     const u32x2 w = xw[ai][m]; const float xv[4] = {bf_lo(w.x), bf_hi(w.x), bf_lo(w.y), bf_hi(w.y)};
;                     u32x4 o;
; #pragma unroll
;                     for (int j = 0; j < 4; ++j) { const float r = __builtin_amdgcn_rcpf(1.0f + __expf(-rp[j])), ig = __builtin_amdgcn_rcpf(1.0f + __expf(-ip[j])); const float la = sp[j] * r; const float d = 1.0f - __expf(la);
;                         o[j] = cvt_pk_bf16(d, __builtin_amdgcn_sqrtf(fmaxf(d * (2.0f - d), 0.f)) * (ig * xv[j])); }
	v_fmac_f32_e32 v226, v153, v232
	v_sub_f32_e32 v225, v225, v149
	v_add_f32_e32 v231, v148, v225
	v_add_f32_e32 v148, v224, v226
	v_sub_f32_e32 v225, v149, v148
	v_pk_add_f32 v[228:229], v[148:149], v[224:225] neg_lo:[0,1] neg_hi:[0,1]
	v_mov_b32_e32 v227, v148
	v_pk_add_f32 v[148:149], v[228:229], v[226:227] neg_lo:[0,1] neg_hi:[0,1]
	v_exp_f32_e32 v138, v138
	v_add_f32_e32 v149, v231, v149
	v_add_f32_e32 v148, v148, v149
	v_add_f32_e32 v149, v223, v153
	v_add_f32_e32 v148, v225, v148
	v_sub_f32_e32 v223, v149, v223
	v_mul_f32_e32 v148, v233, v148
	v_sub_f32_e32 v153, v153, v223
	v_add_f32_e32 v223, v153, v148
	v_add_f32_e32 v224, v149, v223
	v_mul_f32_e32 v226, v224, v224
	v_fmamk_f32 v148, v226, 0x3e9b6dac, v218
	v_fmaak_f32 v153, v226, v148, 0x3f2aaada
	v_cvt_f32_i32_e32 v148, v230
	v_sub_f32_e32 v149, v224, v149
	v_sub_f32_e32 v149, v223, v149
	v_ldexp_f32 v223, v149, 1
	v_mul_f32_e32 v149, v224, v226
	v_pk_mul_f32 v[226:227], v[148:149], v[152:153]
	v_ldexp_f32 v225, v224, 1
	v_fma_f32 v224, v148, s77, -v226
	v_fmac_f32_e32 v224, 0xb102e308, v148
	v_pk_add_f32 v[148:149], v[226:227], v[224:225]
	v_mov_b32_e32 v228, v226
	v_sub_f32_e32 v153, v149, v225
	v_sub_f32_e32 v153, v227, v153
	v_add_f32_e32 v229, v223, v153
	v_pk_add_f32 v[226:227], v[148:149], v[226:227] neg_lo:[0,1] neg_hi:[0,1]
	v_pk_add_f32 v[230:231], v[148:149], v[228:229]
	v_mov_b32_e32 v225, v148
	v_mov_b32_e32 v227, v231
	v_pk_add_f32 v[232:233], v[224:225], v[226:227] neg_lo:[0,1] neg_hi:[0,1]
	v_pk_add_f32 v[224:225], v[224:225], v[226:227]
	v_mov_b32_e32 v228, v229
	v_pk_add_f32 v[226:227], v[224:225], v[148:149] op_sel:[1,0] op_sel_hi:[0,1] neg_lo:[0,1] neg_hi:[0,1]
	v_pk_add_f32 v[234:235], v[230:231], v[226:227] op_sel_hi:[1,0] neg_lo:[0,1] neg_hi:[0,1]
	v_mov_b32_e32 v230, v231
	v_mov_b32_e32 v231, v225
	v_pk_mov_b32 v[226:227], v[148:149], v[226:227] op_sel:[1,0]
	v_mov_b32_e32 v229, v148
	v_pk_add_f32 v[226:227], v[230:231], v[226:227] neg_lo:[0,1] neg_hi:[0,1]
	v_mov_b32_e32 v234, v232
	v_pk_add_f32 v[148:149], v[228:229], v[226:227] neg_lo:[0,1] neg_hi:[0,1]
	v_mov_b32_e32 v233, v225
	v_pk_add_f32 v[226:227], v[234:235], v[148:149]
	v_mul_f32_e32 v139, 0xbfb8aa3b, v139
	v_pk_add_f32 v[228:229], v[226:227], v[226:227] op_sel:[0,1] op_sel_hi:[1,0]
	v_exp_f32_e32 v139, v139
	v_pk_add_f32 v[224:225], v[224:225], v[228:229] op_sel:[1,0] op_sel_hi:[0,1]
	v_mov_b32_e32 v227, v224
	v_pk_add_f32 v[230:231], v[226:227], v[232:233] neg_lo:[0,1] neg_hi:[0,1]
	v_mov_b32_e32 v149, v228
	v_sub_f32_e32 v153, v226, v230
	v_pk_add_f32 v[148:149], v[148:149], v[230:231] neg_lo:[0,1] neg_hi:[0,1]
	v_sub_f32_e32 v153, v232, v153
	v_add_f32_e32 v148, v148, v153
	v_add_f32_e32 v148, v148, v149
	v_add_f32_e32 v148, v224, v148
	v_cndmask_b32_e32 v148, v219, v148, vcc
	v_cmp_ngt_f32_e32 vcc, -1.0, v136
	v_add_f32_e32 v153, 1.0, v137
	v_add_f32_e32 v128, v128, v76
	v_cndmask_b32_e32 v148, v220, v148, vcc
	v_cmp_neq_f32_e32 vcc, -1.0, v136
	v_mul_f32_e32 v128, 0xbfb8aa3b, v128
	v_exp_f32_e32 v128, v128
	v_cndmask_b32_e32 v148, v221, v148, vcc
	v_cmp_lt_f32_e64 vcc, |v136|, s79
	v_add_f32_e32 v132, v132, v72
	v_add_f32_e32 v128, 1.0, v128
	v_cndmask_b32_e32 v136, v148, v136, vcc
	v_add_f32_e32 v148, -1.0, v153
	v_sub_f32_e32 v149, v148, v153
	v_add_f32_e32 v149, 1.0, v149
	v_sub_f32_e32 v148, v137, v148
	v_add_f32_e32 v223, v148, v149
	v_frexp_mant_f32_e32 v148, v153
	v_cmp_gt_f32_e32 vcc, s76, v148
	v_cvt_f64_f32_e32 v[148:149], v153
	v_frexp_exp_i32_f64_e32 v148, v[148:149]
	v_subbrev_co_u32_e32 v230, vcc, 0, v148, vcc
	v_sub_u32_e32 v148, 0, v230
	v_ldexp_f32 v149, v153, v148
	v_add_f32_e32 v153, -1.0, v149
	v_add_f32_e32 v224, 1.0, v149
	v_ldexp_f32 v148, v223, v148
	v_add_f32_e32 v223, 1.0, v153
	v_add_f32_e32 v225, -1.0, v224
	v_sub_f32_e32 v223, v149, v223
	v_sub_f32_e32 v149, v149, v225
	v_add_f32_e32 v223, v148, v223
	v_add_f32_e32 v148, v148, v149
	v_add_f32_e32 v231, v224, v148
	v_rcp_f32_e32 v233, v231
	v_sub_f32_e32 v149, v231, v224
	v_sub_f32_e32 v232, v148, v149
	v_add_f32_e32 v149, v153, v223
	v_sub_f32_e32 v148, v149, v153
	v_sub_f32_e32 v153, v223, v148
	v_mul_f32_e32 v223, v149, v233
	v_mul_f32_e32 v224, v231, v223
	v_fma_f32 v226, v223, v231, -v224
	v_fmac_f32_e32 v226, v223, v232
	v_add_f32_e32 v148, v224, v226
	v_sub_f32_e32 v225, v149, v148
	v_pk_add_f32 v[228:229], v[148:149], v[224:225] neg_lo:[0,1] neg_hi:[0,1]
	v_mov_b32_e32 v227, v148
	v_pk_add_f32 v[148:149], v[228:229], v[226:227] neg_lo:[0,1] neg_hi:[0,1]
	v_cmp_neq_f32_e32 vcc, s78, v137
	v_add_f32_e32 v149, v153, v149
	v_add_f32_e32 v148, v148, v149
	v_add_f32_e32 v149, v225, v148
	v_mul_f32_e32 v153, v233, v149
	v_mul_f32_e32 v224, v231, v153
	v_fma_f32 v226, v153, v231, -v224
	v_fmac_f32_e32 v226, v153, v232
	v_sub_f32_e32 v225, v225, v149
	v_add_f32_e32 v231, v148, v225
	v_add_f32_e32 v148, v224, v226
	v_sub_f32_e32 v225, v149, v148
	v_pk_add_f32 v[228:229], v[148:149], v[224:225] neg_lo:[0,1] neg_hi:[0,1]
	v_mov_b32_e32 v227, v148
	v_pk_add_f32 v[148:149], v[228:229], v[226:227] neg_lo:[0,1] neg_hi:[0,1]
	v_rcp_f32_e32 v128, v128
	v_add_f32_e32 v149, v231, v149
	v_add_f32_e32 v148, v148, v149
	v_add_f32_e32 v149, v223, v153
	v_add_f32_e32 v148, v225, v148
	v_sub_f32_e32 v223, v149, v223
	v_mul_f32_e32 v148, v233, v148
	v_sub_f32_e32 v153, v153, v223
	v_add_f32_e32 v223, v153, v148
	v_add_f32_e32 v224, v149, v223
	v_mul_f32_e32 v226, v224, v224
	v_fmamk_f32 v148, v226, 0x3e9b6dac, v218
	v_fmaak_f32 v153, v226, v148, 0x3f2aaada
	v_cvt_f32_i32_e32 v148, v230
	v_sub_f32_e32 v149, v224, v149
	v_sub_f32_e32 v149, v223, v149
	v_ldexp_f32 v223, v149, 1
	v_mul_f32_e32 v149, v224, v226
; __device__ __forceinline__ unsigned cvt_pk_bf16(float lo, float hi) { const bf16x2_t r = __builtin_convertvector((f32x2){lo, hi}, bf16x2_t); return __builtin_bit_cast(unsigned, r); }
; __device__ __forceinline__ float bf_lo(unsigned w) { return __uint_as_float(w << 16); }
; __device__ __forceinline__ float bf_hi(unsigned w) { return __uint_as_float(w & 0xffff0000u); }
;     __device__ __forceinline__ void operator()(const AccT& acc, const Unit& u, int wr, int wc, int fr, int fq) const {
;     ...
;             for (int j = 0; j < 4; ++j) sp[j] = -8.0f * log1pf(__expf(-l[j]));
; #pragma unroll
;             for (int ai = 0; ai < 2; ++ai)
; #pragma unroll
;                 for (int m = 0; m < 4; ++m) { const size_t off = (size_t)(row0 + ai * HALF + m * 16) * DM + ch0 + 16 * n;
;                     const f32x4 rp = acc[ai][0][m][n] + bra, ip = acc[ai][1][m][n] + bri;
;                     const u32x2 w = xw[ai][m]; const float xv[4] = {bf_lo(w.x), bf_hi(w.x), bf_lo(w.y), bf_hi(w.y)};
;                     u32x4 o;
; #pragma unroll
;                     for (int j = 0; j < 4; ++j) { const float r = __builtin_amdgcn_rcpf(1.0f + __expf(-rp[j])), ig = __builtin_amdgcn_rcpf(1.0f + __expf(-ip[j])); const float la = sp[j] * r; const float d = 1.0f - __expf(la);
;                         o[j] = cvt_pk_bf16(d, __builtin_amdgcn_sqrtf(fmaxf(d * (2.0f - d), 0.f)) * (ig * xv[j])); }
	v_pk_mul_f32 v[226:227], v[148:149], v[152:153]
	v_ldexp_f32 v225, v224, 1
	v_fma_f32 v224, v148, s77, -v226
	v_fmac_f32_e32 v224, 0xb102e308, v148
	v_pk_add_f32 v[148:149], v[226:227], v[224:225]
	v_mov_b32_e32 v228, v226
	v_sub_f32_e32 v153, v149, v225
	v_sub_f32_e32 v153, v227, v153
	v_add_f32_e32 v229, v223, v153
	v_pk_add_f32 v[226:227], v[148:149], v[226:227] neg_lo:[0,1] neg_hi:[0,1]
	v_pk_add_f32 v[230:231], v[148:149], v[228:229]
	v_mov_b32_e32 v225, v148
	v_mov_b32_e32 v227, v231
	v_pk_add_f32 v[232:233], v[224:225], v[226:227] neg_lo:[0,1] neg_hi:[0,1]
	v_pk_add_f32 v[224:225], v[224:225], v[226:227]
	v_mov_b32_e32 v228, v229
	v_pk_add_f32 v[226:227], v[224:225], v[148:149] op_sel:[1,0] op_sel_hi:[0,1] neg_lo:[0,1] neg_hi:[0,1]
	v_pk_add_f32 v[234:235], v[230:231], v[226:227] op_sel_hi:[1,0] neg_lo:[0,1] neg_hi:[0,1]
	v_mov_b32_e32 v230, v231
	v_mov_b32_e32 v231, v225
	v_pk_mov_b32 v[226:227], v[148:149], v[226:227] op_sel:[1,0]
	v_mov_b32_e32 v229, v148
	v_pk_add_f32 v[226:227], v[230:231], v[226:227] neg_lo:[0,1] neg_hi:[0,1]
	v_mov_b32_e32 v234, v232
	v_pk_add_f32 v[148:149], v[228:229], v[226:227] neg_lo:[0,1] neg_hi:[0,1]
	v_mov_b32_e32 v233, v225
	v_pk_add_f32 v[226:227], v[234:235], v[148:149]
	v_mul_f32_e32 v136, 0xc1000000, v136
	v_pk_add_f32 v[228:229], v[226:227], v[226:227] op_sel:[0,1] op_sel_hi:[1,0]
	v_mul_f32_e32 v128, v128, v136
	v_pk_add_f32 v[224:225], v[224:225], v[228:229] op_sel:[1,0] op_sel_hi:[0,1]
	v_mov_b32_e32 v227, v224
	v_pk_add_f32 v[230:231], v[226:227], v[232:233] neg_lo:[0,1] neg_hi:[0,1]
	v_mov_b32_e32 v149, v228
	v_sub_f32_e32 v153, v226, v230
	v_pk_add_f32 v[148:149], v[148:149], v[230:231] neg_lo:[0,1] neg_hi:[0,1]
	v_sub_f32_e32 v153, v232, v153
	v_add_f32_e32 v148, v148, v153
	v_add_f32_e32 v148, v148, v149
	v_add_f32_e32 v148, v224, v148
	v_cndmask_b32_e32 v148, v219, v148, vcc
	v_cmp_ngt_f32_e32 vcc, -1.0, v137
	v_add_f32_e32 v153, 1.0, v138
	v_mul_f32_e32 v128, 0x3fb8aa3b, v128
	v_cndmask_b32_e32 v148, v220, v148, vcc
	v_cmp_neq_f32_e32 vcc, -1.0, v137
	v_exp_f32_e32 v128, v128
	v_mul_f32_e32 v132, 0xbfb8aa3b, v132
	v_cndmask_b32_e32 v148, v221, v148, vcc
	v_cmp_lt_f32_e64 vcc, |v137|, s79
	v_exp_f32_e32 v132, v132
	v_sub_f32_e32 v128, 1.0, v128
	v_cndmask_b32_e32 v137, v148, v137, vcc
	v_add_f32_e32 v148, -1.0, v153
	v_sub_f32_e32 v149, v148, v153
	v_add_f32_e32 v149, 1.0, v149
	v_sub_f32_e32 v148, v138, v148
	v_add_f32_e32 v223, v148, v149
	v_frexp_mant_f32_e32 v148, v153
	v_cmp_gt_f32_e32 vcc, s76, v148
	v_cvt_f64_f32_e32 v[148:149], v153
	v_frexp_exp_i32_f64_e32 v148, v[148:149]
	v_subbrev_co_u32_e32 v230, vcc, 0, v148, vcc
	v_sub_u32_e32 v148, 0, v230
	v_ldexp_f32 v149, v153, v148
	v_add_f32_e32 v153, -1.0, v149
	v_add_f32_e32 v224, 1.0, v149
	v_ldexp_f32 v148, v223, v148
	v_add_f32_e32 v223, 1.0, v153
	v_add_f32_e32 v225, -1.0, v224
	v_sub_f32_e32 v223, v149, v223
	v_sub_f32_e32 v149, v149, v225
	v_add_f32_e32 v223, v148, v223
	v_add_f32_e32 v148, v148, v149
	v_add_f32_e32 v231, v224, v148
	v_rcp_f32_e32 v233, v231
	v_sub_f32_e32 v149, v231, v224
	v_sub_f32_e32 v232, v148, v149
	v_add_f32_e32 v149, v153, v223
	v_sub_f32_e32 v148, v149, v153
	v_sub_f32_e32 v153, v223, v148
	v_mul_f32_e32 v223, v149, v233
	v_mul_f32_e32 v224, v231, v223
	v_fma_f32 v226, v223, v231, -v224
	v_fmac_f32_e32 v226, v223, v232
	v_add_f32_e32 v148, v224, v226
	v_sub_f32_e32 v225, v149, v148
	v_pk_add_f32 v[228:229], v[148:149], v[224:225] neg_lo:[0,1] neg_hi:[0,1]
	v_mov_b32_e32 v227, v148
	v_pk_add_f32 v[148:149], v[228:229], v[226:227] neg_lo:[0,1] neg_hi:[0,1]
	v_cmp_neq_f32_e32 vcc, s78, v138
	v_add_f32_e32 v149, v153, v149
	v_add_f32_e32 v148, v148, v149
	v_add_f32_e32 v149, v225, v148
	v_mul_f32_e32 v153, v233, v149
	v_mul_f32_e32 v224, v231, v153
	v_fma_f32 v226, v153, v231, -v224
	v_fmac_f32_e32 v226, v153, v232
	v_sub_f32_e32 v225, v225, v149
	v_add_f32_e32 v231, v148, v225
	v_add_f32_e32 v148, v224, v226
	v_sub_f32_e32 v225, v149, v148
	v_pk_add_f32 v[228:229], v[148:149], v[224:225] neg_lo:[0,1] neg_hi:[0,1]
	v_mov_b32_e32 v227, v148
	v_pk_add_f32 v[148:149], v[228:229], v[226:227] neg_lo:[0,1] neg_hi:[0,1]
	v_add_f32_e32 v132, 1.0, v132
	v_add_f32_e32 v149, v231, v149
	v_add_f32_e32 v148, v148, v149
	v_add_f32_e32 v149, v223, v153
	v_add_f32_e32 v148, v225, v148
	v_sub_f32_e32 v223, v149, v223
	v_mul_f32_e32 v148, v233, v148
	v_sub_f32_e32 v153, v153, v223
	v_add_f32_e32 v223, v153, v148
	v_add_f32_e32 v224, v149, v223
	v_mul_f32_e32 v226, v224, v224
	v_fmamk_f32 v148, v226, 0x3e9b6dac, v218
	v_fmaak_f32 v153, v226, v148, 0x3f2aaada
	v_cvt_f32_i32_e32 v148, v230
	v_sub_f32_e32 v149, v224, v149
	v_sub_f32_e32 v149, v223, v149
	v_ldexp_f32 v223, v149, 1
	v_mul_f32_e32 v149, v224, v226
	v_pk_mul_f32 v[226:227], v[148:149], v[152:153]
	v_ldexp_f32 v225, v224, 1
	v_fma_f32 v224, v148, s77, -v226
	v_fmac_f32_e32 v224, 0xb102e308, v148
	v_pk_add_f32 v[148:149], v[226:227], v[224:225]
	v_mov_b32_e32 v228, v226
	v_sub_f32_e32 v153, v149, v225
	v_sub_f32_e32 v153, v227, v153
	v_add_f32_e32 v229, v223, v153
	v_pk_add_f32 v[226:227], v[148:149], v[226:227] neg_lo:[0,1] neg_hi:[0,1]
	v_pk_add_f32 v[230:231], v[148:149], v[228:229]
	v_mov_b32_e32 v225, v148
	v_mov_b32_e32 v227, v231
	v_pk_add_f32 v[232:233], v[224:225], v[226:227] neg_lo:[0,1] neg_hi:[0,1]
	v_pk_add_f32 v[224:225], v[224:225], v[226:227]
	v_mov_b32_e32 v228, v229
	v_pk_add_f32 v[226:227], v[224:225], v[148:149] op_sel:[1,0] op_sel_hi:[0,1] neg_lo:[0,1] neg_hi:[0,1]
	v_pk_add_f32 v[234:235], v[230:231], v[226:227] op_sel_hi:[1,0] neg_lo:[0,1] neg_hi:[0,1]
	v_mov_b32_e32 v230, v231
	v_mov_b32_e32 v231, v225
	v_pk_mov_b32 v[226:227], v[148:149], v[226:227] op_sel:[1,0]
; __device__ __forceinline__ unsigned cvt_pk_bf16(float lo, float hi) { const bf16x2_t r = __builtin_convertvector((f32x2){lo, hi}, bf16x2_t); return __builtin_bit_cast(unsigned, r); }
; __device__ __forceinline__ float bf_lo(unsigned w) { return __uint_as_float(w << 16); }
; __device__ __forceinline__ float bf_hi(unsigned w) { return __uint_as_float(w & 0xffff0000u); }
;     __device__ __forceinline__ void operator()(const AccT& acc, const Unit& u, int wr, int wc, int fr, int fq) const {
;     ...
;             for (int j = 0; j < 4; ++j) sp[j] = -8.0f * log1pf(__expf(-l[j]));
; #pragma unroll
;             for (int ai = 0; ai < 2; ++ai)
; #pragma unroll
;                 for (int m = 0; m < 4; ++m) { const size_t off = (size_t)(row0 + ai * HALF + m * 16) * DM + ch0 + 16 * n;
;                     const f32x4 rp = acc[ai][0][m][n] + bra, ip = acc[ai][1][m][n] + bri;
;                     const u32x2 w = xw[ai][m]; const float xv[4] = {bf_lo(w.x), bf_hi(w.x), bf_lo(w.y), bf_hi(w.y)};
;                     u32x4 o;
; #pragma unroll
;                     for (int j = 0; j < 4; ++j) { const float r = __builtin_amdgcn_rcpf(1.0f + __expf(-rp[j])), ig = __builtin_amdgcn_rcpf(1.0f + __expf(-ip[j])); const float la = sp[j] * r; const float d = 1.0f - __expf(la);
;                         o[j] = cvt_pk_bf16(d, __builtin_amdgcn_sqrtf(fmaxf(d * (2.0f - d), 0.f)) * (ig * xv[j])); }
	v_mov_b32_e32 v229, v148
	v_pk_add_f32 v[226:227], v[230:231], v[226:227] neg_lo:[0,1] neg_hi:[0,1]
	v_mov_b32_e32 v234, v232
	v_pk_add_f32 v[148:149], v[228:229], v[226:227] neg_lo:[0,1] neg_hi:[0,1]
	v_mov_b32_e32 v233, v225
	v_pk_add_f32 v[226:227], v[234:235], v[148:149]
	v_rcp_f32_e32 v132, v132
	v_pk_add_f32 v[228:229], v[226:227], v[226:227] op_sel:[0,1] op_sel_hi:[1,0]
	v_mul_f32_e32 v137, 0xc1000000, v137
	v_pk_add_f32 v[224:225], v[224:225], v[228:229] op_sel:[1,0] op_sel_hi:[0,1]
	v_mov_b32_e32 v227, v224
	v_pk_add_f32 v[230:231], v[226:227], v[232:233] neg_lo:[0,1] neg_hi:[0,1]
	v_mov_b32_e32 v149, v228
	v_sub_f32_e32 v153, v226, v230
	v_pk_add_f32 v[148:149], v[148:149], v[230:231] neg_lo:[0,1] neg_hi:[0,1]
	v_sub_f32_e32 v153, v232, v153
	v_add_f32_e32 v148, v148, v153
	v_add_f32_e32 v148, v148, v149
	v_add_f32_e32 v148, v224, v148
	v_cndmask_b32_e32 v148, v219, v148, vcc
	v_cmp_ngt_f32_e32 vcc, -1.0, v138
	v_add_f32_e32 v153, 1.0, v139
	v_add_f32_e32 v120, v120, v76
	v_cndmask_b32_e32 v148, v220, v148, vcc
	v_cmp_neq_f32_e32 vcc, -1.0, v138
	v_mul_f32_e32 v120, 0xbfb8aa3b, v120
	v_exp_f32_e32 v120, v120
	v_cndmask_b32_e32 v148, v221, v148, vcc
	v_cmp_lt_f32_e64 vcc, |v138|, s79
	v_add_f32_e32 v124, v124, v72
	v_add_f32_e32 v120, 1.0, v120
	v_cndmask_b32_e32 v138, v148, v138, vcc
	v_add_f32_e32 v148, -1.0, v153
	v_sub_f32_e32 v149, v148, v153
	v_add_f32_e32 v149, 1.0, v149
	v_sub_f32_e32 v148, v139, v148
	v_add_f32_e32 v223, v148, v149
	v_frexp_mant_f32_e32 v148, v153
	v_cmp_gt_f32_e32 vcc, s76, v148
	v_cvt_f64_f32_e32 v[148:149], v153
	v_frexp_exp_i32_f64_e32 v148, v[148:149]
	v_subbrev_co_u32_e32 v230, vcc, 0, v148, vcc
	v_sub_u32_e32 v148, 0, v230
	v_ldexp_f32 v149, v153, v148
	v_add_f32_e32 v153, -1.0, v149
	v_add_f32_e32 v224, 1.0, v149
	v_ldexp_f32 v148, v223, v148
	v_add_f32_e32 v223, 1.0, v153
	v_add_f32_e32 v225, -1.0, v224
	v_sub_f32_e32 v223, v149, v223
	v_sub_f32_e32 v149, v149, v225
	v_add_f32_e32 v223, v148, v223
	v_add_f32_e32 v148, v148, v149
	v_add_f32_e32 v231, v224, v148
	v_rcp_f32_e32 v233, v231
	v_sub_f32_e32 v149, v231, v224
	v_sub_f32_e32 v232, v148, v149
	v_add_f32_e32 v149, v153, v223
	v_sub_f32_e32 v148, v149, v153
	v_sub_f32_e32 v153, v223, v148
	v_mul_f32_e32 v223, v149, v233
	v_mul_f32_e32 v224, v231, v223
	v_fma_f32 v226, v223, v231, -v224
	v_fmac_f32_e32 v226, v223, v232
	v_add_f32_e32 v148, v224, v226
	v_sub_f32_e32 v225, v149, v148
	v_pk_add_f32 v[228:229], v[148:149], v[224:225] neg_lo:[0,1] neg_hi:[0,1]
	v_mov_b32_e32 v227, v148
	v_pk_add_f32 v[148:149], v[228:229], v[226:227] neg_lo:[0,1] neg_hi:[0,1]
	v_cmp_neq_f32_e32 vcc, s78, v139
	v_add_f32_e32 v149, v153, v149
	v_add_f32_e32 v148, v148, v149
	v_add_f32_e32 v149, v225, v148
	v_mul_f32_e32 v153, v233, v149
	v_mul_f32_e32 v224, v231, v153
	v_fma_f32 v226, v153, v231, -v224
	v_fmac_f32_e32 v226, v153, v232
	v_sub_f32_e32 v225, v225, v149
	v_add_f32_e32 v231, v148, v225
	v_add_f32_e32 v148, v224, v226
	v_sub_f32_e32 v225, v149, v148
	v_pk_add_f32 v[228:229], v[148:149], v[224:225] neg_lo:[0,1] neg_hi:[0,1]
	v_mov_b32_e32 v227, v148
	v_pk_add_f32 v[148:149], v[228:229], v[226:227] neg_lo:[0,1] neg_hi:[0,1]
	v_mul_f32_e32 v138, 0xc1000000, v138
	v_add_f32_e32 v149, v231, v149
	v_add_f32_e32 v148, v148, v149
	v_add_f32_e32 v149, v223, v153
	v_add_f32_e32 v148, v225, v148
	v_sub_f32_e32 v223, v149, v223
	v_mul_f32_e32 v148, v233, v148
	v_sub_f32_e32 v153, v153, v223
	v_add_f32_e32 v223, v153, v148
	v_add_f32_e32 v224, v149, v223
	v_mul_f32_e32 v226, v224, v224
	v_fmamk_f32 v148, v226, 0x3e9b6dac, v218
	v_fmaak_f32 v153, v226, v148, 0x3f2aaada
	v_cvt_f32_i32_e32 v148, v230
	v_sub_f32_e32 v149, v224, v149
	v_sub_f32_e32 v149, v223, v149
	v_ldexp_f32 v223, v149, 1
	v_mul_f32_e32 v149, v224, v226
	v_pk_mul_f32 v[226:227], v[148:149], v[152:153]
	v_ldexp_f32 v225, v224, 1
	v_fma_f32 v224, v148, s77, -v226
	v_fmac_f32_e32 v224, 0xb102e308, v148
	v_pk_add_f32 v[148:149], v[226:227], v[224:225]
	v_mov_b32_e32 v228, v226
	v_sub_f32_e32 v153, v149, v225
	v_sub_f32_e32 v153, v227, v153
	v_add_f32_e32 v229, v223, v153
	v_pk_add_f32 v[226:227], v[148:149], v[226:227] neg_lo:[0,1] neg_hi:[0,1]
	v_pk_add_f32 v[230:231], v[148:149], v[228:229]
	v_mov_b32_e32 v225, v148
	v_mov_b32_e32 v227, v231
	v_pk_add_f32 v[232:233], v[224:225], v[226:227] neg_lo:[0,1] neg_hi:[0,1]
	v_pk_add_f32 v[224:225], v[224:225], v[226:227]
	v_mov_b32_e32 v228, v229
	v_pk_add_f32 v[226:227], v[224:225], v[148:149] op_sel:[1,0] op_sel_hi:[0,1] neg_lo:[0,1] neg_hi:[0,1]
	v_pk_add_f32 v[234:235], v[230:231], v[226:227] op_sel_hi:[1,0] neg_lo:[0,1] neg_hi:[0,1]
	v_mov_b32_e32 v230, v231
	v_mov_b32_e32 v231, v225
	v_pk_mov_b32 v[226:227], v[148:149], v[226:227] op_sel:[1,0]
	v_mov_b32_e32 v229, v148
	v_pk_add_f32 v[226:227], v[230:231], v[226:227] neg_lo:[0,1] neg_hi:[0,1]
	v_mov_b32_e32 v234, v232
	v_pk_add_f32 v[148:149], v[228:229], v[226:227] neg_lo:[0,1] neg_hi:[0,1]
	v_mov_b32_e32 v233, v225
	v_pk_add_f32 v[226:227], v[234:235], v[148:149]
	v_rcp_f32_e32 v120, v120
	v_pk_add_f32 v[228:229], v[226:227], v[226:227] op_sel:[0,1] op_sel_hi:[1,0]
	v_mul_f32_e32 v124, 0xbfb8aa3b, v124
	v_pk_add_f32 v[224:225], v[224:225], v[228:229] op_sel:[1,0] op_sel_hi:[0,1]
	v_mov_b32_e32 v227, v224
	v_pk_add_f32 v[230:231], v[226:227], v[232:233] neg_lo:[0,1] neg_hi:[0,1]
	v_mov_b32_e32 v149, v228
	v_sub_f32_e32 v153, v226, v230
	v_pk_add_f32 v[148:149], v[148:149], v[230:231] neg_lo:[0,1] neg_hi:[0,1]
	v_sub_f32_e32 v153, v232, v153
	v_add_f32_e32 v148, v148, v153
	v_add_f32_e32 v148, v148, v149
	v_add_f32_e32 v148, v224, v148
	v_cndmask_b32_e32 v148, v219, v148, vcc
	v_cmp_ngt_f32_e32 vcc, -1.0, v139
; __device__ __forceinline__ unsigned cvt_pk_bf16(float lo, float hi) { const bf16x2_t r = __builtin_convertvector((f32x2){lo, hi}, bf16x2_t); return __builtin_bit_cast(unsigned, r); }
; __device__ __forceinline__ float bf_lo(unsigned w) { return __uint_as_float(w << 16); }
; __device__ __forceinline__ float bf_hi(unsigned w) { return __uint_as_float(w & 0xffff0000u); }
;     __device__ __forceinline__ void operator()(const AccT& acc, const Unit& u, int wr, int wc, int fr, int fq) const {
;     ...
;                 for (int m = 0; m < 4; ++m) { const size_t off = (size_t)(row0 + ai * HALF + m * 16) * DM + ch0 + 16 * n;
;                     const f32x4 rp = acc[ai][0][m][n] + bra, ip = acc[ai][1][m][n] + bri;
;                     const u32x2 w = xw[ai][m]; const float xv[4] = {bf_lo(w.x), bf_hi(w.x), bf_lo(w.y), bf_hi(w.y)};
;                     u32x4 o;
; #pragma unroll
;                     for (int j = 0; j < 4; ++j) { const float r = __builtin_amdgcn_rcpf(1.0f + __expf(-rp[j])), ig = __builtin_amdgcn_rcpf(1.0f + __expf(-ip[j])); const float la = sp[j] * r; const float d = 1.0f - __expf(la);
;                         o[j] = cvt_pk_bf16(d, __builtin_amdgcn_sqrtf(fmaxf(d * (2.0f - d), 0.f)) * (ig * xv[j])); }
;                     *(u32x4*)(AU + off) = o; }
	v_and_b32_e32 v149, 0xffff0000, v210
	v_lshlrev_b32_e32 v153, 16, v211
	v_cndmask_b32_e32 v148, v220, v148, vcc
	v_cmp_neq_f32_e32 vcc, -1.0, v139
	v_mul_f32_e32 v120, v120, v136
	v_mul_f32_e32 v120, 0x3fb8aa3b, v120
	v_cndmask_b32_e32 v148, v221, v148, vcc
	v_cmp_lt_f32_e64 vcc, |v139|, s79
	v_exp_f32_e32 v120, v120
	v_exp_f32_e32 v124, v124
	v_cndmask_b32_e32 v139, v148, v139, vcc
	v_lshlrev_b32_e32 v148, 16, v210
	v_and_b32_e32 v210, 0xffff0000, v211
	v_sub_f32_e32 v211, 2.0, v128
	v_mul_f32_e32 v211, v128, v211
	v_max_f32_e32 v211, 0, v211
	v_sqrt_f32_e32 v211, v211
	v_mul_f32_e32 v132, v132, v148
	v_mul_f32_e32 v139, 0xc1000000, v139
	v_sub_f32_e32 v120, 1.0, v120
	v_mul_f32_e32 v132, v132, v211
	v_cvt_pk_bf16_f32 v132, v128, v132
	v_add_f32_e32 v128, v129, v77
	v_mul_f32_e32 v128, 0xbfb8aa3b, v128
	v_exp_f32_e32 v128, v128
	v_add_f32_e32 v129, v133, v73
	v_mul_f32_e32 v129, 0xbfb8aa3b, v129
	v_exp_f32_e32 v129, v129
	v_add_f32_e32 v128, 1.0, v128
	v_rcp_f32_e32 v128, v128
	v_add_f32_e32 v124, 1.0, v124
	v_add_f32_e32 v129, 1.0, v129
	v_rcp_f32_e32 v129, v129
	v_mul_f32_e32 v128, v128, v137
	v_mul_f32_e32 v128, 0x3fb8aa3b, v128
	v_exp_f32_e32 v128, v128
	v_mul_f32_e32 v129, v129, v149
	v_rcp_f32_e32 v124, v124
	v_add_f32_e32 v112, v112, v76
	v_sub_f32_e32 v128, 1.0, v128
	v_sub_f32_e32 v133, 2.0, v128
	v_mul_f32_e32 v133, v128, v133
	v_max_f32_e32 v133, 0, v133
	v_sqrt_f32_e32 v133, v133
	v_mul_f32_e32 v112, 0xbfb8aa3b, v112
	v_exp_f32_e32 v112, v112
	v_add_f32_e32 v116, v116, v72
	v_mul_f32_e32 v129, v129, v133
	v_cvt_pk_bf16_f32 v133, v128, v129
	v_add_f32_e32 v128, v130, v78
	v_mul_f32_e32 v128, 0xbfb8aa3b, v128
	v_exp_f32_e32 v128, v128
	v_add_f32_e32 v129, v134, v74
	v_mul_f32_e32 v129, 0xbfb8aa3b, v129
	v_exp_f32_e32 v129, v129
	v_add_f32_e32 v128, 1.0, v128
	v_rcp_f32_e32 v128, v128
	v_add_f32_e32 v112, 1.0, v112
	v_add_f32_e32 v129, 1.0, v129
	v_rcp_f32_e32 v129, v129
	v_mul_f32_e32 v128, v128, v138
	v_mul_f32_e32 v128, 0x3fb8aa3b, v128
	v_exp_f32_e32 v128, v128
	v_mul_f32_e32 v129, v129, v153
	v_rcp_f32_e32 v112, v112
	v_mul_f32_e32 v116, 0xbfb8aa3b, v116
	v_sub_f32_e32 v128, 1.0, v128
	v_sub_f32_e32 v130, 2.0, v128
	v_mul_f32_e32 v130, v128, v130
	v_max_f32_e32 v130, 0, v130
	v_sqrt_f32_e32 v130, v130
	v_mul_f32_e32 v112, v112, v136
	v_mul_f32_e32 v112, 0x3fb8aa3b, v112
	v_exp_f32_e32 v112, v112
	v_mul_f32_e32 v129, v129, v130
	v_cvt_pk_bf16_f32 v134, v128, v129
	v_add_f32_e32 v128, v131, v79
	v_mul_f32_e32 v128, 0xbfb8aa3b, v128
	v_exp_f32_e32 v128, v128
	v_add_f32_e32 v129, v135, v75
	v_mul_f32_e32 v129, 0xbfb8aa3b, v129
	v_exp_f32_e32 v129, v129
	v_add_f32_e32 v128, 1.0, v128
	v_rcp_f32_e32 v128, v128
	v_and_b32_e32 v131, 0xffff0000, v208
	v_add_f32_e32 v129, 1.0, v129
	v_rcp_f32_e32 v129, v129
	v_mul_f32_e32 v128, v128, v139
	v_mul_f32_e32 v128, 0x3fb8aa3b, v128
	v_exp_f32_e32 v128, v128
	v_mul_f32_e32 v129, v129, v210
	v_exp_f32_e32 v116, v116
	v_sub_f32_e32 v112, 1.0, v112
	v_sub_f32_e32 v128, 1.0, v128
	v_sub_f32_e32 v130, 2.0, v128
	v_mul_f32_e32 v130, v128, v130
	v_max_f32_e32 v130, 0, v130
	v_sqrt_f32_e32 v130, v130
	v_add_f32_e32 v116, 1.0, v116
	v_rcp_f32_e32 v116, v116
	v_add_f32_e32 v104, v104, v76
	v_mul_f32_e32 v129, v129, v130
	v_cvt_pk_bf16_f32 v135, v128, v129
	v_lshlrev_b64 v[128:129], 13, v[206:207]
	v_lshl_add_u64 v[128:129], s[42:43], 0, v[128:129]
	v_lshl_add_u64 v[128:129], v[128:129], 0, v[174:175]
	global_store_dwordx4 v[128:129], v[132:135], off
	v_lshlrev_b32_e32 v130, 16, v208
	v_mul_f32_e32 v124, v124, v130
	v_sub_f32_e32 v134, 2.0, v120
	v_mul_f32_e32 v134, v120, v134
	v_max_f32_e32 v134, 0, v134
	v_sqrt_f32_e32 v134, v134
	v_lshlrev_b32_e32 v132, 16, v209
	v_and_b32_e32 v133, 0xffff0000, v209
	v_mul_f32_e32 v104, 0xbfb8aa3b, v104
	v_mul_f32_e32 v124, v124, v134
	v_cvt_pk_bf16_f32 v124, v120, v124
	v_add_f32_e32 v120, v121, v77
	v_mul_f32_e32 v120, 0xbfb8aa3b, v120
	v_exp_f32_e32 v120, v120
	v_add_f32_e32 v121, v125, v73
	v_mul_f32_e32 v121, 0xbfb8aa3b, v121
	v_exp_f32_e32 v121, v121
	v_add_f32_e32 v120, 1.0, v120
	v_rcp_f32_e32 v120, v120
	v_exp_f32_e32 v104, v104
	v_add_f32_e32 v121, 1.0, v121
	v_rcp_f32_e32 v121, v121
	v_mul_f32_e32 v120, v120, v137
	v_mul_f32_e32 v120, 0x3fb8aa3b, v120
	v_exp_f32_e32 v120, v120
	v_mul_f32_e32 v121, v121, v131
	v_add_f32_e32 v104, 1.0, v104
	v_rcp_f32_e32 v104, v104
	v_sub_f32_e32 v120, 1.0, v120
	v_sub_f32_e32 v125, 2.0, v120
	v_mul_f32_e32 v125, v120, v125
	v_max_f32_e32 v125, 0, v125
	v_sqrt_f32_e32 v125, v125
	v_mul_f32_e32 v104, v104, v136
	v_mul_f32_e32 v104, 0x3fb8aa3b, v104
	v_add_f32_e32 v108, v108, v72
	v_mul_f32_e32 v121, v121, v125
	v_cvt_pk_bf16_f32 v125, v120, v121
	v_add_f32_e32 v120, v122, v78
	v_mul_f32_e32 v120, 0xbfb8aa3b, v120
	v_exp_f32_e32 v120, v120
	v_add_f32_e32 v121, v126, v74
	v_mul_f32_e32 v121, 0xbfb8aa3b, v121
	v_exp_f32_e32 v121, v121
	v_add_f32_e32 v120, 1.0, v120
	v_rcp_f32_e32 v120, v120
	v_exp_f32_e32 v104, v104
	v_add_f32_e32 v121, 1.0, v121
	v_rcp_f32_e32 v121, v121
	v_mul_f32_e32 v120, v120, v138
	v_mul_f32_e32 v120, 0x3fb8aa3b, v120
	v_exp_f32_e32 v120, v120
	v_mul_f32_e32 v121, v121, v132
	v_mul_f32_e32 v108, 0xbfb8aa3b, v108
	v_exp_f32_e32 v108, v108
	v_sub_f32_e32 v120, 1.0, v120
	v_sub_f32_e32 v122, 2.0, v120
	v_mul_f32_e32 v122, v120, v122
	v_max_f32_e32 v122, 0, v122
	v_sqrt_f32_e32 v122, v122
	v_sub_f32_e32 v104, 1.0, v104
	v_add_f32_e32 v108, 1.0, v108
	v_rcp_f32_e32 v108, v108
	v_mul_f32_e32 v121, v121, v122
	v_cvt_pk_bf16_f32 v126, v120, v121
	v_add_f32_e32 v120, v123, v79
	v_mul_f32_e32 v120, 0xbfb8aa3b, v120
	v_exp_f32_e32 v120, v120
	v_add_f32_e32 v121, v127, v75
	v_mul_f32_e32 v121, 0xbfb8aa3b, v121
; __device__ __forceinline__ unsigned cvt_pk_bf16(float lo, float hi) { const bf16x2_t r = __builtin_convertvector((f32x2){lo, hi}, bf16x2_t); return __builtin_bit_cast(unsigned, r); }
; __device__ __forceinline__ float bf_lo(unsigned w) { return __uint_as_float(w << 16); }
; __device__ __forceinline__ float bf_hi(unsigned w) { return __uint_as_float(w & 0xffff0000u); }
;     __device__ __forceinline__ void operator()(const AccT& acc, const Unit& u, int wr, int wc, int fr, int fq) const {
;     ...
;                 for (int m = 0; m < 4; ++m) { const size_t off = (size_t)(row0 + ai * HALF + m * 16) * DM + ch0 + 16 * n;
;                     const f32x4 rp = acc[ai][0][m][n] + bra, ip = acc[ai][1][m][n] + bri;
;                     const u32x2 w = xw[ai][m]; const float xv[4] = {bf_lo(w.x), bf_hi(w.x), bf_lo(w.y), bf_hi(w.y)};
;                     u32x4 o;
; #pragma unroll
;                     for (int j = 0; j < 4; ++j) { const float r = __builtin_amdgcn_rcpf(1.0f + __expf(-rp[j])), ig = __builtin_amdgcn_rcpf(1.0f + __expf(-ip[j])); const float la = sp[j] * r; const float d = 1.0f - __expf(la);
;                         o[j] = cvt_pk_bf16(d, __builtin_amdgcn_sqrtf(fmaxf(d * (2.0f - d), 0.f)) * (ig * xv[j])); }
;                     *(u32x4*)(AU + off) = o; }
	v_exp_f32_e32 v121, v121
	v_add_f32_e32 v120, 1.0, v120
	v_rcp_f32_e32 v120, v120
	v_and_b32_e32 v123, 0xffff0000, v204
	v_add_f32_e32 v121, 1.0, v121
	v_rcp_f32_e32 v121, v121
	v_mul_f32_e32 v120, v120, v139
	v_mul_f32_e32 v120, 0x3fb8aa3b, v120
	v_exp_f32_e32 v120, v120
	v_mul_f32_e32 v121, v121, v133
	v_add_f32_e32 v96, v96, v76
	v_mul_f32_e32 v96, 0xbfb8aa3b, v96
	v_sub_f32_e32 v120, 1.0, v120
	v_sub_f32_e32 v122, 2.0, v120
	v_mul_f32_e32 v122, v120, v122
	v_max_f32_e32 v122, 0, v122
	v_sqrt_f32_e32 v122, v122
	v_exp_f32_e32 v96, v96
	v_add_f32_e32 v100, v100, v72
	v_mul_f32_e32 v100, 0xbfb8aa3b, v100
	v_mul_f32_e32 v121, v121, v122
	v_cvt_pk_bf16_f32 v127, v120, v121
	v_lshlrev_b64 v[120:121], 13, v[202:203]
	v_lshl_add_u64 v[120:121], s[42:43], 0, v[120:121]
	v_lshl_add_u64 v[120:121], v[120:121], 0, v[174:175]
	global_store_dwordx4 v[120:121], v[124:127], off
	v_lshlrev_b32_e32 v122, 16, v204
	v_mul_f32_e32 v116, v116, v122
	v_sub_f32_e32 v126, 2.0, v112
	v_mul_f32_e32 v126, v112, v126
	v_max_f32_e32 v126, 0, v126
	v_sqrt_f32_e32 v126, v126
	v_lshlrev_b32_e32 v124, 16, v205
	v_and_b32_e32 v125, 0xffff0000, v205
	v_add_f32_e32 v96, 1.0, v96
	v_mul_f32_e32 v116, v116, v126
	v_cvt_pk_bf16_f32 v116, v112, v116
	v_add_f32_e32 v112, v113, v77
	v_mul_f32_e32 v112, 0xbfb8aa3b, v112
	v_exp_f32_e32 v112, v112
	v_add_f32_e32 v113, v117, v73
	v_mul_f32_e32 v113, 0xbfb8aa3b, v113
	v_exp_f32_e32 v113, v113
	v_add_f32_e32 v112, 1.0, v112
	v_rcp_f32_e32 v112, v112
	v_rcp_f32_e32 v96, v96
	v_add_f32_e32 v113, 1.0, v113
	v_rcp_f32_e32 v113, v113
	v_mul_f32_e32 v112, v112, v137
	v_mul_f32_e32 v112, 0x3fb8aa3b, v112
	v_exp_f32_e32 v112, v112
	v_mul_f32_e32 v113, v113, v123
	v_mul_f32_e32 v96, v96, v136
	v_mul_f32_e32 v96, 0x3fb8aa3b, v96
	v_sub_f32_e32 v112, 1.0, v112
	v_sub_f32_e32 v117, 2.0, v112
	v_mul_f32_e32 v117, v112, v117
	v_max_f32_e32 v117, 0, v117
	v_sqrt_f32_e32 v117, v117
	v_exp_f32_e32 v96, v96
	v_exp_f32_e32 v100, v100
	v_add_f32_e32 v88, v88, v76
	v_mul_f32_e32 v113, v113, v117
	v_cvt_pk_bf16_f32 v117, v112, v113
	v_add_f32_e32 v112, v114, v78
	v_mul_f32_e32 v112, 0xbfb8aa3b, v112
	v_exp_f32_e32 v112, v112
	v_add_f32_e32 v113, v118, v74
	v_mul_f32_e32 v113, 0xbfb8aa3b, v113
	v_exp_f32_e32 v113, v113
	v_add_f32_e32 v112, 1.0, v112
	v_rcp_f32_e32 v112, v112
	v_sub_f32_e32 v96, 1.0, v96
	v_add_f32_e32 v113, 1.0, v113
	v_rcp_f32_e32 v113, v113
	v_mul_f32_e32 v112, v112, v138
	v_mul_f32_e32 v112, 0x3fb8aa3b, v112
	v_exp_f32_e32 v112, v112
	v_mul_f32_e32 v113, v113, v124
	v_add_f32_e32 v100, 1.0, v100
	v_rcp_f32_e32 v100, v100
	v_sub_f32_e32 v112, 1.0, v112
	v_sub_f32_e32 v114, 2.0, v112
	v_mul_f32_e32 v114, v112, v114
	v_max_f32_e32 v114, 0, v114
	v_sqrt_f32_e32 v114, v114
	v_mul_f32_e32 v88, 0xbfb8aa3b, v88
	v_exp_f32_e32 v88, v88
	v_add_f32_e32 v92, v92, v72
	v_mul_f32_e32 v113, v113, v114
	v_cvt_pk_bf16_f32 v118, v112, v113
	v_add_f32_e32 v112, v115, v79
	v_mul_f32_e32 v112, 0xbfb8aa3b, v112
	v_exp_f32_e32 v112, v112
	v_add_f32_e32 v113, v119, v75
	v_mul_f32_e32 v113, 0xbfb8aa3b, v113
	v_exp_f32_e32 v113, v113
	v_add_f32_e32 v112, 1.0, v112
	v_rcp_f32_e32 v112, v112
	v_and_b32_e32 v115, 0xffff0000, v198
	v_add_f32_e32 v113, 1.0, v113
	v_rcp_f32_e32 v113, v113
	v_mul_f32_e32 v112, v112, v139
	v_mul_f32_e32 v112, 0x3fb8aa3b, v112
	v_exp_f32_e32 v112, v112
	v_mul_f32_e32 v113, v113, v125
	v_add_f32_e32 v88, 1.0, v88
	v_rcp_f32_e32 v88, v88
	v_sub_f32_e32 v112, 1.0, v112
	v_sub_f32_e32 v114, 2.0, v112
	v_mul_f32_e32 v114, v112, v114
	v_max_f32_e32 v114, 0, v114
	v_sqrt_f32_e32 v114, v114
	v_mul_f32_e32 v88, v88, v136
	v_mul_f32_e32 v88, 0x3fb8aa3b, v88
	v_exp_f32_e32 v88, v88
	v_mul_f32_e32 v113, v113, v114
	v_cvt_pk_bf16_f32 v119, v112, v113
	v_lshlrev_b64 v[112:113], 13, v[196:197]
	v_lshl_add_u64 v[112:113], s[42:43], 0, v[112:113]
	v_lshl_add_u64 v[112:113], v[112:113], 0, v[174:175]
	global_store_dwordx4 v[112:113], v[116:119], off
	v_lshlrev_b32_e32 v114, 16, v198
	v_mul_f32_e32 v108, v108, v114
	v_sub_f32_e32 v118, 2.0, v104
	v_mul_f32_e32 v118, v104, v118
	v_max_f32_e32 v118, 0, v118
	v_sqrt_f32_e32 v118, v118
	v_lshlrev_b32_e32 v116, 16, v199
	v_and_b32_e32 v117, 0xffff0000, v199
	v_mul_f32_e32 v92, 0xbfb8aa3b, v92
	v_mul_f32_e32 v108, v108, v118
	v_cvt_pk_bf16_f32 v108, v104, v108
	v_add_f32_e32 v104, v105, v77
	v_mul_f32_e32 v104, 0xbfb8aa3b, v104
	v_exp_f32_e32 v104, v104
	v_add_f32_e32 v105, v109, v73
	v_mul_f32_e32 v105, 0xbfb8aa3b, v105
	v_exp_f32_e32 v105, v105
	v_add_f32_e32 v104, 1.0, v104
	v_rcp_f32_e32 v104, v104
	v_exp_f32_e32 v92, v92
	v_add_f32_e32 v105, 1.0, v105
	v_rcp_f32_e32 v105, v105
	v_mul_f32_e32 v104, v104, v137
	v_mul_f32_e32 v104, 0x3fb8aa3b, v104
	v_exp_f32_e32 v104, v104
	v_mul_f32_e32 v105, v105, v115
	v_sub_f32_e32 v88, 1.0, v88
	v_add_f32_e32 v92, 1.0, v92
	v_sub_f32_e32 v104, 1.0, v104
	v_sub_f32_e32 v109, 2.0, v104
	v_mul_f32_e32 v109, v104, v109
	v_max_f32_e32 v109, 0, v109
	v_sqrt_f32_e32 v109, v109
	v_rcp_f32_e32 v92, v92
	v_add_f32_e32 v80, v80, v76
	v_mul_f32_e32 v80, 0xbfb8aa3b, v80
	v_mul_f32_e32 v105, v105, v109
	v_cvt_pk_bf16_f32 v109, v104, v105
	v_add_f32_e32 v104, v106, v78
	v_mul_f32_e32 v104, 0xbfb8aa3b, v104
	v_exp_f32_e32 v104, v104
	v_add_f32_e32 v105, v110, v74
	v_mul_f32_e32 v105, 0xbfb8aa3b, v105
	v_exp_f32_e32 v105, v105
	v_add_f32_e32 v104, 1.0, v104
	v_rcp_f32_e32 v104, v104
	v_exp_f32_e32 v80, v80
	v_add_f32_e32 v105, 1.0, v105
	v_rcp_f32_e32 v105, v105
	v_mul_f32_e32 v104, v104, v138
	v_mul_f32_e32 v104, 0x3fb8aa3b, v104
	v_exp_f32_e32 v104, v104
	v_mul_f32_e32 v105, v105, v116
	v_add_f32_e32 v80, 1.0, v80
	v_rcp_f32_e32 v80, v80
	v_sub_f32_e32 v104, 1.0, v104
; __device__ __forceinline__ unsigned cvt_pk_bf16(float lo, float hi) { const bf16x2_t r = __builtin_convertvector((f32x2){lo, hi}, bf16x2_t); return __builtin_bit_cast(unsigned, r); }
; __device__ __forceinline__ float bf_lo(unsigned w) { return __uint_as_float(w << 16); }
; __device__ __forceinline__ float bf_hi(unsigned w) { return __uint_as_float(w & 0xffff0000u); }
;     __device__ __forceinline__ void operator()(const AccT& acc, const Unit& u, int wr, int wc, int fr, int fq) const {
;     ...
;         for (int n = 0; n < 2; ++n) {
;             u32x2 xw[2][4];
; #pragma unroll
;             for (int ai = 0; ai < 2; ++ai)
; #pragma unroll
;                 for (int m = 0; m < 4; ++m) xw[ai][m] = *(const u32x2*)(XC + (size_t)(row0 + ai * HALF + m * 16) * DM + ch0 + 16 * n);
;             const f32x4 bra = *(const f32x4*)(b_ra + ch0 + 16 * n), bri = *(const f32x4*)(b_ri + ch0 + 16 * n), l = *(const f32x4*)(lam + ch0 + 16 * n);
;             f32x4 sp;
; #pragma unroll
;             for (int j = 0; j < 4; ++j) sp[j] = -8.0f * log1pf(__expf(-l[j]));
; #pragma unroll
;             for (int ai = 0; ai < 2; ++ai)
; #pragma unroll
;                 for (int m = 0; m < 4; ++m) { const size_t off = (size_t)(row0 + ai * HALF + m * 16) * DM + ch0 + 16 * n;
;                     const f32x4 rp = acc[ai][0][m][n] + bra, ip = acc[ai][1][m][n] + bri;
;                     const u32x2 w = xw[ai][m]; const float xv[4] = {bf_lo(w.x), bf_hi(w.x), bf_lo(w.y), bf_hi(w.y)};
;                     u32x4 o;
; #pragma unroll
;                     for (int j = 0; j < 4; ++j) { const float r = __builtin_amdgcn_rcpf(1.0f + __expf(-rp[j])), ig = __builtin_amdgcn_rcpf(1.0f + __expf(-ip[j])); const float la = sp[j] * r; const float d = 1.0f - __expf(la);
;                         o[j] = cvt_pk_bf16(d, __builtin_amdgcn_sqrtf(fmaxf(d * (2.0f - d), 0.f)) * (ig * xv[j])); }
;                     *(u32x4*)(AU + off) = o; }
	v_sub_f32_e32 v106, 2.0, v104
	v_mul_f32_e32 v106, v104, v106
	v_max_f32_e32 v106, 0, v106
	v_sqrt_f32_e32 v106, v106
	v_mul_f32_e32 v80, v80, v136
	v_mul_f32_e32 v80, 0x3fb8aa3b, v80
	v_add_f32_e32 v84, v84, v72
	v_mul_f32_e32 v105, v105, v106
	v_cvt_pk_bf16_f32 v110, v104, v105
	v_add_f32_e32 v104, v107, v79
	v_mul_f32_e32 v104, 0xbfb8aa3b, v104
	v_exp_f32_e32 v104, v104
	v_add_f32_e32 v105, v111, v75
	v_mul_f32_e32 v105, 0xbfb8aa3b, v105
	v_exp_f32_e32 v105, v105
	v_add_f32_e32 v104, 1.0, v104
	v_rcp_f32_e32 v104, v104
	v_and_b32_e32 v107, 0xffff0000, v194
	v_add_f32_e32 v105, 1.0, v105
	v_rcp_f32_e32 v105, v105
	v_mul_f32_e32 v104, v104, v139
	v_mul_f32_e32 v104, 0x3fb8aa3b, v104
	v_exp_f32_e32 v104, v104
	v_mul_f32_e32 v105, v105, v117
	v_exp_f32_e32 v80, v80
	v_mul_f32_e32 v84, 0xbfb8aa3b, v84
	v_sub_f32_e32 v104, 1.0, v104
	v_sub_f32_e32 v106, 2.0, v104
	v_mul_f32_e32 v106, v104, v106
	v_max_f32_e32 v106, 0, v106
	v_sqrt_f32_e32 v106, v106
	v_exp_f32_e32 v84, v84
	v_sub_f32_e32 v80, 1.0, v80
	v_add_f32_e32 v64, v64, v76
	v_mul_f32_e32 v105, v105, v106
	v_cvt_pk_bf16_f32 v111, v104, v105
	v_lshlrev_b64 v[104:105], 13, v[192:193]
	v_lshl_add_u64 v[104:105], s[42:43], 0, v[104:105]
	v_lshl_add_u64 v[104:105], v[104:105], 0, v[174:175]
	global_store_dwordx4 v[104:105], v[108:111], off
	global_load_dwordx2 v[114:115], v[154:155], off offset:32
	global_load_dwordx2 v[122:123], v[156:157], off offset:32
	global_load_dwordx2 v[148:149], v[158:159], off offset:32
	global_load_dwordx2 v[192:193], v[160:161], off offset:32
	global_load_dwordx2 v[202:203], v[162:163], off offset:32
	global_load_dwordx2 v[208:209], v[164:165], off offset:32
	global_load_dwordx2 v[210:211], v[166:167], off offset:32
	global_load_dwordx2 v[224:225], v[168:169], off offset:32
	global_load_dwordx4 v[116:119], v[176:177], off offset:64
	global_load_dwordx4 v[196:199], v[178:179], off offset:64
	global_load_dwordx4 v[204:207], v[172:173], off offset:64
	v_lshlrev_b32_e32 v106, 16, v194
	v_mul_f32_e32 v100, v100, v106
	v_sub_f32_e32 v110, 2.0, v96
	v_mul_f32_e32 v110, v96, v110
	v_max_f32_e32 v110, 0, v110
	v_sqrt_f32_e32 v110, v110
	v_lshlrev_b32_e32 v108, 16, v195
	v_and_b32_e32 v109, 0xffff0000, v195
	v_add_f32_e32 v84, 1.0, v84
	v_mul_f32_e32 v100, v100, v110
	v_cvt_pk_bf16_f32 v100, v96, v100
	v_add_f32_e32 v96, v97, v77
	v_mul_f32_e32 v96, 0xbfb8aa3b, v96
	v_exp_f32_e32 v96, v96
	v_add_f32_e32 v97, v101, v73
	v_mul_f32_e32 v97, 0xbfb8aa3b, v97
	v_exp_f32_e32 v97, v97
	v_add_f32_e32 v96, 1.0, v96
	v_rcp_f32_e32 v96, v96
	v_rcp_f32_e32 v84, v84
	v_add_f32_e32 v97, 1.0, v97
	v_rcp_f32_e32 v97, v97
	v_mul_f32_e32 v96, v96, v137
	v_mul_f32_e32 v96, 0x3fb8aa3b, v96
	v_exp_f32_e32 v96, v96
	v_mul_f32_e32 v97, v97, v107
	v_mul_f32_e32 v64, 0xbfb8aa3b, v64
	v_exp_f32_e32 v64, v64
	v_sub_f32_e32 v96, 1.0, v96
	v_sub_f32_e32 v101, 2.0, v96
	v_mul_f32_e32 v101, v96, v101
	v_max_f32_e32 v101, 0, v101
	v_sqrt_f32_e32 v101, v101
	v_add_f32_e32 v64, 1.0, v64
	v_rcp_f32_e32 v64, v64
	v_add_f32_e32 v68, v68, v72
	v_mul_f32_e32 v97, v97, v101
	v_cvt_pk_bf16_f32 v101, v96, v97
	v_add_f32_e32 v96, v98, v78
	v_mul_f32_e32 v96, 0xbfb8aa3b, v96
	v_exp_f32_e32 v96, v96
	v_add_f32_e32 v97, v102, v74
	v_mul_f32_e32 v97, 0xbfb8aa3b, v97
	v_exp_f32_e32 v97, v97
	v_add_f32_e32 v96, 1.0, v96
	v_rcp_f32_e32 v96, v96
	v_mul_f32_e32 v64, v64, v136
	v_add_f32_e32 v97, 1.0, v97
	v_rcp_f32_e32 v97, v97
	v_mul_f32_e32 v96, v96, v138
	v_mul_f32_e32 v96, 0x3fb8aa3b, v96
	v_exp_f32_e32 v96, v96
	v_mul_f32_e32 v97, v97, v108
	v_mul_f32_e32 v64, 0x3fb8aa3b, v64
	v_exp_f32_e32 v64, v64
	v_sub_f32_e32 v96, 1.0, v96
	v_sub_f32_e32 v98, 2.0, v96
	v_mul_f32_e32 v98, v96, v98
	v_max_f32_e32 v98, 0, v98
	v_sqrt_f32_e32 v98, v98
	v_add_f32_e32 v65, v65, v77
	v_mul_f32_e32 v68, 0xbfb8aa3b, v68
	v_mul_f32_e32 v65, 0xbfb8aa3b, v65
	v_mul_f32_e32 v97, v97, v98
	v_cvt_pk_bf16_f32 v102, v96, v97
	v_add_f32_e32 v96, v99, v79
	v_mul_f32_e32 v96, 0xbfb8aa3b, v96
	v_exp_f32_e32 v96, v96
	v_add_f32_e32 v97, v103, v75
	v_mul_f32_e32 v97, 0xbfb8aa3b, v97
	v_exp_f32_e32 v97, v97
	v_add_f32_e32 v96, 1.0, v96
	v_rcp_f32_e32 v96, v96
	v_and_b32_e32 v99, 0xffff0000, v190
	v_add_f32_e32 v97, 1.0, v97
	v_rcp_f32_e32 v97, v97
	v_mul_f32_e32 v96, v96, v139
	v_mul_f32_e32 v96, 0x3fb8aa3b, v96
	v_exp_f32_e32 v96, v96
	v_mul_f32_e32 v97, v97, v109
	v_exp_f32_e32 v68, v68
	v_exp_f32_e32 v65, v65
	v_sub_f32_e32 v96, 1.0, v96
	v_sub_f32_e32 v98, 2.0, v96
	v_mul_f32_e32 v98, v96, v98
	v_max_f32_e32 v98, 0, v98
	v_sqrt_f32_e32 v98, v98
	v_sub_f32_e32 v64, 1.0, v64
	v_sub_f32_e32 v72, 2.0, v64
	v_add_f32_e32 v68, 1.0, v68
	v_mul_f32_e32 v97, v97, v98
	v_cvt_pk_bf16_f32 v103, v96, v97
	v_lshlrev_b64 v[96:97], 13, v[188:189]
	v_lshl_add_u64 v[96:97], s[42:43], 0, v[96:97]
	v_lshl_add_u64 v[96:97], v[96:97], 0, v[174:175]
	global_store_dwordx4 v[96:97], v[100:103], off
	v_lshlrev_b32_e32 v98, 16, v190
	v_mul_f32_e32 v92, v92, v98
	v_sub_f32_e32 v102, 2.0, v88
	v_mul_f32_e32 v102, v88, v102
	v_max_f32_e32 v102, 0, v102
	v_sqrt_f32_e32 v102, v102
	v_lshlrev_b32_e32 v100, 16, v191
	v_and_b32_e32 v101, 0xffff0000, v191
	v_mul_f32_e32 v72, v64, v72
	v_mul_f32_e32 v92, v92, v102
	v_cvt_pk_bf16_f32 v92, v88, v92
	v_add_f32_e32 v88, v89, v77
	v_mul_f32_e32 v88, 0xbfb8aa3b, v88
	v_exp_f32_e32 v88, v88
	v_add_f32_e32 v89, v93, v73
	v_mul_f32_e32 v89, 0xbfb8aa3b, v89
	v_exp_f32_e32 v89, v89
	v_add_f32_e32 v88, 1.0, v88
	v_rcp_f32_e32 v88, v88
	v_add_f32_e32 v65, 1.0, v65
	v_add_f32_e32 v89, 1.0, v89
	v_rcp_f32_e32 v89, v89
	v_mul_f32_e32 v88, v88, v137
	v_mul_f32_e32 v88, 0x3fb8aa3b, v88
	v_exp_f32_e32 v88, v88
	v_mul_f32_e32 v89, v89, v99
; __device__ __forceinline__ unsigned cvt_pk_bf16(float lo, float hi) { const bf16x2_t r = __builtin_convertvector((f32x2){lo, hi}, bf16x2_t); return __builtin_bit_cast(unsigned, r); }
; __device__ __forceinline__ float bf_lo(unsigned w) { return __uint_as_float(w << 16); }
; __device__ __forceinline__ float bf_hi(unsigned w) { return __uint_as_float(w & 0xffff0000u); }
;     __device__ __forceinline__ void operator()(const AccT& acc, const Unit& u, int wr, int wc, int fr, int fq) const {
;     ...
; #pragma unroll
;             for (int ai = 0; ai < 2; ++ai)
; #pragma unroll
;                 for (int m = 0; m < 4; ++m) { const size_t off = (size_t)(row0 + ai * HALF + m * 16) * DM + ch0 + 16 * n;
;                     const f32x4 rp = acc[ai][0][m][n] + bra, ip = acc[ai][1][m][n] + bri;
;                     const u32x2 w = xw[ai][m]; const float xv[4] = {bf_lo(w.x), bf_hi(w.x), bf_lo(w.y), bf_hi(w.y)};
;                     u32x4 o;
; #pragma unroll
;                     for (int j = 0; j < 4; ++j) { const float r = __builtin_amdgcn_rcpf(1.0f + __expf(-rp[j])), ig = __builtin_amdgcn_rcpf(1.0f + __expf(-ip[j])); const float la = sp[j] * r; const float d = 1.0f - __expf(la);
;                         o[j] = cvt_pk_bf16(d, __builtin_amdgcn_sqrtf(fmaxf(d * (2.0f - d), 0.f)) * (ig * xv[j])); }
;                     *(u32x4*)(AU + off) = o; }
	v_rcp_f32_e32 v68, v68
	v_max_f32_e32 v72, 0, v72
	v_sub_f32_e32 v88, 1.0, v88
	v_sub_f32_e32 v93, 2.0, v88
	v_mul_f32_e32 v93, v88, v93
	v_max_f32_e32 v93, 0, v93
	v_sqrt_f32_e32 v93, v93
	v_rcp_f32_e32 v65, v65
	v_sqrt_f32_e32 v72, v72
	v_add_f32_e32 v66, v66, v78
	v_mul_f32_e32 v89, v89, v93
	v_cvt_pk_bf16_f32 v93, v88, v89
	v_add_f32_e32 v88, v90, v78
	v_mul_f32_e32 v88, 0xbfb8aa3b, v88
	v_exp_f32_e32 v88, v88
	v_add_f32_e32 v89, v94, v74
	v_mul_f32_e32 v89, 0xbfb8aa3b, v89
	v_exp_f32_e32 v89, v89
	v_add_f32_e32 v88, 1.0, v88
	v_rcp_f32_e32 v88, v88
	v_mul_f32_e32 v65, v65, v137
	v_add_f32_e32 v89, 1.0, v89
	v_rcp_f32_e32 v89, v89
	v_mul_f32_e32 v88, v88, v138
	v_mul_f32_e32 v88, 0x3fb8aa3b, v88
	v_exp_f32_e32 v88, v88
	v_mul_f32_e32 v89, v89, v100
	v_mul_f32_e32 v65, 0x3fb8aa3b, v65
	v_exp_f32_e32 v65, v65
	v_sub_f32_e32 v88, 1.0, v88
	v_sub_f32_e32 v90, 2.0, v88
	v_mul_f32_e32 v90, v88, v90
	v_max_f32_e32 v90, 0, v90
	v_sqrt_f32_e32 v90, v90
	v_mul_f32_e32 v66, 0xbfb8aa3b, v66
	v_exp_f32_e32 v66, v66
	v_sub_f32_e32 v65, 1.0, v65
	v_mul_f32_e32 v89, v89, v90
	v_cvt_pk_bf16_f32 v94, v88, v89
	v_add_f32_e32 v88, v91, v79
	v_mul_f32_e32 v88, 0xbfb8aa3b, v88
	v_exp_f32_e32 v88, v88
	v_add_f32_e32 v89, v95, v75
	v_mul_f32_e32 v89, 0xbfb8aa3b, v89
	v_exp_f32_e32 v89, v89
	v_add_f32_e32 v88, 1.0, v88
	v_rcp_f32_e32 v88, v88
	v_and_b32_e32 v91, 0xffff0000, v186
	v_add_f32_e32 v89, 1.0, v89
	v_rcp_f32_e32 v89, v89
	v_mul_f32_e32 v88, v88, v139
	v_mul_f32_e32 v88, 0x3fb8aa3b, v88
	v_exp_f32_e32 v88, v88
	v_mul_f32_e32 v89, v89, v101
	v_add_f32_e32 v66, 1.0, v66
	v_rcp_f32_e32 v66, v66
	v_sub_f32_e32 v88, 1.0, v88
	v_sub_f32_e32 v90, 2.0, v88
	v_mul_f32_e32 v90, v88, v90
	v_max_f32_e32 v90, 0, v90
	v_sqrt_f32_e32 v90, v90
	v_mul_f32_e32 v66, v66, v138
	v_mul_f32_e32 v66, 0x3fb8aa3b, v66
	v_exp_f32_e32 v66, v66
	v_mul_f32_e32 v89, v89, v90
	v_cvt_pk_bf16_f32 v95, v88, v89
	v_lshlrev_b64 v[88:89], 13, v[184:185]
	v_lshl_add_u64 v[88:89], s[42:43], 0, v[88:89]
	v_lshl_add_u64 v[88:89], v[88:89], 0, v[174:175]
	global_store_dwordx4 v[88:89], v[92:95], off
	v_lshlrev_b32_e32 v90, 16, v186
	v_mul_f32_e32 v84, v84, v90
	v_sub_f32_e32 v94, 2.0, v80
	v_mul_f32_e32 v94, v80, v94
	v_max_f32_e32 v94, 0, v94
	v_sqrt_f32_e32 v94, v94
	v_lshlrev_b32_e32 v92, 16, v187
	v_and_b32_e32 v93, 0xffff0000, v187
	v_add_f32_e32 v67, v67, v79
	v_mul_f32_e32 v84, v84, v94
	v_cvt_pk_bf16_f32 v84, v80, v84
	v_add_f32_e32 v80, v81, v77
	v_mul_f32_e32 v80, 0xbfb8aa3b, v80
	v_exp_f32_e32 v80, v80
	v_add_f32_e32 v81, v85, v73
	v_mul_f32_e32 v81, 0xbfb8aa3b, v81
	v_exp_f32_e32 v81, v81
	v_add_f32_e32 v80, 1.0, v80
	v_rcp_f32_e32 v80, v80
	v_mul_f32_e32 v67, 0xbfb8aa3b, v67
	v_add_f32_e32 v81, 1.0, v81
	v_rcp_f32_e32 v81, v81
	v_mul_f32_e32 v80, v80, v137
	v_mul_f32_e32 v80, 0x3fb8aa3b, v80
	v_exp_f32_e32 v80, v80
	v_mul_f32_e32 v81, v81, v91
	v_exp_f32_e32 v67, v67
	v_sub_f32_e32 v66, 1.0, v66
	v_sub_f32_e32 v80, 1.0, v80
	v_sub_f32_e32 v85, 2.0, v80
	v_mul_f32_e32 v85, v80, v85
	v_max_f32_e32 v85, 0, v85
	v_sqrt_f32_e32 v85, v85
	v_add_f32_e32 v67, 1.0, v67
	v_rcp_f32_e32 v67, v67
	v_mul_f32_e32 v81, v81, v85
	v_cvt_pk_bf16_f32 v85, v80, v81
	v_add_f32_e32 v80, v82, v78
	v_mul_f32_e32 v80, 0xbfb8aa3b, v80
	v_exp_f32_e32 v80, v80
	v_add_f32_e32 v81, v86, v74
	v_mul_f32_e32 v81, 0xbfb8aa3b, v81
	v_exp_f32_e32 v81, v81
	v_add_f32_e32 v80, 1.0, v80
	v_rcp_f32_e32 v80, v80
	v_mul_f32_e32 v67, v67, v139
	v_add_f32_e32 v81, 1.0, v81
	v_rcp_f32_e32 v81, v81
	v_mul_f32_e32 v80, v80, v138
	v_mul_f32_e32 v80, 0x3fb8aa3b, v80
	v_exp_f32_e32 v80, v80
	v_mul_f32_e32 v81, v81, v92
	v_mul_f32_e32 v67, 0x3fb8aa3b, v67
	v_exp_f32_e32 v67, v67
	v_sub_f32_e32 v80, 1.0, v80
	v_sub_f32_e32 v82, 2.0, v80
	v_mul_f32_e32 v82, v80, v82
	v_max_f32_e32 v82, 0, v82
	v_sqrt_f32_e32 v82, v82
	v_sub_f32_e32 v67, 1.0, v67
	v_mul_f32_e32 v81, v81, v82
	v_cvt_pk_bf16_f32 v86, v80, v81
	v_add_f32_e32 v80, v83, v79
	v_mul_f32_e32 v80, 0xbfb8aa3b, v80
	v_exp_f32_e32 v80, v80
	v_add_f32_e32 v81, v87, v75
	v_mul_f32_e32 v81, 0xbfb8aa3b, v81
	v_exp_f32_e32 v81, v81
	v_add_f32_e32 v80, 1.0, v80
	v_rcp_f32_e32 v80, v80
	v_and_b32_e32 v83, 0xffff0000, v182
	v_add_f32_e32 v81, 1.0, v81
	v_rcp_f32_e32 v81, v81
	v_mul_f32_e32 v80, v80, v139
	v_mul_f32_e32 v80, 0x3fb8aa3b, v80
	v_exp_f32_e32 v80, v80
	v_mul_f32_e32 v81, v81, v93
	v_sub_f32_e32 v80, 1.0, v80
	v_sub_f32_e32 v82, 2.0, v80
	v_mul_f32_e32 v82, v80, v82
	v_max_f32_e32 v82, 0, v82
	v_sqrt_f32_e32 v82, v82
	s_nop 0
	v_mul_f32_e32 v81, v81, v82
	v_lshlrev_b32_e32 v82, 16, v182
	v_mul_f32_e32 v68, v68, v82
	v_mul_f32_e32 v68, v68, v72
	v_cvt_pk_bf16_f32 v64, v64, v68
	v_add_f32_e32 v68, v69, v73
	v_mul_f32_e32 v68, 0xbfb8aa3b, v68
	v_exp_f32_e32 v68, v68
	v_sub_f32_e32 v69, 2.0, v65
	v_mul_f32_e32 v69, v65, v69
	v_max_f32_e32 v69, 0, v69
	v_add_f32_e32 v68, 1.0, v68
	v_rcp_f32_e32 v68, v68
	v_sqrt_f32_e32 v69, v69
	v_cvt_pk_bf16_f32 v87, v80, v81
	v_lshlrev_b64 v[80:81], 13, v[180:181]
	v_mul_f32_e32 v68, v68, v83
	v_mul_f32_e32 v68, v68, v69
	v_cvt_pk_bf16_f32 v65, v65, v68
	v_add_f32_e32 v68, v70, v74
	v_mul_f32_e32 v68, 0xbfb8aa3b, v68
	v_exp_f32_e32 v68, v68
	v_sub_f32_e32 v69, 2.0, v66
	v_mul_f32_e32 v69, v66, v69
	v_max_f32_e32 v69, 0, v69
	v_add_f32_e32 v68, 1.0, v68
	v_rcp_f32_e32 v68, v68
	v_lshl_add_u64 v[80:81], s[42:43], 0, v[80:81]
	v_sqrt_f32_e32 v69, v69
	v_lshl_add_u64 v[80:81], v[80:81], 0, v[174:175]
	global_store_dwordx4 v[80:81], v[84:87], off
	s_nop 1
	v_lshlrev_b32_e32 v84, 16, v183
	v_mul_f32_e32 v68, v68, v84
	v_mul_f32_e32 v68, v68, v69
	v_cvt_pk_bf16_f32 v66, v66, v68
	v_add_f32_e32 v68, v71, v75
	v_mul_f32_e32 v68, 0xbfb8aa3b, v68
	v_exp_f32_e32 v68, v68
	v_sub_f32_e32 v69, 2.0, v67
	v_mul_f32_e32 v69, v67, v69
	v_max_f32_e32 v69, 0, v69
	v_add_f32_e32 v68, 1.0, v68
	v_rcp_f32_e32 v68, v68
	v_sqrt_f32_e32 v69, v69
	v_and_b32_e32 v85, 0xffff0000, v183
	v_mul_f32_e32 v68, v68, v85
	v_mul_f32_e32 v68, v68, v69
	v_cvt_pk_bf16_f32 v67, v67, v68
	v_lshlrev_b64 v[68:69], 13, v[170:171]
	v_lshl_add_u64 v[68:69], s[42:43], 0, v[68:69]
	v_lshl_add_u64 v[76:77], v[68:69], 0, v[174:175]
	global_store_dwordx4 v[76:77], v[64:67], off
	s_waitcnt vmcnt(4)
; __device__ __forceinline__ unsigned cvt_pk_bf16(float lo, float hi) { const bf16x2_t r = __builtin_convertvector((f32x2){lo, hi}, bf16x2_t); return __builtin_bit_cast(unsigned, r); }
; __device__ __forceinline__ float bf_lo(unsigned w) { return __uint_as_float(w << 16); }
; __device__ __forceinline__ float bf_hi(unsigned w) { return __uint_as_float(w & 0xffff0000u); }
;     __device__ __forceinline__ void operator()(const AccT& acc, const Unit& u, int wr, int wc, int fr, int fq) const {
;     ...
;                 for (int m = 0; m < 4; ++m) xw[ai][m] = *(const u32x2*)(XC + (size_t)(row0 + ai * HALF + m * 16) * DM + ch0 + 16 * n);
;             const f32x4 bra = *(const f32x4*)(b_ra + ch0 + 16 * n), bri = *(const f32x4*)(b_ri + ch0 + 16 * n), l = *(const f32x4*)(lam + ch0 + 16 * n);
;             f32x4 sp;
; #pragma unroll
;             for (int j = 0; j < 4; ++j) sp[j] = -8.0f * log1pf(__expf(-l[j]));
; #pragma unroll
;             for (int ai = 0; ai < 2; ++ai)
; #pragma unroll
;                 for (int m = 0; m < 4; ++m) { const size_t off = (size_t)(row0 + ai * HALF + m * 16) * DM + ch0 + 16 * n;
;                     const f32x4 rp = acc[ai][0][m][n] + bra, ip = acc[ai][1][m][n] + bri;
;                     const u32x2 w = xw[ai][m]; const float xv[4] = {bf_lo(w.x), bf_hi(w.x), bf_lo(w.y), bf_hi(w.y)};
;                     u32x4 o;
; #pragma unroll
;                     for (int j = 0; j < 4; ++j) { const float r = __builtin_amdgcn_rcpf(1.0f + __expf(-rp[j])), ig = __builtin_amdgcn_rcpf(1.0f + __expf(-ip[j])); const float la = sp[j] * r; const float d = 1.0f - __expf(la);
;                         o[j] = cvt_pk_bf16(d, __builtin_amdgcn_sqrtf(fmaxf(d * (2.0f - d), 0.f)) * (ig * xv[j])); }
	v_mov_b64_e32 v[98:99], v[114:115]
	v_mov_b64_e32 v[94:95], v[122:123]
	v_mov_b64_e32 v[92:93], v[148:149]
	v_mov_b64_e32 v[90:91], v[192:193]
	v_mov_b64_e32 v[86:87], v[202:203]
	v_mov_b64_e32 v[84:85], v[208:209]
	v_mov_b64_e32 v[82:83], v[210:211]
	v_mov_b64_e32 v[78:79], v[224:225]
	v_mov_b64_e32 v[68:69], v[116:117]
	v_mov_b64_e32 v[70:71], v[118:119]
	v_mov_b64_e32 v[64:65], v[196:197]
	v_mov_b64_e32 v[66:67], v[198:199]
	v_mov_b64_e32 v[72:73], v[204:205]
	v_mov_b64_e32 v[74:75], v[206:207]
	v_add_f32_e32 v56, v56, v68
	v_mul_f32_e32 v56, 0xbfb8aa3b, v56
	v_mul_f32_e32 v72, 0xbfb8aa3b, v72
	v_exp_f32_e32 v72, v72
	v_mul_f32_e32 v73, 0xbfb8aa3b, v73
	v_exp_f32_e32 v73, v73
	v_mul_f32_e32 v74, 0xbfb8aa3b, v74
	v_add_f32_e32 v102, 1.0, v72
	v_add_f32_e32 v100, -1.0, v102
	v_sub_f32_e32 v101, v100, v102
	v_add_f32_e32 v101, 1.0, v101
	v_sub_f32_e32 v100, v72, v100
	v_add_f32_e32 v103, v100, v101
	v_frexp_mant_f32_e32 v100, v102
	v_cmp_gt_f32_e32 vcc, s76, v100
	v_cvt_f64_f32_e32 v[100:101], v102
	v_frexp_exp_i32_f64_e32 v100, v[100:101]
	v_subbrev_co_u32_e32 v110, vcc, 0, v100, vcc
	v_sub_u32_e32 v100, 0, v110
	v_ldexp_f32 v101, v102, v100
	v_add_f32_e32 v102, -1.0, v101
	v_add_f32_e32 v106, 1.0, v101
	v_ldexp_f32 v100, v103, v100
	v_add_f32_e32 v103, 1.0, v102
	v_add_f32_e32 v107, -1.0, v106
	v_sub_f32_e32 v103, v101, v103
	v_sub_f32_e32 v101, v101, v107
	v_add_f32_e32 v103, v100, v103
	v_add_f32_e32 v100, v100, v101
	v_add_f32_e32 v111, v106, v100
	v_rcp_f32_e32 v115, v111
	v_sub_f32_e32 v101, v111, v106
	v_sub_f32_e32 v114, v100, v101
	v_add_f32_e32 v101, v102, v103
	v_mul_f32_e32 v117, v101, v115
	v_sub_f32_e32 v100, v101, v102
	v_mul_f32_e32 v102, v111, v117
	v_fma_f32 v106, v117, v111, -v102
	v_fmac_f32_e32 v106, v117, v114
	v_sub_f32_e32 v116, v103, v100
	v_add_f32_e32 v100, v102, v106
	v_sub_f32_e32 v103, v101, v100
	v_pk_add_f32 v[108:109], v[100:101], v[102:103] neg_lo:[0,1] neg_hi:[0,1]
	v_mov_b32_e32 v107, v100
	v_pk_add_f32 v[100:101], v[108:109], v[106:107] neg_lo:[0,1] neg_hi:[0,1]
	v_cmp_neq_f32_e32 vcc, s78, v72
	v_add_f32_e32 v101, v116, v101
	v_add_f32_e32 v100, v100, v101
	v_add_f32_e32 v101, v103, v100
	v_mul_f32_e32 v116, v115, v101
	v_mul_f32_e32 v102, v111, v116
	v_fma_f32 v106, v116, v111, -v102
	v_fmac_f32_e32 v106, v116, v114
	v_sub_f32_e32 v103, v103, v101
	v_add_f32_e32 v111, v100, v103
	v_add_f32_e32 v100, v102, v106
	v_sub_f32_e32 v103, v101, v100
	v_pk_add_f32 v[108:109], v[100:101], v[102:103] neg_lo:[0,1] neg_hi:[0,1]
	v_mov_b32_e32 v107, v100
	v_pk_add_f32 v[100:101], v[108:109], v[106:107] neg_lo:[0,1] neg_hi:[0,1]
	v_exp_f32_e32 v74, v74
	v_add_f32_e32 v101, v111, v101
	v_add_f32_e32 v100, v100, v101
	v_add_f32_e32 v101, v117, v116
	v_add_f32_e32 v100, v103, v100
	v_sub_f32_e32 v102, v101, v117
	v_mul_f32_e32 v100, v115, v100
	v_sub_f32_e32 v102, v116, v102
	v_add_f32_e32 v102, v102, v100
	v_add_f32_e32 v106, v101, v102
	v_mul_f32_e32 v107, v106, v106
	v_fmamk_f32 v100, v107, 0x3e9b6dac, v218
	v_fmaak_f32 v153, v107, v100, 0x3f2aaada
	v_cvt_f32_i32_e32 v100, v110
	v_sub_f32_e32 v101, v106, v101
	v_sub_f32_e32 v101, v102, v101
	v_ldexp_f32 v108, v101, 1
	v_mul_f32_e32 v101, v106, v107
	v_ldexp_f32 v103, v106, 1
	v_pk_mul_f32 v[106:107], v[100:101], v[152:153]
	v_mul_f32_e32 v75, 0xbfb8aa3b, v75
	v_fma_f32 v102, v100, s77, -v106
	v_fmac_f32_e32 v102, 0xb102e308, v100
	v_pk_add_f32 v[100:101], v[106:107], v[102:103]
	v_exp_f32_e32 v75, v75
	v_sub_f32_e32 v103, v101, v103
	v_sub_f32_e32 v103, v107, v103
	v_add_f32_e32 v109, v108, v103
	v_mov_b32_e32 v108, v106
	v_pk_add_f32 v[106:107], v[100:101], v[106:107] neg_lo:[0,1] neg_hi:[0,1]
	v_pk_add_f32 v[110:111], v[100:101], v[108:109]
	v_mov_b32_e32 v103, v100
	v_mov_b32_e32 v107, v111
	v_pk_add_f32 v[114:115], v[102:103], v[106:107] neg_lo:[0,1] neg_hi:[0,1]
	v_pk_add_f32 v[102:103], v[102:103], v[106:107]
	v_mov_b32_e32 v108, v109
	v_pk_add_f32 v[106:107], v[102:103], v[100:101] op_sel:[1,0] op_sel_hi:[0,1] neg_lo:[0,1] neg_hi:[0,1]
	v_pk_add_f32 v[116:117], v[110:111], v[106:107] op_sel_hi:[1,0] neg_lo:[0,1] neg_hi:[0,1]
	v_mov_b32_e32 v110, v111
	v_mov_b32_e32 v111, v103
	v_pk_mov_b32 v[106:107], v[100:101], v[106:107] op_sel:[1,0]
	v_mov_b32_e32 v109, v100
	v_pk_add_f32 v[106:107], v[110:111], v[106:107] neg_lo:[0,1] neg_hi:[0,1]
	v_mov_b32_e32 v116, v114
	v_pk_add_f32 v[100:101], v[108:109], v[106:107] neg_lo:[0,1] neg_hi:[0,1]
	v_mov_b32_e32 v115, v103
	v_pk_add_f32 v[106:107], v[116:117], v[100:101]
	v_exp_f32_e32 v56, v56
	v_pk_add_f32 v[108:109], v[106:107], v[106:107] op_sel:[0,1] op_sel_hi:[1,0]
	v_add_f32_e32 v60, v60, v64
	v_pk_add_f32 v[102:103], v[102:103], v[108:109] op_sel:[1,0] op_sel_hi:[0,1]
	v_mov_b32_e32 v107, v102
	v_pk_add_f32 v[110:111], v[106:107], v[114:115] neg_lo:[0,1] neg_hi:[0,1]
	v_mov_b32_e32 v101, v108
	v_sub_f32_e32 v103, v106, v110
	v_pk_add_f32 v[100:101], v[100:101], v[110:111] neg_lo:[0,1] neg_hi:[0,1]
	v_sub_f32_e32 v103, v114, v103
	v_add_f32_e32 v100, v100, v103
	v_add_f32_e32 v100, v100, v101
	v_add_f32_e32 v100, v102, v100
	v_cndmask_b32_e32 v100, v219, v100, vcc
	v_cmp_ngt_f32_e32 vcc, -1.0, v72
	v_add_f32_e32 v102, 1.0, v73
	v_add_f32_e32 v56, 1.0, v56
	v_cndmask_b32_e32 v100, v220, v100, vcc
	v_cmp_neq_f32_e32 vcc, -1.0, v72
	v_rcp_f32_e32 v56, v56
	v_add_f32_e32 v57, v57, v69
	v_cndmask_b32_e32 v100, v221, v100, vcc
	v_cmp_lt_f32_e64 vcc, |v72|, s79
	v_mul_f32_e32 v60, 0xbfb8aa3b, v60
	v_mul_f32_e32 v57, 0xbfb8aa3b, v57
	v_cndmask_b32_e32 v72, v100, v72, vcc
	v_add_f32_e32 v100, -1.0, v102
	v_sub_f32_e32 v101, v100, v102
	v_add_f32_e32 v101, 1.0, v101
	v_sub_f32_e32 v100, v73, v100
	v_add_f32_e32 v103, v100, v101
; __device__ __forceinline__ float bf_lo(unsigned w) { return __uint_as_float(w << 16); }
; __device__ __forceinline__ float bf_hi(unsigned w) { return __uint_as_float(w & 0xffff0000u); }
;     __device__ __forceinline__ void operator()(const AccT& acc, const Unit& u, int wr, int wc, int fr, int fq) const {
;     ...
;             for (int j = 0; j < 4; ++j) sp[j] = -8.0f * log1pf(__expf(-l[j]));
; #pragma unroll
;             for (int ai = 0; ai < 2; ++ai)
; #pragma unroll
;                 for (int m = 0; m < 4; ++m) { const size_t off = (size_t)(row0 + ai * HALF + m * 16) * DM + ch0 + 16 * n;
;                     const f32x4 rp = acc[ai][0][m][n] + bra, ip = acc[ai][1][m][n] + bri;
;                     const u32x2 w = xw[ai][m]; const float xv[4] = {bf_lo(w.x), bf_hi(w.x), bf_lo(w.y), bf_hi(w.y)};
;                     u32x4 o;
; #pragma unroll
;                     for (int j = 0; j < 4; ++j) { const float r = __builtin_amdgcn_rcpf(1.0f + __expf(-rp[j])), ig = __builtin_amdgcn_rcpf(1.0f + __expf(-ip[j])); const float la = sp[j] * r; const float d = 1.0f - __expf(la);
	v_frexp_mant_f32_e32 v100, v102
	v_cmp_gt_f32_e32 vcc, s76, v100
	v_cvt_f64_f32_e32 v[100:101], v102
	v_frexp_exp_i32_f64_e32 v100, v[100:101]
	v_subbrev_co_u32_e32 v110, vcc, 0, v100, vcc
	v_sub_u32_e32 v100, 0, v110
	v_ldexp_f32 v101, v102, v100
	v_add_f32_e32 v102, -1.0, v101
	v_add_f32_e32 v106, 1.0, v101
	v_ldexp_f32 v100, v103, v100
	v_add_f32_e32 v103, 1.0, v102
	v_add_f32_e32 v107, -1.0, v106
	v_sub_f32_e32 v103, v101, v103
	v_sub_f32_e32 v101, v101, v107
	v_add_f32_e32 v103, v100, v103
	v_add_f32_e32 v100, v100, v101
	v_add_f32_e32 v111, v106, v100
	v_rcp_f32_e32 v115, v111
	v_sub_f32_e32 v101, v111, v106
	v_sub_f32_e32 v114, v100, v101
	v_add_f32_e32 v101, v102, v103
	v_mul_f32_e32 v117, v101, v115
	v_sub_f32_e32 v100, v101, v102
	v_mul_f32_e32 v102, v111, v117
	v_fma_f32 v106, v117, v111, -v102
	v_fmac_f32_e32 v106, v117, v114
	v_sub_f32_e32 v116, v103, v100
	v_add_f32_e32 v100, v102, v106
	v_sub_f32_e32 v103, v101, v100
	v_pk_add_f32 v[108:109], v[100:101], v[102:103] neg_lo:[0,1] neg_hi:[0,1]
	v_mov_b32_e32 v107, v100
	v_pk_add_f32 v[100:101], v[108:109], v[106:107] neg_lo:[0,1] neg_hi:[0,1]
	v_cmp_neq_f32_e32 vcc, s78, v73
	v_add_f32_e32 v101, v116, v101
	v_add_f32_e32 v100, v100, v101
	v_add_f32_e32 v101, v103, v100
	v_mul_f32_e32 v116, v115, v101
	v_mul_f32_e32 v102, v111, v116
	v_fma_f32 v106, v116, v111, -v102
	v_fmac_f32_e32 v106, v116, v114
	v_sub_f32_e32 v103, v103, v101
	v_add_f32_e32 v111, v100, v103
	v_add_f32_e32 v100, v102, v106
	v_sub_f32_e32 v103, v101, v100
	v_pk_add_f32 v[108:109], v[100:101], v[102:103] neg_lo:[0,1] neg_hi:[0,1]
	v_mov_b32_e32 v107, v100
	v_pk_add_f32 v[100:101], v[108:109], v[106:107] neg_lo:[0,1] neg_hi:[0,1]
	v_mul_f32_e32 v72, 0xc1000000, v72
	v_add_f32_e32 v101, v111, v101
	v_add_f32_e32 v100, v100, v101
	v_add_f32_e32 v101, v117, v116
	v_add_f32_e32 v100, v103, v100
	v_sub_f32_e32 v102, v101, v117
	v_mul_f32_e32 v100, v115, v100
	v_sub_f32_e32 v102, v116, v102
	v_add_f32_e32 v102, v102, v100
	v_add_f32_e32 v106, v101, v102
	v_mul_f32_e32 v107, v106, v106
	v_fmamk_f32 v100, v107, 0x3e9b6dac, v218
	v_fmaak_f32 v153, v107, v100, 0x3f2aaada
	v_cvt_f32_i32_e32 v100, v110
	v_sub_f32_e32 v101, v106, v101
	v_sub_f32_e32 v101, v102, v101
	v_ldexp_f32 v108, v101, 1
	v_mul_f32_e32 v101, v106, v107
	v_ldexp_f32 v103, v106, 1
	v_pk_mul_f32 v[106:107], v[100:101], v[152:153]
	v_mul_f32_e32 v56, v56, v72
	v_fma_f32 v102, v100, s77, -v106
	v_fmac_f32_e32 v102, 0xb102e308, v100
	v_pk_add_f32 v[100:101], v[106:107], v[102:103]
	v_mul_f32_e32 v56, 0x3fb8aa3b, v56
	v_sub_f32_e32 v103, v101, v103
	v_sub_f32_e32 v103, v107, v103
	v_add_f32_e32 v109, v108, v103
	v_mov_b32_e32 v108, v106
	v_pk_add_f32 v[106:107], v[100:101], v[106:107] neg_lo:[0,1] neg_hi:[0,1]
	v_pk_add_f32 v[110:111], v[100:101], v[108:109]
	v_mov_b32_e32 v103, v100
	v_mov_b32_e32 v107, v111
	v_pk_add_f32 v[114:115], v[102:103], v[106:107] neg_lo:[0,1] neg_hi:[0,1]
	v_pk_add_f32 v[102:103], v[102:103], v[106:107]
	v_mov_b32_e32 v108, v109
	v_pk_add_f32 v[106:107], v[102:103], v[100:101] op_sel:[1,0] op_sel_hi:[0,1] neg_lo:[0,1] neg_hi:[0,1]
	v_pk_add_f32 v[116:117], v[110:111], v[106:107] op_sel_hi:[1,0] neg_lo:[0,1] neg_hi:[0,1]
	v_mov_b32_e32 v110, v111
	v_mov_b32_e32 v111, v103
	v_pk_mov_b32 v[106:107], v[100:101], v[106:107] op_sel:[1,0]
	v_mov_b32_e32 v109, v100
	v_pk_add_f32 v[106:107], v[110:111], v[106:107] neg_lo:[0,1] neg_hi:[0,1]
	v_mov_b32_e32 v116, v114
	v_pk_add_f32 v[100:101], v[108:109], v[106:107] neg_lo:[0,1] neg_hi:[0,1]
	v_mov_b32_e32 v115, v103
	v_pk_add_f32 v[106:107], v[116:117], v[100:101]
	v_exp_f32_e32 v56, v56
	v_pk_add_f32 v[108:109], v[106:107], v[106:107] op_sel:[0,1] op_sel_hi:[1,0]
	v_exp_f32_e32 v60, v60
	v_pk_add_f32 v[102:103], v[102:103], v[108:109] op_sel:[1,0] op_sel_hi:[0,1]
	v_mov_b32_e32 v107, v102
	v_pk_add_f32 v[110:111], v[106:107], v[114:115] neg_lo:[0,1] neg_hi:[0,1]
	v_mov_b32_e32 v101, v108
	v_sub_f32_e32 v103, v106, v110
	v_pk_add_f32 v[100:101], v[100:101], v[110:111] neg_lo:[0,1] neg_hi:[0,1]
	v_sub_f32_e32 v103, v114, v103
	v_add_f32_e32 v100, v100, v103
	v_add_f32_e32 v100, v100, v101
	v_add_f32_e32 v100, v102, v100
	v_cndmask_b32_e32 v100, v219, v100, vcc
	v_cmp_ngt_f32_e32 vcc, -1.0, v73
	v_add_f32_e32 v102, 1.0, v74
	v_exp_f32_e32 v57, v57
	v_cndmask_b32_e32 v100, v220, v100, vcc
	v_cmp_neq_f32_e32 vcc, -1.0, v73
	v_sub_f32_e32 v56, 1.0, v56
	v_add_f32_e32 v60, 1.0, v60
	v_cndmask_b32_e32 v100, v221, v100, vcc
	v_cmp_lt_f32_e64 vcc, |v73|, s79
	v_add_f32_e32 v57, 1.0, v57
	v_rcp_f32_e32 v60, v60
	v_cndmask_b32_e32 v73, v100, v73, vcc
	v_add_f32_e32 v100, -1.0, v102
	v_sub_f32_e32 v101, v100, v102
	v_add_f32_e32 v101, 1.0, v101
	v_sub_f32_e32 v100, v74, v100
	v_add_f32_e32 v103, v100, v101
	v_frexp_mant_f32_e32 v100, v102
	v_cmp_gt_f32_e32 vcc, s76, v100
	v_cvt_f64_f32_e32 v[100:101], v102
	v_frexp_exp_i32_f64_e32 v100, v[100:101]
	v_subbrev_co_u32_e32 v110, vcc, 0, v100, vcc
	v_sub_u32_e32 v100, 0, v110
	v_ldexp_f32 v101, v102, v100
	v_add_f32_e32 v102, -1.0, v101
	v_add_f32_e32 v106, 1.0, v101
	v_ldexp_f32 v100, v103, v100
	v_add_f32_e32 v103, 1.0, v102
	v_add_f32_e32 v107, -1.0, v106
	v_sub_f32_e32 v103, v101, v103
	v_sub_f32_e32 v101, v101, v107
	v_add_f32_e32 v103, v100, v103
	v_add_f32_e32 v100, v100, v101
	v_add_f32_e32 v111, v106, v100
	v_rcp_f32_e32 v115, v111
	v_sub_f32_e32 v101, v111, v106
	v_sub_f32_e32 v114, v100, v101
	v_add_f32_e32 v101, v102, v103
	v_mul_f32_e32 v117, v101, v115
	v_sub_f32_e32 v100, v101, v102
	v_mul_f32_e32 v102, v111, v117
	v_fma_f32 v106, v117, v111, -v102
	v_fmac_f32_e32 v106, v117, v114
	v_sub_f32_e32 v116, v103, v100
	v_add_f32_e32 v100, v102, v106
; __device__ __forceinline__ float bf_lo(unsigned w) { return __uint_as_float(w << 16); }
; __device__ __forceinline__ float bf_hi(unsigned w) { return __uint_as_float(w & 0xffff0000u); }
;     __device__ __forceinline__ void operator()(const AccT& acc, const Unit& u, int wr, int wc, int fr, int fq) const {
;     ...
;             for (int j = 0; j < 4; ++j) sp[j] = -8.0f * log1pf(__expf(-l[j]));
; #pragma unroll
;             for (int ai = 0; ai < 2; ++ai)
; #pragma unroll
;                 for (int m = 0; m < 4; ++m) { const size_t off = (size_t)(row0 + ai * HALF + m * 16) * DM + ch0 + 16 * n;
;                     const f32x4 rp = acc[ai][0][m][n] + bra, ip = acc[ai][1][m][n] + bri;
;                     const u32x2 w = xw[ai][m]; const float xv[4] = {bf_lo(w.x), bf_hi(w.x), bf_lo(w.y), bf_hi(w.y)};
;                     u32x4 o;
; #pragma unroll
;                     for (int j = 0; j < 4; ++j) { const float r = __builtin_amdgcn_rcpf(1.0f + __expf(-rp[j])), ig = __builtin_amdgcn_rcpf(1.0f + __expf(-ip[j])); const float la = sp[j] * r; const float d = 1.0f - __expf(la);
	v_sub_f32_e32 v103, v101, v100
	v_pk_add_f32 v[108:109], v[100:101], v[102:103] neg_lo:[0,1] neg_hi:[0,1]
	v_mov_b32_e32 v107, v100
	v_pk_add_f32 v[100:101], v[108:109], v[106:107] neg_lo:[0,1] neg_hi:[0,1]
	v_cmp_neq_f32_e32 vcc, s78, v74
	v_add_f32_e32 v101, v116, v101
	v_add_f32_e32 v100, v100, v101
	v_add_f32_e32 v101, v103, v100
	v_mul_f32_e32 v116, v115, v101
	v_mul_f32_e32 v102, v111, v116
	v_fma_f32 v106, v116, v111, -v102
	v_fmac_f32_e32 v106, v116, v114
	v_sub_f32_e32 v103, v103, v101
	v_add_f32_e32 v111, v100, v103
	v_add_f32_e32 v100, v102, v106
	v_sub_f32_e32 v103, v101, v100
	v_pk_add_f32 v[108:109], v[100:101], v[102:103] neg_lo:[0,1] neg_hi:[0,1]
	v_mov_b32_e32 v107, v100
	v_pk_add_f32 v[100:101], v[108:109], v[106:107] neg_lo:[0,1] neg_hi:[0,1]
	v_rcp_f32_e32 v57, v57
	v_add_f32_e32 v101, v111, v101
	v_add_f32_e32 v100, v100, v101
	v_add_f32_e32 v101, v117, v116
	v_add_f32_e32 v100, v103, v100
	v_sub_f32_e32 v102, v101, v117
	v_mul_f32_e32 v100, v115, v100
	v_sub_f32_e32 v102, v116, v102
	v_add_f32_e32 v102, v102, v100
	v_add_f32_e32 v106, v101, v102
	v_mul_f32_e32 v107, v106, v106
	v_fmamk_f32 v100, v107, 0x3e9b6dac, v218
	v_fmaak_f32 v153, v107, v100, 0x3f2aaada
	v_cvt_f32_i32_e32 v100, v110
	v_sub_f32_e32 v101, v106, v101
	v_sub_f32_e32 v101, v102, v101
	v_ldexp_f32 v108, v101, 1
	v_mul_f32_e32 v101, v106, v107
	v_ldexp_f32 v103, v106, 1
	v_pk_mul_f32 v[106:107], v[100:101], v[152:153]
	v_mul_f32_e32 v73, 0xc1000000, v73
	v_fma_f32 v102, v100, s77, -v106
	v_fmac_f32_e32 v102, 0xb102e308, v100
	v_pk_add_f32 v[100:101], v[106:107], v[102:103]
	v_mul_f32_e32 v57, v57, v73
	v_sub_f32_e32 v103, v101, v103
	v_sub_f32_e32 v103, v107, v103
	v_add_f32_e32 v109, v108, v103
	v_mov_b32_e32 v108, v106
	v_pk_add_f32 v[106:107], v[100:101], v[106:107] neg_lo:[0,1] neg_hi:[0,1]
	v_pk_add_f32 v[110:111], v[100:101], v[108:109]
	v_mov_b32_e32 v103, v100
	v_mov_b32_e32 v107, v111
	v_pk_add_f32 v[114:115], v[102:103], v[106:107] neg_lo:[0,1] neg_hi:[0,1]
	v_pk_add_f32 v[102:103], v[102:103], v[106:107]
	v_mov_b32_e32 v108, v109
	v_pk_add_f32 v[106:107], v[102:103], v[100:101] op_sel:[1,0] op_sel_hi:[0,1] neg_lo:[0,1] neg_hi:[0,1]
	v_pk_add_f32 v[116:117], v[110:111], v[106:107] op_sel_hi:[1,0] neg_lo:[0,1] neg_hi:[0,1]
	v_mov_b32_e32 v110, v111
	v_mov_b32_e32 v111, v103
	v_pk_mov_b32 v[106:107], v[100:101], v[106:107] op_sel:[1,0]
	v_mov_b32_e32 v109, v100
	v_pk_add_f32 v[106:107], v[110:111], v[106:107] neg_lo:[0,1] neg_hi:[0,1]
	v_mov_b32_e32 v116, v114
	v_pk_add_f32 v[100:101], v[108:109], v[106:107] neg_lo:[0,1] neg_hi:[0,1]
	v_mov_b32_e32 v115, v103
	v_pk_add_f32 v[106:107], v[116:117], v[100:101]
	v_mul_f32_e32 v57, 0x3fb8aa3b, v57
	v_pk_add_f32 v[108:109], v[106:107], v[106:107] op_sel:[0,1] op_sel_hi:[1,0]
	v_exp_f32_e32 v57, v57
	v_pk_add_f32 v[102:103], v[102:103], v[108:109] op_sel:[1,0] op_sel_hi:[0,1]
	v_mov_b32_e32 v107, v102
	v_pk_add_f32 v[110:111], v[106:107], v[114:115] neg_lo:[0,1] neg_hi:[0,1]
	v_mov_b32_e32 v101, v108
	v_sub_f32_e32 v103, v106, v110
	v_pk_add_f32 v[100:101], v[100:101], v[110:111] neg_lo:[0,1] neg_hi:[0,1]
	v_sub_f32_e32 v103, v114, v103
	v_add_f32_e32 v100, v100, v103
	v_add_f32_e32 v100, v100, v101
	v_add_f32_e32 v100, v102, v100
	v_cndmask_b32_e32 v100, v219, v100, vcc
	v_cmp_ngt_f32_e32 vcc, -1.0, v74
	v_add_f32_e32 v102, 1.0, v75
	v_add_f32_e32 v58, v58, v70
	v_cndmask_b32_e32 v100, v220, v100, vcc
	v_cmp_neq_f32_e32 vcc, -1.0, v74
	v_mul_f32_e32 v58, 0xbfb8aa3b, v58
	v_exp_f32_e32 v58, v58
	v_cndmask_b32_e32 v100, v221, v100, vcc
	v_cmp_lt_f32_e64 vcc, |v74|, s79
	v_sub_f32_e32 v57, 1.0, v57
	v_add_f32_e32 v58, 1.0, v58
	v_cndmask_b32_e32 v74, v100, v74, vcc
	v_add_f32_e32 v100, -1.0, v102
	v_sub_f32_e32 v101, v100, v102
	v_add_f32_e32 v101, 1.0, v101
	v_sub_f32_e32 v100, v75, v100
	v_add_f32_e32 v103, v100, v101
	v_frexp_mant_f32_e32 v100, v102
	v_cmp_gt_f32_e32 vcc, s76, v100
	v_cvt_f64_f32_e32 v[100:101], v102
	v_frexp_exp_i32_f64_e32 v100, v[100:101]
	v_subbrev_co_u32_e32 v110, vcc, 0, v100, vcc
	v_sub_u32_e32 v100, 0, v110
	v_ldexp_f32 v101, v102, v100
	v_add_f32_e32 v102, -1.0, v101
	v_add_f32_e32 v106, 1.0, v101
	v_ldexp_f32 v100, v103, v100
	v_add_f32_e32 v103, 1.0, v102
	v_add_f32_e32 v107, -1.0, v106
	v_sub_f32_e32 v103, v101, v103
	v_sub_f32_e32 v101, v101, v107
	v_add_f32_e32 v103, v100, v103
	v_add_f32_e32 v100, v100, v101
	v_add_f32_e32 v111, v106, v100
	v_rcp_f32_e32 v115, v111
	v_sub_f32_e32 v101, v111, v106
	v_sub_f32_e32 v114, v100, v101
	v_add_f32_e32 v101, v102, v103
	v_mul_f32_e32 v117, v101, v115
	v_sub_f32_e32 v100, v101, v102
	v_mul_f32_e32 v102, v111, v117
	v_fma_f32 v106, v117, v111, -v102
	v_fmac_f32_e32 v106, v117, v114
	v_sub_f32_e32 v116, v103, v100
	v_add_f32_e32 v100, v102, v106
	v_sub_f32_e32 v103, v101, v100
	v_pk_add_f32 v[108:109], v[100:101], v[102:103] neg_lo:[0,1] neg_hi:[0,1]
	v_mov_b32_e32 v107, v100
	v_pk_add_f32 v[100:101], v[108:109], v[106:107] neg_lo:[0,1] neg_hi:[0,1]
	v_cmp_neq_f32_e32 vcc, s78, v75
	v_add_f32_e32 v101, v116, v101
	v_add_f32_e32 v100, v100, v101
	v_add_f32_e32 v101, v103, v100
	v_mul_f32_e32 v116, v115, v101
	v_mul_f32_e32 v102, v111, v116
	v_fma_f32 v106, v116, v111, -v102
	v_fmac_f32_e32 v106, v116, v114
	v_sub_f32_e32 v103, v103, v101
	v_add_f32_e32 v111, v100, v103
	v_add_f32_e32 v100, v102, v106
	v_sub_f32_e32 v103, v101, v100
	v_pk_add_f32 v[108:109], v[100:101], v[102:103] neg_lo:[0,1] neg_hi:[0,1]
	v_mov_b32_e32 v107, v100
	v_pk_add_f32 v[100:101], v[108:109], v[106:107] neg_lo:[0,1] neg_hi:[0,1]
	v_rcp_f32_e32 v58, v58
	v_add_f32_e32 v101, v111, v101
	v_add_f32_e32 v100, v100, v101
	v_add_f32_e32 v101, v117, v116
; __device__ __forceinline__ unsigned cvt_pk_bf16(float lo, float hi) { const bf16x2_t r = __builtin_convertvector((f32x2){lo, hi}, bf16x2_t); return __builtin_bit_cast(unsigned, r); }
; __device__ __forceinline__ float bf_lo(unsigned w) { return __uint_as_float(w << 16); }
; __device__ __forceinline__ float bf_hi(unsigned w) { return __uint_as_float(w & 0xffff0000u); }
;     __device__ __forceinline__ void operator()(const AccT& acc, const Unit& u, int wr, int wc, int fr, int fq) const {
;     ...
;             for (int j = 0; j < 4; ++j) sp[j] = -8.0f * log1pf(__expf(-l[j]));
; #pragma unroll
;             for (int ai = 0; ai < 2; ++ai)
; #pragma unroll
;                 for (int m = 0; m < 4; ++m) { const size_t off = (size_t)(row0 + ai * HALF + m * 16) * DM + ch0 + 16 * n;
;                     const f32x4 rp = acc[ai][0][m][n] + bra, ip = acc[ai][1][m][n] + bri;
;                     const u32x2 w = xw[ai][m]; const float xv[4] = {bf_lo(w.x), bf_hi(w.x), bf_lo(w.y), bf_hi(w.y)};
;                     u32x4 o;
; #pragma unroll
;                     for (int j = 0; j < 4; ++j) { const float r = __builtin_amdgcn_rcpf(1.0f + __expf(-rp[j])), ig = __builtin_amdgcn_rcpf(1.0f + __expf(-ip[j])); const float la = sp[j] * r; const float d = 1.0f - __expf(la);
;                         o[j] = cvt_pk_bf16(d, __builtin_amdgcn_sqrtf(fmaxf(d * (2.0f - d), 0.f)) * (ig * xv[j])); }
;                     *(u32x4*)(AU + off) = o; }
	v_add_f32_e32 v100, v103, v100
	v_sub_f32_e32 v102, v101, v117
	v_mul_f32_e32 v100, v115, v100
	v_sub_f32_e32 v102, v116, v102
	v_add_f32_e32 v102, v102, v100
	v_add_f32_e32 v106, v101, v102
	v_mul_f32_e32 v107, v106, v106
	v_fmamk_f32 v100, v107, 0x3e9b6dac, v218
	v_fmaak_f32 v153, v107, v100, 0x3f2aaada
	v_cvt_f32_i32_e32 v100, v110
	v_sub_f32_e32 v101, v106, v101
	v_sub_f32_e32 v101, v102, v101
	v_ldexp_f32 v108, v101, 1
	v_mul_f32_e32 v101, v106, v107
	v_ldexp_f32 v103, v106, 1
	v_pk_mul_f32 v[106:107], v[100:101], v[152:153]
	v_mul_f32_e32 v74, 0xc1000000, v74
	v_fma_f32 v102, v100, s77, -v106
	v_fmac_f32_e32 v102, 0xb102e308, v100
	v_pk_add_f32 v[100:101], v[106:107], v[102:103]
	v_mul_f32_e32 v58, v58, v74
	v_sub_f32_e32 v103, v101, v103
	v_sub_f32_e32 v103, v107, v103
	v_add_f32_e32 v109, v108, v103
	v_mov_b32_e32 v108, v106
	v_pk_add_f32 v[106:107], v[100:101], v[106:107] neg_lo:[0,1] neg_hi:[0,1]
	v_pk_add_f32 v[110:111], v[100:101], v[108:109]
	v_mov_b32_e32 v103, v100
	v_mov_b32_e32 v107, v111
	v_pk_add_f32 v[114:115], v[102:103], v[106:107] neg_lo:[0,1] neg_hi:[0,1]
	v_pk_add_f32 v[102:103], v[102:103], v[106:107]
	v_mov_b32_e32 v108, v109
	v_pk_add_f32 v[106:107], v[102:103], v[100:101] op_sel:[1,0] op_sel_hi:[0,1] neg_lo:[0,1] neg_hi:[0,1]
	v_pk_add_f32 v[116:117], v[110:111], v[106:107] op_sel_hi:[1,0] neg_lo:[0,1] neg_hi:[0,1]
	v_mov_b32_e32 v110, v111
	v_mov_b32_e32 v111, v103
	v_pk_mov_b32 v[106:107], v[100:101], v[106:107] op_sel:[1,0]
	v_mov_b32_e32 v109, v100
	v_pk_add_f32 v[106:107], v[110:111], v[106:107] neg_lo:[0,1] neg_hi:[0,1]
	v_mov_b32_e32 v116, v114
	v_pk_add_f32 v[100:101], v[108:109], v[106:107] neg_lo:[0,1] neg_hi:[0,1]
	v_mov_b32_e32 v115, v103
	v_pk_add_f32 v[106:107], v[116:117], v[100:101]
	v_mul_f32_e32 v58, 0x3fb8aa3b, v58
	v_pk_add_f32 v[108:109], v[106:107], v[106:107] op_sel:[0,1] op_sel_hi:[1,0]
	v_exp_f32_e32 v58, v58
	v_pk_add_f32 v[102:103], v[102:103], v[108:109] op_sel:[1,0] op_sel_hi:[0,1]
	v_mov_b32_e32 v107, v102
	v_pk_add_f32 v[110:111], v[106:107], v[114:115] neg_lo:[0,1] neg_hi:[0,1]
	v_mov_b32_e32 v101, v108
	v_sub_f32_e32 v103, v106, v110
	v_pk_add_f32 v[100:101], v[100:101], v[110:111] neg_lo:[0,1] neg_hi:[0,1]
	v_sub_f32_e32 v103, v114, v103
	v_add_f32_e32 v100, v100, v103
	v_add_f32_e32 v100, v100, v101
	v_add_f32_e32 v100, v102, v100
	v_sub_f32_e32 v102, 2.0, v56
	v_mul_f32_e32 v102, v56, v102
	v_cndmask_b32_e32 v100, v219, v100, vcc
	v_cmp_ngt_f32_e32 vcc, -1.0, v75
	v_max_f32_e32 v102, 0, v102
	v_sqrt_f32_e32 v102, v102
	v_cndmask_b32_e32 v100, v220, v100, vcc
	v_cmp_neq_f32_e32 vcc, -1.0, v75
	v_add_f32_e32 v59, v59, v71
	v_mul_f32_e32 v59, 0xbfb8aa3b, v59
	v_cndmask_b32_e32 v100, v221, v100, vcc
	v_cmp_lt_f32_e64 vcc, |v75|, s79
	v_exp_f32_e32 v59, v59
	v_sub_f32_e32 v58, 1.0, v58
	v_cndmask_b32_e32 v75, v100, v75, vcc
	v_lshlrev_b32_e32 v100, 16, v98
	v_mul_f32_e32 v60, v60, v100
	v_mul_f32_e32 v60, v60, v102
	v_cvt_pk_bf16_f32 v56, v56, v60
	v_add_f32_e32 v60, v61, v65
	v_mul_f32_e32 v60, 0xbfb8aa3b, v60
	v_exp_f32_e32 v60, v60
	v_sub_f32_e32 v61, 2.0, v57
	v_mul_f32_e32 v61, v57, v61
	v_max_f32_e32 v61, 0, v61
	v_add_f32_e32 v60, 1.0, v60
	v_rcp_f32_e32 v60, v60
	v_sqrt_f32_e32 v61, v61
	v_and_b32_e32 v98, 0xffff0000, v98
	v_add_f32_e32 v59, 1.0, v59
	v_mul_f32_e32 v60, v60, v98
	v_mul_f32_e32 v60, v60, v61
	v_cvt_pk_bf16_f32 v57, v57, v60
	v_add_f32_e32 v60, v62, v66
	v_mul_f32_e32 v60, 0xbfb8aa3b, v60
	v_exp_f32_e32 v60, v60
	v_sub_f32_e32 v61, 2.0, v58
	v_mul_f32_e32 v61, v58, v61
	v_max_f32_e32 v61, 0, v61
	v_add_f32_e32 v60, 1.0, v60
	v_rcp_f32_e32 v60, v60
	v_rcp_f32_e32 v59, v59
	v_sqrt_f32_e32 v61, v61
	v_add_f32_e32 v48, v48, v68
	v_mul_f32_e32 v48, 0xbfb8aa3b, v48
	v_mul_f32_e32 v75, 0xc1000000, v75
	v_lshlrev_b32_e32 v101, 16, v99
	v_exp_f32_e32 v48, v48
	v_mul_f32_e32 v60, v60, v101
	v_mul_f32_e32 v59, v59, v75
	v_mul_f32_e32 v60, v60, v61
	v_mul_f32_e32 v59, 0x3fb8aa3b, v59
	v_cvt_pk_bf16_f32 v58, v58, v60
	v_add_f32_e32 v60, v63, v67
	v_exp_f32_e32 v59, v59
	v_mul_f32_e32 v60, 0xbfb8aa3b, v60
	v_add_f32_e32 v48, 1.0, v48
	v_exp_f32_e32 v60, v60
	v_rcp_f32_e32 v48, v48
	v_sub_f32_e32 v59, 1.0, v59
	v_sub_f32_e32 v61, 2.0, v59
	v_add_f32_e32 v60, 1.0, v60
	v_mul_f32_e32 v61, v59, v61
	v_mul_f32_e32 v48, v48, v72
	v_rcp_f32_e32 v60, v60
	v_max_f32_e32 v61, 0, v61
	v_mul_f32_e32 v48, 0x3fb8aa3b, v48
	v_sqrt_f32_e32 v61, v61
	v_add_f32_e32 v52, v52, v64
	v_exp_f32_e32 v48, v48
	v_add_f32_e32 v49, v49, v69
	v_mul_f32_e32 v52, 0xbfb8aa3b, v52
	v_mul_f32_e32 v49, 0xbfb8aa3b, v49
	v_and_b32_e32 v99, 0xffff0000, v99
	v_exp_f32_e32 v52, v52
	v_exp_f32_e32 v49, v49
	v_mul_f32_e32 v60, v60, v99
	v_mul_f32_e32 v60, v60, v61
	v_sub_f32_e32 v48, 1.0, v48
	v_cvt_pk_bf16_f32 v59, v59, v60
	v_sub_f32_e32 v60, 2.0, v48
	v_add_f32_e32 v52, 1.0, v52
	v_mul_f32_e32 v60, v48, v60
	v_add_f32_e32 v49, 1.0, v49
	v_rcp_f32_e32 v52, v52
	v_max_f32_e32 v60, 0, v60
	v_rcp_f32_e32 v49, v49
	v_sqrt_f32_e32 v60, v60
	global_store_dwordx4 v[128:129], v[56:59], off offset:64
	v_add_f32_e32 v50, v50, v70
	v_mul_f32_e32 v49, v49, v73
	v_lshlrev_b32_e32 v56, 16, v94
	v_mul_f32_e32 v52, v52, v56
	v_mul_f32_e32 v52, v52, v60
	v_mul_f32_e32 v49, 0x3fb8aa3b, v49
	v_cvt_pk_bf16_f32 v48, v48, v52
	v_add_f32_e32 v52, v53, v65
	v_exp_f32_e32 v49, v49
	v_mul_f32_e32 v52, 0xbfb8aa3b, v52
	v_mul_f32_e32 v50, 0xbfb8aa3b, v50
	v_exp_f32_e32 v52, v52
	v_exp_f32_e32 v50, v50
	v_sub_f32_e32 v49, 1.0, v49
	v_sub_f32_e32 v53, 2.0, v49
	v_add_f32_e32 v52, 1.0, v52
	v_mul_f32_e32 v53, v49, v53
	v_add_f32_e32 v50, 1.0, v50
	v_rcp_f32_e32 v52, v52
	v_max_f32_e32 v53, 0, v53
	v_rcp_f32_e32 v50, v50
	v_sqrt_f32_e32 v53, v53
; __device__ __forceinline__ unsigned cvt_pk_bf16(float lo, float hi) { const bf16x2_t r = __builtin_convertvector((f32x2){lo, hi}, bf16x2_t); return __builtin_bit_cast(unsigned, r); }
; __device__ __forceinline__ float bf_lo(unsigned w) { return __uint_as_float(w << 16); }
; __device__ __forceinline__ float bf_hi(unsigned w) { return __uint_as_float(w & 0xffff0000u); }
;     __device__ __forceinline__ void operator()(const AccT& acc, const Unit& u, int wr, int wc, int fr, int fq) const {
;     ...
; #pragma unroll
;             for (int ai = 0; ai < 2; ++ai)
; #pragma unroll
;                 for (int m = 0; m < 4; ++m) { const size_t off = (size_t)(row0 + ai * HALF + m * 16) * DM + ch0 + 16 * n;
;                     const f32x4 rp = acc[ai][0][m][n] + bra, ip = acc[ai][1][m][n] + bri;
;                     const u32x2 w = xw[ai][m]; const float xv[4] = {bf_lo(w.x), bf_hi(w.x), bf_lo(w.y), bf_hi(w.y)};
;                     u32x4 o;
; #pragma unroll
;                     for (int j = 0; j < 4; ++j) { const float r = __builtin_amdgcn_rcpf(1.0f + __expf(-rp[j])), ig = __builtin_amdgcn_rcpf(1.0f + __expf(-ip[j])); const float la = sp[j] * r; const float d = 1.0f - __expf(la);
;                         o[j] = cvt_pk_bf16(d, __builtin_amdgcn_sqrtf(fmaxf(d * (2.0f - d), 0.f)) * (ig * xv[j])); }
;                     *(u32x4*)(AU + off) = o; }
	v_and_b32_e32 v57, 0xffff0000, v94
	v_mul_f32_e32 v52, v52, v57
	v_mul_f32_e32 v50, v50, v74
	v_mul_f32_e32 v52, v52, v53
	v_mul_f32_e32 v50, 0x3fb8aa3b, v50
	v_cvt_pk_bf16_f32 v49, v49, v52
	v_add_f32_e32 v52, v54, v66
	v_exp_f32_e32 v50, v50
	v_add_f32_e32 v51, v51, v71
	v_mul_f32_e32 v52, 0xbfb8aa3b, v52
	v_mul_f32_e32 v51, 0xbfb8aa3b, v51
	v_exp_f32_e32 v52, v52
	v_exp_f32_e32 v51, v51
	v_sub_f32_e32 v50, 1.0, v50
	v_sub_f32_e32 v53, 2.0, v50
	v_add_f32_e32 v52, 1.0, v52
	v_mul_f32_e32 v53, v50, v53
	v_add_f32_e32 v51, 1.0, v51
	v_rcp_f32_e32 v52, v52
	v_max_f32_e32 v53, 0, v53
	v_rcp_f32_e32 v51, v51
	v_sqrt_f32_e32 v53, v53
	v_add_f32_e32 v40, v40, v68
	v_mul_f32_e32 v40, 0xbfb8aa3b, v40
	v_lshlrev_b32_e32 v58, 16, v95
	v_exp_f32_e32 v40, v40
	v_mul_f32_e32 v52, v52, v58
	v_mul_f32_e32 v51, v51, v75
	v_mul_f32_e32 v52, v52, v53
	v_mul_f32_e32 v51, 0x3fb8aa3b, v51
	v_cvt_pk_bf16_f32 v50, v50, v52
	v_add_f32_e32 v52, v55, v67
	v_exp_f32_e32 v51, v51
	v_mul_f32_e32 v52, 0xbfb8aa3b, v52
	v_add_f32_e32 v40, 1.0, v40
	v_exp_f32_e32 v52, v52
	v_rcp_f32_e32 v40, v40
	v_sub_f32_e32 v51, 1.0, v51
	v_sub_f32_e32 v53, 2.0, v51
	v_add_f32_e32 v52, 1.0, v52
	v_mul_f32_e32 v53, v51, v53
	v_mul_f32_e32 v40, v40, v72
	v_rcp_f32_e32 v52, v52
	v_max_f32_e32 v53, 0, v53
	v_mul_f32_e32 v40, 0x3fb8aa3b, v40
	v_sqrt_f32_e32 v53, v53
	v_add_f32_e32 v44, v44, v64
	v_exp_f32_e32 v40, v40
	v_add_f32_e32 v41, v41, v69
	v_mul_f32_e32 v44, 0xbfb8aa3b, v44
	v_mul_f32_e32 v41, 0xbfb8aa3b, v41
	v_and_b32_e32 v59, 0xffff0000, v95
	v_exp_f32_e32 v44, v44
	v_exp_f32_e32 v41, v41
	v_mul_f32_e32 v52, v52, v59
	v_mul_f32_e32 v52, v52, v53
	v_sub_f32_e32 v40, 1.0, v40
	v_cvt_pk_bf16_f32 v51, v51, v52
	v_sub_f32_e32 v52, 2.0, v40
	v_add_f32_e32 v44, 1.0, v44
	v_mul_f32_e32 v52, v40, v52
	v_add_f32_e32 v41, 1.0, v41
	v_rcp_f32_e32 v44, v44
	v_max_f32_e32 v52, 0, v52
	v_rcp_f32_e32 v41, v41
	v_sqrt_f32_e32 v52, v52
	global_store_dwordx4 v[120:121], v[48:51], off offset:64
	v_add_f32_e32 v42, v42, v70
	v_mul_f32_e32 v41, v41, v73
	v_lshlrev_b32_e32 v48, 16, v92
	v_mul_f32_e32 v44, v44, v48
	v_mul_f32_e32 v44, v44, v52
	v_mul_f32_e32 v41, 0x3fb8aa3b, v41
	v_cvt_pk_bf16_f32 v40, v40, v44
	v_add_f32_e32 v44, v45, v65
	v_exp_f32_e32 v41, v41
	v_mul_f32_e32 v44, 0xbfb8aa3b, v44
	v_mul_f32_e32 v42, 0xbfb8aa3b, v42
	v_exp_f32_e32 v44, v44
	v_exp_f32_e32 v42, v42
	v_sub_f32_e32 v41, 1.0, v41
	v_sub_f32_e32 v45, 2.0, v41
	v_add_f32_e32 v44, 1.0, v44
	v_mul_f32_e32 v45, v41, v45
	v_add_f32_e32 v42, 1.0, v42
	v_rcp_f32_e32 v44, v44
	v_max_f32_e32 v45, 0, v45
	v_rcp_f32_e32 v42, v42
	v_sqrt_f32_e32 v45, v45
	v_and_b32_e32 v49, 0xffff0000, v92
	v_mul_f32_e32 v44, v44, v49
	v_mul_f32_e32 v42, v42, v74
	v_mul_f32_e32 v44, v44, v45
	v_mul_f32_e32 v42, 0x3fb8aa3b, v42
	v_cvt_pk_bf16_f32 v41, v41, v44
	v_add_f32_e32 v44, v46, v66
	v_exp_f32_e32 v42, v42
	v_add_f32_e32 v43, v43, v71
	v_mul_f32_e32 v44, 0xbfb8aa3b, v44
	v_mul_f32_e32 v43, 0xbfb8aa3b, v43
	v_exp_f32_e32 v44, v44
	v_exp_f32_e32 v43, v43
	v_sub_f32_e32 v42, 1.0, v42
	v_sub_f32_e32 v45, 2.0, v42
	v_add_f32_e32 v44, 1.0, v44
	v_mul_f32_e32 v45, v42, v45
	v_add_f32_e32 v43, 1.0, v43
	v_rcp_f32_e32 v44, v44
	v_max_f32_e32 v45, 0, v45
	v_rcp_f32_e32 v43, v43
	v_sqrt_f32_e32 v45, v45
	v_add_f32_e32 v32, v32, v68
	v_mul_f32_e32 v32, 0xbfb8aa3b, v32
	v_lshlrev_b32_e32 v50, 16, v93
	v_exp_f32_e32 v32, v32
	v_mul_f32_e32 v44, v44, v50
	v_mul_f32_e32 v43, v43, v75
	v_mul_f32_e32 v44, v44, v45
	v_mul_f32_e32 v43, 0x3fb8aa3b, v43
	v_cvt_pk_bf16_f32 v42, v42, v44
	v_add_f32_e32 v44, v47, v67
	v_exp_f32_e32 v43, v43
	v_mul_f32_e32 v44, 0xbfb8aa3b, v44
	v_add_f32_e32 v32, 1.0, v32
	v_exp_f32_e32 v44, v44
	v_rcp_f32_e32 v32, v32
	v_sub_f32_e32 v43, 1.0, v43
	v_sub_f32_e32 v45, 2.0, v43
	v_add_f32_e32 v44, 1.0, v44
	v_mul_f32_e32 v45, v43, v45
	v_mul_f32_e32 v32, v32, v72
	v_rcp_f32_e32 v44, v44
	v_max_f32_e32 v45, 0, v45
	v_mul_f32_e32 v32, 0x3fb8aa3b, v32
	v_sqrt_f32_e32 v45, v45
	v_add_f32_e32 v36, v36, v64
	v_exp_f32_e32 v32, v32
	v_add_f32_e32 v33, v33, v69
	v_mul_f32_e32 v36, 0xbfb8aa3b, v36
	v_mul_f32_e32 v33, 0xbfb8aa3b, v33
	v_and_b32_e32 v51, 0xffff0000, v93
	v_exp_f32_e32 v36, v36
	v_exp_f32_e32 v33, v33
	v_mul_f32_e32 v44, v44, v51
	v_mul_f32_e32 v44, v44, v45
	v_sub_f32_e32 v32, 1.0, v32
	v_cvt_pk_bf16_f32 v43, v43, v44
	v_sub_f32_e32 v44, 2.0, v32
	v_add_f32_e32 v36, 1.0, v36
	v_mul_f32_e32 v44, v32, v44
	v_add_f32_e32 v33, 1.0, v33
	v_rcp_f32_e32 v36, v36
	v_max_f32_e32 v44, 0, v44
	v_rcp_f32_e32 v33, v33
	v_sqrt_f32_e32 v44, v44
	global_store_dwordx4 v[112:113], v[40:43], off offset:64
	v_add_f32_e32 v34, v34, v70
	v_mul_f32_e32 v33, v33, v73
	v_lshlrev_b32_e32 v40, 16, v90
	v_mul_f32_e32 v36, v36, v40
	v_mul_f32_e32 v36, v36, v44
	v_mul_f32_e32 v33, 0x3fb8aa3b, v33
	v_cvt_pk_bf16_f32 v32, v32, v36
	v_add_f32_e32 v36, v37, v65
	v_exp_f32_e32 v33, v33
	v_mul_f32_e32 v36, 0xbfb8aa3b, v36
	v_mul_f32_e32 v34, 0xbfb8aa3b, v34
	v_exp_f32_e32 v36, v36
	v_exp_f32_e32 v34, v34
	v_sub_f32_e32 v33, 1.0, v33
	v_sub_f32_e32 v37, 2.0, v33
	v_add_f32_e32 v36, 1.0, v36
	v_mul_f32_e32 v37, v33, v37
	v_add_f32_e32 v34, 1.0, v34
	v_rcp_f32_e32 v36, v36
	v_max_f32_e32 v37, 0, v37
	v_rcp_f32_e32 v34, v34
	v_sqrt_f32_e32 v37, v37
	v_and_b32_e32 v41, 0xffff0000, v90
	v_mul_f32_e32 v36, v36, v41
	v_mul_f32_e32 v34, v34, v74
	v_mul_f32_e32 v36, v36, v37
	v_mul_f32_e32 v34, 0x3fb8aa3b, v34
	v_cvt_pk_bf16_f32 v33, v33, v36
	v_add_f32_e32 v36, v38, v66
	v_exp_f32_e32 v34, v34
	v_add_f32_e32 v35, v35, v71
	v_mul_f32_e32 v36, 0xbfb8aa3b, v36
	v_mul_f32_e32 v35, 0xbfb8aa3b, v35
	v_exp_f32_e32 v36, v36
	v_exp_f32_e32 v35, v35
	v_sub_f32_e32 v34, 1.0, v34
; __device__ __forceinline__ unsigned cvt_pk_bf16(float lo, float hi) { const bf16x2_t r = __builtin_convertvector((f32x2){lo, hi}, bf16x2_t); return __builtin_bit_cast(unsigned, r); }
; __device__ __forceinline__ float bf_lo(unsigned w) { return __uint_as_float(w << 16); }
; __device__ __forceinline__ float bf_hi(unsigned w) { return __uint_as_float(w & 0xffff0000u); }
;     __device__ __forceinline__ void operator()(const AccT& acc, const Unit& u, int wr, int wc, int fr, int fq) const {
;     ...
; #pragma unroll
;             for (int ai = 0; ai < 2; ++ai)
; #pragma unroll
;                 for (int m = 0; m < 4; ++m) { const size_t off = (size_t)(row0 + ai * HALF + m * 16) * DM + ch0 + 16 * n;
;                     const f32x4 rp = acc[ai][0][m][n] + bra, ip = acc[ai][1][m][n] + bri;
;                     const u32x2 w = xw[ai][m]; const float xv[4] = {bf_lo(w.x), bf_hi(w.x), bf_lo(w.y), bf_hi(w.y)};
;                     u32x4 o;
; #pragma unroll
;                     for (int j = 0; j < 4; ++j) { const float r = __builtin_amdgcn_rcpf(1.0f + __expf(-rp[j])), ig = __builtin_amdgcn_rcpf(1.0f + __expf(-ip[j])); const float la = sp[j] * r; const float d = 1.0f - __expf(la);
;                         o[j] = cvt_pk_bf16(d, __builtin_amdgcn_sqrtf(fmaxf(d * (2.0f - d), 0.f)) * (ig * xv[j])); }
;                     *(u32x4*)(AU + off) = o; }
	v_sub_f32_e32 v37, 2.0, v34
	v_add_f32_e32 v36, 1.0, v36
	v_mul_f32_e32 v37, v34, v37
	v_add_f32_e32 v35, 1.0, v35
	v_rcp_f32_e32 v36, v36
	v_max_f32_e32 v37, 0, v37
	v_rcp_f32_e32 v35, v35
	v_sqrt_f32_e32 v37, v37
	v_add_f32_e32 v24, v24, v68
	v_mul_f32_e32 v24, 0xbfb8aa3b, v24
	v_lshlrev_b32_e32 v42, 16, v91
	v_exp_f32_e32 v24, v24
	v_mul_f32_e32 v36, v36, v42
	v_mul_f32_e32 v35, v35, v75
	v_mul_f32_e32 v36, v36, v37
	v_mul_f32_e32 v35, 0x3fb8aa3b, v35
	v_cvt_pk_bf16_f32 v34, v34, v36
	v_add_f32_e32 v36, v39, v67
	v_exp_f32_e32 v35, v35
	v_mul_f32_e32 v36, 0xbfb8aa3b, v36
	v_add_f32_e32 v24, 1.0, v24
	v_exp_f32_e32 v36, v36
	v_rcp_f32_e32 v24, v24
	v_sub_f32_e32 v35, 1.0, v35
	v_sub_f32_e32 v37, 2.0, v35
	v_add_f32_e32 v36, 1.0, v36
	v_mul_f32_e32 v37, v35, v37
	v_mul_f32_e32 v24, v24, v72
	v_rcp_f32_e32 v36, v36
	v_max_f32_e32 v37, 0, v37
	v_mul_f32_e32 v24, 0x3fb8aa3b, v24
	v_sqrt_f32_e32 v37, v37
	v_add_f32_e32 v28, v28, v64
	v_exp_f32_e32 v24, v24
	v_add_f32_e32 v25, v25, v69
	v_mul_f32_e32 v28, 0xbfb8aa3b, v28
	v_mul_f32_e32 v25, 0xbfb8aa3b, v25
	v_and_b32_e32 v43, 0xffff0000, v91
	v_exp_f32_e32 v28, v28
	v_exp_f32_e32 v25, v25
	v_mul_f32_e32 v36, v36, v43
	v_mul_f32_e32 v36, v36, v37
	v_sub_f32_e32 v24, 1.0, v24
	v_cvt_pk_bf16_f32 v35, v35, v36
	v_sub_f32_e32 v36, 2.0, v24
	v_add_f32_e32 v28, 1.0, v28
	v_mul_f32_e32 v36, v24, v36
	v_add_f32_e32 v25, 1.0, v25
	v_rcp_f32_e32 v28, v28
	v_max_f32_e32 v36, 0, v36
	v_rcp_f32_e32 v25, v25
	v_sqrt_f32_e32 v36, v36
	global_store_dwordx4 v[104:105], v[32:35], off offset:64
	v_add_f32_e32 v26, v26, v70
	v_mul_f32_e32 v25, v25, v73
	v_lshlrev_b32_e32 v32, 16, v86
	v_mul_f32_e32 v28, v28, v32
	v_mul_f32_e32 v28, v28, v36
	v_mul_f32_e32 v25, 0x3fb8aa3b, v25
	v_cvt_pk_bf16_f32 v24, v24, v28
	v_add_f32_e32 v28, v29, v65
	v_exp_f32_e32 v25, v25
	v_mul_f32_e32 v28, 0xbfb8aa3b, v28
	v_mul_f32_e32 v26, 0xbfb8aa3b, v26
	v_exp_f32_e32 v28, v28
	v_exp_f32_e32 v26, v26
	v_sub_f32_e32 v25, 1.0, v25
	v_sub_f32_e32 v29, 2.0, v25
	v_add_f32_e32 v28, 1.0, v28
	v_mul_f32_e32 v29, v25, v29
	v_add_f32_e32 v26, 1.0, v26
	v_rcp_f32_e32 v28, v28
	v_max_f32_e32 v29, 0, v29
	v_rcp_f32_e32 v26, v26
	v_sqrt_f32_e32 v29, v29
	v_and_b32_e32 v33, 0xffff0000, v86
	v_mul_f32_e32 v28, v28, v33
	v_mul_f32_e32 v26, v26, v74
	v_mul_f32_e32 v28, v28, v29
	v_mul_f32_e32 v26, 0x3fb8aa3b, v26
	v_cvt_pk_bf16_f32 v25, v25, v28
	v_add_f32_e32 v28, v30, v66
	v_exp_f32_e32 v26, v26
	v_add_f32_e32 v27, v27, v71
	v_mul_f32_e32 v28, 0xbfb8aa3b, v28
	v_mul_f32_e32 v27, 0xbfb8aa3b, v27
	v_exp_f32_e32 v28, v28
	v_exp_f32_e32 v27, v27
	v_sub_f32_e32 v26, 1.0, v26
	v_sub_f32_e32 v29, 2.0, v26
	v_add_f32_e32 v28, 1.0, v28
	v_mul_f32_e32 v29, v26, v29
	v_add_f32_e32 v27, 1.0, v27
	v_rcp_f32_e32 v28, v28
	v_max_f32_e32 v29, 0, v29
	v_rcp_f32_e32 v27, v27
	v_sqrt_f32_e32 v29, v29
	v_add_f32_e32 v16, v16, v68
	v_mul_f32_e32 v16, 0xbfb8aa3b, v16
	v_lshlrev_b32_e32 v34, 16, v87
	v_exp_f32_e32 v16, v16
	v_mul_f32_e32 v28, v28, v34
	v_mul_f32_e32 v27, v27, v75
	v_mul_f32_e32 v28, v28, v29
	v_mul_f32_e32 v27, 0x3fb8aa3b, v27
	v_cvt_pk_bf16_f32 v26, v26, v28
	v_add_f32_e32 v28, v31, v67
	v_exp_f32_e32 v27, v27
	v_mul_f32_e32 v28, 0xbfb8aa3b, v28
	v_add_f32_e32 v16, 1.0, v16
	v_exp_f32_e32 v28, v28
	v_rcp_f32_e32 v16, v16
	v_sub_f32_e32 v27, 1.0, v27
	v_sub_f32_e32 v29, 2.0, v27
	v_add_f32_e32 v28, 1.0, v28
	v_mul_f32_e32 v29, v27, v29
	v_mul_f32_e32 v16, v16, v72
	v_rcp_f32_e32 v28, v28
	v_max_f32_e32 v29, 0, v29
	v_mul_f32_e32 v16, 0x3fb8aa3b, v16
	v_sqrt_f32_e32 v29, v29
	v_add_f32_e32 v20, v20, v64
	v_exp_f32_e32 v16, v16
	v_add_f32_e32 v17, v17, v69
	v_mul_f32_e32 v20, 0xbfb8aa3b, v20
	v_mul_f32_e32 v17, 0xbfb8aa3b, v17
	v_and_b32_e32 v35, 0xffff0000, v87
	v_exp_f32_e32 v20, v20
	v_exp_f32_e32 v17, v17
	v_mul_f32_e32 v28, v28, v35
	v_mul_f32_e32 v28, v28, v29
	v_sub_f32_e32 v16, 1.0, v16
	v_cvt_pk_bf16_f32 v27, v27, v28
	v_sub_f32_e32 v28, 2.0, v16
	v_add_f32_e32 v20, 1.0, v20
	v_mul_f32_e32 v28, v16, v28
	v_add_f32_e32 v17, 1.0, v17
	v_rcp_f32_e32 v20, v20
	v_max_f32_e32 v28, 0, v28
	v_rcp_f32_e32 v17, v17
	v_sqrt_f32_e32 v28, v28
	global_store_dwordx4 v[96:97], v[24:27], off offset:64
	v_add_f32_e32 v18, v18, v70
	v_mul_f32_e32 v17, v17, v73
	v_lshlrev_b32_e32 v24, 16, v84
	v_mul_f32_e32 v20, v20, v24
	v_mul_f32_e32 v20, v20, v28
	v_mul_f32_e32 v17, 0x3fb8aa3b, v17
	v_cvt_pk_bf16_f32 v16, v16, v20
	v_add_f32_e32 v20, v21, v65
	v_exp_f32_e32 v17, v17
	v_mul_f32_e32 v20, 0xbfb8aa3b, v20
	v_mul_f32_e32 v18, 0xbfb8aa3b, v18
	v_exp_f32_e32 v20, v20
	v_exp_f32_e32 v18, v18
	v_sub_f32_e32 v17, 1.0, v17
	v_sub_f32_e32 v21, 2.0, v17
	v_add_f32_e32 v20, 1.0, v20
	v_mul_f32_e32 v21, v17, v21
	v_add_f32_e32 v18, 1.0, v18
	v_rcp_f32_e32 v20, v20
	v_max_f32_e32 v21, 0, v21
	v_rcp_f32_e32 v18, v18
	v_sqrt_f32_e32 v21, v21
	v_and_b32_e32 v25, 0xffff0000, v84
	v_mul_f32_e32 v20, v20, v25
	v_mul_f32_e32 v18, v18, v74
	v_mul_f32_e32 v20, v20, v21
	v_mul_f32_e32 v18, 0x3fb8aa3b, v18
	v_cvt_pk_bf16_f32 v17, v17, v20
	v_add_f32_e32 v20, v22, v66
	v_exp_f32_e32 v18, v18
	v_add_f32_e32 v19, v19, v71
	v_mul_f32_e32 v20, 0xbfb8aa3b, v20
	v_mul_f32_e32 v19, 0xbfb8aa3b, v19
	v_exp_f32_e32 v20, v20
	v_exp_f32_e32 v19, v19
	v_sub_f32_e32 v18, 1.0, v18
	v_sub_f32_e32 v21, 2.0, v18
	v_add_f32_e32 v20, 1.0, v20
	v_mul_f32_e32 v21, v18, v21
	v_add_f32_e32 v19, 1.0, v19
	v_rcp_f32_e32 v20, v20
	v_max_f32_e32 v21, 0, v21
	v_rcp_f32_e32 v19, v19
	v_sqrt_f32_e32 v21, v21
	v_add_f32_e32 v8, v8, v68
	v_mul_f32_e32 v8, 0xbfb8aa3b, v8
	v_lshlrev_b32_e32 v26, 16, v85
	v_exp_f32_e32 v8, v8
	v_mul_f32_e32 v20, v20, v26
; __device__ __forceinline__ unsigned cvt_pk_bf16(float lo, float hi) { const bf16x2_t r = __builtin_convertvector((f32x2){lo, hi}, bf16x2_t); return __builtin_bit_cast(unsigned, r); }
; __device__ __forceinline__ float bf_lo(unsigned w) { return __uint_as_float(w << 16); }
; __device__ __forceinline__ float bf_hi(unsigned w) { return __uint_as_float(w & 0xffff0000u); }
; template <class Epi>
; __device__ __forceinline__ void gemm_phase(LAS unsigned char* lds, const bf16_t* A, int lda, const bf16_t* Bt, int ldb, int M, int N, int K, int asel, const Epi& E, const int fixed_round = -1) {
;     ...
;         if (!has_next) break;
;     __device__ __forceinline__ void operator()(const AccT& acc, const Unit& u, int wr, int wc, int fr, int fq) const {
;     ...
; #pragma unroll
;             for (int ai = 0; ai < 2; ++ai)
; #pragma unroll
;                 for (int m = 0; m < 4; ++m) { const size_t off = (size_t)(row0 + ai * HALF + m * 16) * DM + ch0 + 16 * n;
;                     const f32x4 rp = acc[ai][0][m][n] + bra, ip = acc[ai][1][m][n] + bri;
;                     const u32x2 w = xw[ai][m]; const float xv[4] = {bf_lo(w.x), bf_hi(w.x), bf_lo(w.y), bf_hi(w.y)};
;                     u32x4 o;
; #pragma unroll
;                     for (int j = 0; j < 4; ++j) { const float r = __builtin_amdgcn_rcpf(1.0f + __expf(-rp[j])), ig = __builtin_amdgcn_rcpf(1.0f + __expf(-ip[j])); const float la = sp[j] * r; const float d = 1.0f - __expf(la);
;                         o[j] = cvt_pk_bf16(d, __builtin_amdgcn_sqrtf(fmaxf(d * (2.0f - d), 0.f)) * (ig * xv[j])); }
;                     *(u32x4*)(AU + off) = o; }
;         }
;     }
	v_mul_f32_e32 v19, v19, v75
	v_mul_f32_e32 v20, v20, v21
	v_mul_f32_e32 v19, 0x3fb8aa3b, v19
	v_cvt_pk_bf16_f32 v18, v18, v20
	v_add_f32_e32 v20, v23, v67
	v_exp_f32_e32 v19, v19
	v_mul_f32_e32 v20, 0xbfb8aa3b, v20
	v_add_f32_e32 v8, 1.0, v8
	v_exp_f32_e32 v20, v20
	v_rcp_f32_e32 v8, v8
	v_sub_f32_e32 v19, 1.0, v19
	v_sub_f32_e32 v21, 2.0, v19
	v_add_f32_e32 v20, 1.0, v20
	v_mul_f32_e32 v21, v19, v21
	v_mul_f32_e32 v8, v8, v72
	v_rcp_f32_e32 v20, v20
	v_max_f32_e32 v21, 0, v21
	v_mul_f32_e32 v8, 0x3fb8aa3b, v8
	v_sqrt_f32_e32 v21, v21
	v_add_f32_e32 v12, v12, v64
	v_exp_f32_e32 v8, v8
	v_add_f32_e32 v9, v9, v69
	v_mul_f32_e32 v12, 0xbfb8aa3b, v12
	v_mul_f32_e32 v9, 0xbfb8aa3b, v9
	v_and_b32_e32 v27, 0xffff0000, v85
	v_exp_f32_e32 v12, v12
	v_exp_f32_e32 v9, v9
	v_mul_f32_e32 v20, v20, v27
	v_mul_f32_e32 v20, v20, v21
	v_sub_f32_e32 v8, 1.0, v8
	v_cvt_pk_bf16_f32 v19, v19, v20
	v_sub_f32_e32 v20, 2.0, v8
	v_add_f32_e32 v12, 1.0, v12
	v_mul_f32_e32 v20, v8, v20
	v_add_f32_e32 v9, 1.0, v9
	v_rcp_f32_e32 v12, v12
	v_max_f32_e32 v20, 0, v20
	v_rcp_f32_e32 v9, v9
	v_sqrt_f32_e32 v20, v20
	global_store_dwordx4 v[88:89], v[16:19], off offset:64
	v_add_f32_e32 v10, v10, v70
	v_mul_f32_e32 v9, v9, v73
	v_lshlrev_b32_e32 v16, 16, v82
	v_mul_f32_e32 v12, v12, v16
	v_mul_f32_e32 v12, v12, v20
	v_mul_f32_e32 v9, 0x3fb8aa3b, v9
	v_cvt_pk_bf16_f32 v8, v8, v12
	v_add_f32_e32 v12, v13, v65
	v_exp_f32_e32 v9, v9
	v_mul_f32_e32 v12, 0xbfb8aa3b, v12
	v_mul_f32_e32 v10, 0xbfb8aa3b, v10
	v_exp_f32_e32 v12, v12
	v_exp_f32_e32 v10, v10
	v_sub_f32_e32 v9, 1.0, v9
	v_sub_f32_e32 v13, 2.0, v9
	v_add_f32_e32 v12, 1.0, v12
	v_mul_f32_e32 v13, v9, v13
	v_add_f32_e32 v10, 1.0, v10
	v_rcp_f32_e32 v12, v12
	v_max_f32_e32 v13, 0, v13
	v_rcp_f32_e32 v10, v10
	v_sqrt_f32_e32 v13, v13
	v_and_b32_e32 v17, 0xffff0000, v82
	v_mul_f32_e32 v12, v12, v17
	v_mul_f32_e32 v10, v10, v74
	v_mul_f32_e32 v12, v12, v13
	v_mul_f32_e32 v10, 0x3fb8aa3b, v10
	v_cvt_pk_bf16_f32 v9, v9, v12
	v_add_f32_e32 v12, v14, v66
	v_exp_f32_e32 v10, v10
	v_add_f32_e32 v11, v11, v71
	v_mul_f32_e32 v12, 0xbfb8aa3b, v12
	v_mul_f32_e32 v11, 0xbfb8aa3b, v11
	v_exp_f32_e32 v12, v12
	v_exp_f32_e32 v11, v11
	v_sub_f32_e32 v10, 1.0, v10
	v_sub_f32_e32 v13, 2.0, v10
	v_add_f32_e32 v12, 1.0, v12
	v_mul_f32_e32 v13, v10, v13
	v_add_f32_e32 v11, 1.0, v11
	v_rcp_f32_e32 v12, v12
	v_max_f32_e32 v13, 0, v13
	v_rcp_f32_e32 v11, v11
	v_sqrt_f32_e32 v13, v13
	v_add_f32_e32 v0, v0, v68
	v_mul_f32_e32 v0, 0xbfb8aa3b, v0
	v_lshlrev_b32_e32 v18, 16, v83
	v_exp_f32_e32 v0, v0
	v_mul_f32_e32 v12, v12, v18
	v_mul_f32_e32 v11, v11, v75
	v_mul_f32_e32 v12, v12, v13
	v_mul_f32_e32 v11, 0x3fb8aa3b, v11
	v_cvt_pk_bf16_f32 v10, v10, v12
	v_add_f32_e32 v12, v15, v67
	v_exp_f32_e32 v11, v11
	v_mul_f32_e32 v12, 0xbfb8aa3b, v12
	v_add_f32_e32 v0, 1.0, v0
	v_exp_f32_e32 v12, v12
	v_rcp_f32_e32 v0, v0
	v_sub_f32_e32 v11, 1.0, v11
	v_sub_f32_e32 v13, 2.0, v11
	v_add_f32_e32 v12, 1.0, v12
	v_mul_f32_e32 v13, v11, v13
	v_mul_f32_e32 v0, v0, v72
	v_rcp_f32_e32 v12, v12
	v_max_f32_e32 v13, 0, v13
	v_mul_f32_e32 v0, 0x3fb8aa3b, v0
	v_sqrt_f32_e32 v13, v13
	v_add_f32_e32 v4, v4, v64
	v_exp_f32_e32 v0, v0
	v_add_f32_e32 v1, v1, v69
	v_mul_f32_e32 v4, 0xbfb8aa3b, v4
	v_mul_f32_e32 v1, 0xbfb8aa3b, v1
	v_and_b32_e32 v19, 0xffff0000, v83
	v_exp_f32_e32 v4, v4
	v_exp_f32_e32 v1, v1
	v_mul_f32_e32 v12, v12, v19
	v_mul_f32_e32 v12, v12, v13
	v_sub_f32_e32 v0, 1.0, v0
	v_cvt_pk_bf16_f32 v11, v11, v12
	v_sub_f32_e32 v12, 2.0, v0
	v_add_f32_e32 v4, 1.0, v4
	v_mul_f32_e32 v12, v0, v12
	v_add_f32_e32 v1, 1.0, v1
	v_rcp_f32_e32 v4, v4
	v_max_f32_e32 v12, 0, v12
	v_rcp_f32_e32 v1, v1
	v_sqrt_f32_e32 v12, v12
	global_store_dwordx4 v[80:81], v[8:11], off offset:64
	v_add_f32_e32 v2, v2, v70
	v_mul_f32_e32 v1, v1, v73
	v_lshlrev_b32_e32 v8, 16, v78
	v_mul_f32_e32 v4, v4, v8
	v_mul_f32_e32 v4, v4, v12
	v_mul_f32_e32 v1, 0x3fb8aa3b, v1
	v_cvt_pk_bf16_f32 v0, v0, v4
	v_add_f32_e32 v4, v5, v65
	v_exp_f32_e32 v1, v1
	v_mul_f32_e32 v4, 0xbfb8aa3b, v4
	v_mul_f32_e32 v2, 0xbfb8aa3b, v2
	v_exp_f32_e32 v4, v4
	v_exp_f32_e32 v2, v2
	v_sub_f32_e32 v1, 1.0, v1
	v_sub_f32_e32 v5, 2.0, v1
	v_add_f32_e32 v4, 1.0, v4
	v_mul_f32_e32 v5, v1, v5
	v_add_f32_e32 v2, 1.0, v2
	v_rcp_f32_e32 v4, v4
	v_max_f32_e32 v5, 0, v5
	v_rcp_f32_e32 v2, v2
	v_sqrt_f32_e32 v5, v5
	v_and_b32_e32 v9, 0xffff0000, v78
	v_mul_f32_e32 v4, v4, v9
	v_mul_f32_e32 v2, v2, v74
	v_mul_f32_e32 v4, v4, v5
	v_mul_f32_e32 v2, 0x3fb8aa3b, v2
	v_cvt_pk_bf16_f32 v1, v1, v4
	v_add_f32_e32 v4, v6, v66
	v_exp_f32_e32 v2, v2
	v_add_f32_e32 v3, v3, v71
	v_mul_f32_e32 v4, 0xbfb8aa3b, v4
	v_mul_f32_e32 v3, 0xbfb8aa3b, v3
	v_exp_f32_e32 v4, v4
	v_exp_f32_e32 v3, v3
	v_sub_f32_e32 v2, 1.0, v2
	v_sub_f32_e32 v5, 2.0, v2
	v_add_f32_e32 v4, 1.0, v4
	v_mul_f32_e32 v5, v2, v5
	v_add_f32_e32 v3, 1.0, v3
	v_rcp_f32_e32 v4, v4
	v_max_f32_e32 v5, 0, v5
	v_rcp_f32_e32 v3, v3
	v_sqrt_f32_e32 v5, v5
	v_lshlrev_b32_e32 v10, 16, v79
	v_mul_f32_e32 v4, v4, v10
	v_mul_f32_e32 v3, v3, v75
	v_mul_f32_e32 v4, v4, v5
	v_mul_f32_e32 v3, 0x3fb8aa3b, v3
	v_cvt_pk_bf16_f32 v2, v2, v4
	v_add_f32_e32 v4, v7, v67
	v_exp_f32_e32 v3, v3
	v_mul_f32_e32 v4, 0xbfb8aa3b, v4
	v_exp_f32_e32 v4, v4
	v_and_b32_e32 v11, 0xffff0000, v79
	v_sub_f32_e32 v3, 1.0, v3
	v_sub_f32_e32 v5, 2.0, v3
	v_add_f32_e32 v4, 1.0, v4
	v_mul_f32_e32 v5, v3, v5
	v_rcp_f32_e32 v4, v4
	v_max_f32_e32 v5, 0, v5
	v_sqrt_f32_e32 v5, v5
	s_andn2_b64 vcc, exec, s[4:5]
	v_mul_f32_e32 v4, v4, v11
	v_mul_f32_e32 v4, v4, v5
	v_cvt_pk_bf16_f32 v3, v3, v4
	global_store_dwordx4 v[76:77], v[0:3], off offset:64
	s_cbranch_vccz .LBB0_946
